# hand-written norm phases (sites 0-2): 4 consecutive rows per wave so modulation/norm params load once per wave, 3-buffer row prefetch with counted vmcnt, DPP wave reductions instead of ds_bpermute
# speedup vs baseline: 1.0194x; 1.0194x over previous
.LBB0_265:
	v_mov_b32_e32 v0, v147
	v_readlane_b32 s2, v255, 0
	s_mov_b32 s71, s39
	v_ashrrev_i32_e32 v1, 6, v0
	v_lshl_add_u32 v96, s2, 3, v1
	s_movk_i32 s2, 0x2000
	v_cmp_gt_i32_e32 vcc, s2, v96
	s_mul_i32 s2, s70, 0xc00
	v_writelane_b32 v255, s2, 12
	s_nop 1
	v_writelane_b32 v255, s3, 13
	s_and_saveexec_b64 s[16:17], vcc
	s_cbranch_execz .LBB0_280
	s_load_dwordx4 s[8:11], s[0:1], 0x90
	s_load_dwordx4 s[12:15], s[0:1], 0x0
	s_load_dwordx4 s[4:7], s[0:1], 0x40
	s_mul_i32 s2, s70, 0x2d000
	s_mul_i32 s24, s70, 0xc00
	s_waitcnt lgkmcnt(0)
	s_add_u32 s22, s10, 0x100000
	s_addc_u32 s23, s11, 0
	s_cmp_lg_u32 s70, 0
	s_cselect_b64 s[18:19], -1, 0
	s_add_u32 s20, s22, s2
	s_mul_hi_u32 s2, s70, 0x2d000
	s_addc_u32 s21, s23, s2
	s_mov_b32 s2, s24
	v_writelane_b32 v255, s2, 12
	v_sub_u32_e64 v1, s70, 1 clamp
	v_cmp_lt_i32_e32 vcc, v188, v183
	v_writelane_b32 v255, s3, 13
	s_movk_i32 s2, 0xc00
	v_mul_lo_u32 v144, v1, s2
	s_mov_b32 s2, 0x2d000
	v_lshlrev_b64 v[2:3], 2, v[144:145]
	v_mul_lo_u32 v144, v1, s2
	v_lshlrev_b32_e32 v1, 2, v0
	v_and_b32_e32 v98, 0xfc, v1
	v_cndmask_b32_e32 v1, v182, v188, vcc
	v_cmp_lt_i32_e32 vcc, v254, v183
	v_lshlrev_b32_e32 v99, 2, v1
	v_lshl_add_u64 v[4:5], s[22:23], 0, v[144:145]
	v_cndmask_b32_e32 v1, v182, v254, vcc
	v_lshlrev_b32_e32 v128, 2, v1
	v_xor_b32_e32 v1, 4, v182
	v_cmp_lt_i32_e32 vcc, v1, v183
	v_lshlrev_b32_e32 v144, 2, v98
	s_mov_b32 s25, s39
	v_cndmask_b32_e32 v1, v182, v1, vcc
	v_lshlrev_b32_e32 v129, 2, v1
	v_xor_b32_e32 v1, 8, v182
	v_lshl_add_u64 v[2:3], s[6:7], 0, v[2:3]
	v_lshl_add_u64 v[4:5], v[4:5], 0, v[144:145]
	s_mov_b64 s[6:7], 0x8000
	v_cmp_lt_i32_e32 vcc, v1, v183
	s_lshl_b64 s[24:25], s[24:25], 2
	v_lshl_add_u64 v[100:101], v[4:5], 0, s[6:7]
	v_lshl_add_u64 v[2:3], v[2:3], 0, v[144:145]
	s_mov_b64 s[6:7], 0x2000
	v_cndmask_b32_e32 v1, v182, v1, vcc
	v_cmp_lt_i32_e32 vcc, v187, v183
	v_ashrrev_i32_e32 v97, 31, v96
	s_add_u32 s4, s4, s24
	v_lshl_add_u64 v[102:103], v[2:3], 0, s[6:7]
	v_lshlrev_b32_e32 v130, 2, v1
	v_cndmask_b32_e32 v1, v182, v187, vcc
	v_cmp_lt_i32_e32 vcc, v184, v183
	v_lshlrev_b64 v[2:3], 11, v[96:97]
	v_and_b32_e32 v4, 63, v0
	s_addc_u32 s5, s5, s25
	v_lshlrev_b32_e32 v131, 2, v1
	v_cndmask_b32_e32 v1, v182, v184, vcc
	v_lshl_or_b32 v2, v4, 3, v2
	v_lshl_add_u64 v[104:105], s[4:5], 0, v[144:145]
	v_lshlrev_b32_e32 v132, 2, v1
	v_lshl_add_u64 v[0:1], s[10:11], 0, v[2:3]
	s_mov_b64 s[4:5], 0x9800600
	v_lshlrev_b64 v[108:109], 12, v[96:97]
	v_lshl_add_u64 v[106:107], v[0:1], 0, s[4:5]
	v_lshl_or_b32 v108, v4, 4, v108
	s_mov_b64 s[10:11], 0
	s_cmp_eq_u32 s70, 0
	s_cbranch_scc1 .Lnorm0_first
	v_readlane_b32 s2, v255, 0
	v_readfirstlane_b32 s7, v147
	s_load_dwordx2 s[4:5], s[0:1], 0x90
	s_load_dwordx2 s[12:13], s[0:1], 0x98
	s_load_dwordx2 s[14:15], s[0:1], 0x40
	s_load_dwordx2 s[40:41], s[0:1], 0x48
	v_and_b32_e32 v0, 63, v147
	v_lshlrev_b32_e32 v1, 3, v0
	v_lshlrev_b32_e32 v0, 4, v0
	s_lshr_b32 s7, s7, 6
	s_lshl_b32 s2, s2, 3
	s_add_u32 s2, s2, s7
	s_lshl_b32 s24, s2, 2
	s_sub_u32 s27, s24, 0x1000
	s_lshr_b32 s27, s27, 10
	s_add_u32 s27, s27, 1
	s_cmp_lt_u32 s24, 0x1000
	s_cselect_b32 s30, 0, s27
	v_add_u32_e32 v2, 0x8000, v0
	v_mov_b32_e32 v3, v0
	v_add_u32_e32 v4, 0x1000, v0
	s_waitcnt lgkmcnt(0)
	s_lshl_b32 s27, s24, 11
	s_add_u32 s62, s12, s27
	s_addc_u32 s63, s13, 0
	s_add_u32 s58, s62, 0x8800000
	s_addc_u32 s59, s63, 0
	s_add_u32 s60, s58, 0x1000000
	s_addc_u32 s61, s59, 0
	s_add_u32 s62, s62, 0x1000000
	s_addc_u32 s63, s63, 0
	s_lshl_b32 s27, s24, 12
	s_add_u32 s46, s4, s27
	s_addc_u32 s47, s5, 0
	s_mov_b64 s[4:5], s[46:47]
	s_mul_i32 s27, s70, 5
	s_add_u32 s27, s27, s30
	s_mul_i32 s27, s27, 0x9000
	s_add_u32 s27, s27, 0x100000
	s_add_u32 s88, s12, s27
	s_addc_u32 s89, s13, 0
	s_sub_u32 s100, s88, 0x2d000
	s_subb_u32 s101, s89, 0
	s_mul_i32 s27, s70, 0x3000
	s_add_u32 s27, s27, 0xfffff000
	s_add_u32 s40, s40, s27
	s_addc_u32 s41, s41, 0
	s_mul_i32 s27, s70, 0x3000
	s_add_u32 s14, s14, s27
	s_addc_u32 s15, s15, 0
	global_load_dwordx4 v[22:25], v2, s[100:101] offset:0
	global_load_dwordx4 v[38:41], v0, s[40:41] offset:0
	global_load_dwordx4 v[54:57], v3, s[88:89] offset:0
	global_load_dwordx4 v[70:73], v4, s[88:89] offset:0
	global_load_dwordx4 v[86:89], v0, s[14:15] offset:0
	global_load_dwordx4 v[26:29], v2, s[100:101] offset:1024
	global_load_dwordx4 v[42:45], v0, s[40:41] offset:1024
	global_load_dwordx4 v[58:61], v3, s[88:89] offset:1024
	global_load_dwordx4 v[74:77], v4, s[88:89] offset:1024
	global_load_dwordx4 v[90:93], v0, s[14:15] offset:1024
	global_load_dwordx4 v[30:33], v2, s[100:101] offset:2048
	global_load_dwordx4 v[46:49], v0, s[40:41] offset:2048
	global_load_dwordx4 v[62:65], v3, s[88:89] offset:2048
	global_load_dwordx4 v[78:81], v4, s[88:89] offset:2048
	global_load_dwordx4 v[94:97], v0, s[14:15] offset:2048
	global_load_dwordx4 v[34:37], v2, s[100:101] offset:3072
	global_load_dwordx4 v[50:53], v0, s[40:41] offset:3072
	global_load_dwordx4 v[66:69], v3, s[88:89] offset:3072
	global_load_dwordx4 v[82:85], v4, s[88:89] offset:3072
	global_load_dwordx4 v[98:101], v0, s[14:15] offset:3072
	global_load_dwordx4 v[102:105], v0, s[4:5] offset:0
	global_load_dwordx4 v[106:109], v0, s[4:5] offset:1024
	global_load_dwordx4 v[110:113], v0, s[4:5] offset:2048
	global_load_dwordx4 v[114:117], v0, s[4:5] offset:3072
	global_load_dwordx2 v[118:119], v1, s[58:59] offset:0
	global_load_dwordx2 v[122:123], v1, s[58:59] offset:512
	global_load_dwordx2 v[134:135], v1, s[58:59] offset:1024
	global_load_dwordx2 v[138:139], v1, s[58:59] offset:1536
	global_load_dwordx2 v[120:121], v1, s[60:61] offset:0
	global_load_dwordx2 v[124:125], v1, s[60:61] offset:512
	global_load_dwordx2 v[136:137], v1, s[60:61] offset:1024
	global_load_dwordx2 v[140:141], v1, s[60:61] offset:1536
	s_add_u32 s4, s4, 0x1000
	s_addc_u32 s5, s5, 0
	s_add_u32 s58, s58, 0x800
	s_addc_u32 s59, s59, 0
	s_add_u32 s60, s60, 0x800
	s_addc_u32 s61, s61, 0
	global_load_dwordx4 v[154:157], v0, s[4:5] offset:0
	global_load_dwordx4 v[158:161], v0, s[4:5] offset:1024
	global_load_dwordx4 v[162:165], v0, s[4:5] offset:2048
	global_load_dwordx4 v[168:171], v0, s[4:5] offset:3072
	global_load_dwordx2 v[172:173], v1, s[58:59] offset:0
	global_load_dwordx2 v[176:177], v1, s[58:59] offset:512
	global_load_dwordx2 v[204:205], v1, s[58:59] offset:1024
	global_load_dwordx2 v[214:215], v1, s[58:59] offset:1536
	global_load_dwordx2 v[174:175], v1, s[60:61] offset:0
	global_load_dwordx2 v[178:179], v1, s[60:61] offset:512
	global_load_dwordx2 v[206:207], v1, s[60:61] offset:1024
	global_load_dwordx2 v[216:217], v1, s[60:61] offset:1536
	s_add_u32 s4, s4, 0x1000
	s_addc_u32 s5, s5, 0
	s_add_u32 s58, s58, 0x800
	s_addc_u32 s59, s59, 0
	s_add_u32 s60, s60, 0x800
	s_addc_u32 s61, s61, 0
	global_load_dwordx4 v[218:221], v0, s[4:5] offset:0
	global_load_dwordx4 v[222:225], v0, s[4:5] offset:1024
	global_load_dwordx4 v[226:229], v0, s[4:5] offset:2048
	global_load_dwordx4 v[230:233], v0, s[4:5] offset:3072
	global_load_dwordx2 v[234:235], v1, s[58:59] offset:0
	global_load_dwordx2 v[238:239], v1, s[58:59] offset:512
	global_load_dwordx2 v[242:243], v1, s[58:59] offset:1024
	global_load_dwordx2 v[246:247], v1, s[58:59] offset:1536
	global_load_dwordx2 v[236:237], v1, s[60:61] offset:0
	global_load_dwordx2 v[240:241], v1, s[60:61] offset:512
	global_load_dwordx2 v[244:245], v1, s[60:61] offset:1024
	global_load_dwordx2 v[248:249], v1, s[60:61] offset:1536
	s_add_u32 s4, s4, 0x1000
	s_addc_u32 s5, s5, 0
	s_add_u32 s58, s58, 0x800
	s_addc_u32 s59, s59, 0
	s_add_u32 s60, s60, 0x800
	s_addc_u32 s61, s61, 0
	s_waitcnt vmcnt(24)
	v_pk_add_f32 v[70:71], v[70:71], 1.0 op_sel_hi:[1,0]
	v_pk_add_f32 v[72:73], v[72:73], 1.0 op_sel_hi:[1,0]
	v_pk_add_f32 v[74:75], v[74:75], 1.0 op_sel_hi:[1,0]
	v_pk_add_f32 v[76:77], v[76:77], 1.0 op_sel_hi:[1,0]
	v_pk_add_f32 v[78:79], v[78:79], 1.0 op_sel_hi:[1,0]
	v_pk_add_f32 v[80:81], v[80:81], 1.0 op_sel_hi:[1,0]
	v_pk_add_f32 v[82:83], v[82:83], 1.0 op_sel_hi:[1,0]
	v_pk_add_f32 v[84:85], v[84:85], 1.0 op_sel_hi:[1,0]
	v_lshlrev_b32_e32 v14, 16, v118
	v_and_b32_e32 v15, 0xffff0000, v118
	v_lshlrev_b32_e32 v16, 16, v120
	v_and_b32_e32 v17, 0xffff0000, v120
	v_lshlrev_b32_e32 v18, 16, v119
	v_and_b32_e32 v19, 0xffff0000, v119
	v_lshlrev_b32_e32 v20, 16, v121
	v_and_b32_e32 v21, 0xffff0000, v121
	v_pk_add_f32 v[118:119], v[14:15], v[16:17]
	v_pk_add_f32 v[120:121], v[18:19], v[20:21]
	v_lshlrev_b32_e32 v14, 16, v122
	v_and_b32_e32 v15, 0xffff0000, v122
	v_lshlrev_b32_e32 v16, 16, v124
	v_and_b32_e32 v17, 0xffff0000, v124
	v_lshlrev_b32_e32 v18, 16, v123
	v_and_b32_e32 v19, 0xffff0000, v123
	v_lshlrev_b32_e32 v20, 16, v125
	v_and_b32_e32 v21, 0xffff0000, v125
	v_pk_add_f32 v[122:123], v[14:15], v[16:17]
	v_pk_add_f32 v[124:125], v[18:19], v[20:21]
	v_lshlrev_b32_e32 v14, 16, v134
	v_and_b32_e32 v15, 0xffff0000, v134
	v_lshlrev_b32_e32 v16, 16, v136
	v_and_b32_e32 v17, 0xffff0000, v136
	v_lshlrev_b32_e32 v18, 16, v135
	v_and_b32_e32 v19, 0xffff0000, v135
	v_lshlrev_b32_e32 v20, 16, v137
	v_and_b32_e32 v21, 0xffff0000, v137
	v_pk_add_f32 v[134:135], v[14:15], v[16:17]
	v_pk_add_f32 v[136:137], v[18:19], v[20:21]
	v_lshlrev_b32_e32 v14, 16, v138
	v_and_b32_e32 v15, 0xffff0000, v138
	v_lshlrev_b32_e32 v16, 16, v140
	v_and_b32_e32 v17, 0xffff0000, v140
	v_lshlrev_b32_e32 v18, 16, v139
	v_and_b32_e32 v19, 0xffff0000, v139
	v_lshlrev_b32_e32 v20, 16, v141
	v_and_b32_e32 v21, 0xffff0000, v141
	v_pk_add_f32 v[138:139], v[14:15], v[16:17]
	v_pk_add_f32 v[140:141], v[18:19], v[20:21]
	v_pk_mul_f32 v[12:13], v[118:119], v[118:119]
	v_pk_fma_f32 v[12:13], v[120:121], v[120:121], v[12:13]
	v_pk_fma_f32 v[12:13], v[122:123], v[122:123], v[12:13]
	v_pk_fma_f32 v[12:13], v[124:125], v[124:125], v[12:13]
	v_pk_fma_f32 v[12:13], v[134:135], v[134:135], v[12:13]
	v_pk_fma_f32 v[12:13], v[136:137], v[136:137], v[12:13]
	v_pk_fma_f32 v[12:13], v[138:139], v[138:139], v[12:13]
	v_pk_fma_f32 v[12:13], v[140:141], v[140:141], v[12:13]
	v_add_f32_e32 v5, v12, v13
	s_nop 1
	v_add_f32_dpp v5, v5, v5 quad_perm:[1,0,3,2] row_mask:0xf bank_mask:0xf
	s_nop 1
	v_add_f32_dpp v5, v5, v5 quad_perm:[2,3,0,1] row_mask:0xf bank_mask:0xf
	s_nop 1
	v_add_f32_dpp v5, v5, v5 row_half_mirror row_mask:0xf bank_mask:0xf
	s_nop 1
	v_add_f32_dpp v5, v5, v5 row_mirror row_mask:0xf bank_mask:0xf
	s_nop 1
	v_add_f32_dpp v5, v5, v5 row_bcast:15 row_mask:0xa bank_mask:0xf
	s_nop 1
	v_add_f32_dpp v5, v5, v5 row_bcast:31 row_mask:0xc bank_mask:0xf
	s_nop 1
	v_readlane_b32 s32, v5, 63
	s_nop 1
	v_mov_b32_e32 v6, s32
	v_fmamk_f32 v6, v6, 0x3a800000, v146
	v_rsq_f32_e32 v6, v6
	s_nop 0
	v_mul_f32_e32 v8, 0.5, v6
	v_pk_mul_f32 v[14:15], v[118:119], v[8:9] op_sel_hi:[1,0]
	v_pk_mul_f32 v[14:15], v[38:39], v[14:15]
	v_pk_fma_f32 v[102:103], v[22:23], v[14:15], v[102:103]
	v_pk_mul_f32 v[14:15], v[120:121], v[8:9] op_sel_hi:[1,0]
	v_pk_mul_f32 v[14:15], v[40:41], v[14:15]
	v_pk_fma_f32 v[104:105], v[24:25], v[14:15], v[104:105]
	v_pk_mul_f32 v[14:15], v[122:123], v[8:9] op_sel_hi:[1,0]
	v_pk_mul_f32 v[14:15], v[42:43], v[14:15]
	v_pk_fma_f32 v[106:107], v[26:27], v[14:15], v[106:107]
	v_pk_mul_f32 v[14:15], v[124:125], v[8:9] op_sel_hi:[1,0]
	v_pk_mul_f32 v[14:15], v[44:45], v[14:15]
	v_pk_fma_f32 v[108:109], v[28:29], v[14:15], v[108:109]
	v_pk_mul_f32 v[14:15], v[134:135], v[8:9] op_sel_hi:[1,0]
	v_pk_mul_f32 v[14:15], v[46:47], v[14:15]
	v_pk_fma_f32 v[110:111], v[30:31], v[14:15], v[110:111]
	v_pk_mul_f32 v[14:15], v[136:137], v[8:9] op_sel_hi:[1,0]
	v_pk_mul_f32 v[14:15], v[48:49], v[14:15]
	v_pk_fma_f32 v[112:113], v[32:33], v[14:15], v[112:113]
	v_pk_mul_f32 v[14:15], v[138:139], v[8:9] op_sel_hi:[1,0]
	v_pk_mul_f32 v[14:15], v[50:51], v[14:15]
	v_pk_fma_f32 v[114:115], v[34:35], v[14:15], v[114:115]
	v_pk_mul_f32 v[14:15], v[140:141], v[8:9] op_sel_hi:[1,0]
	v_pk_mul_f32 v[14:15], v[52:53], v[14:15]
	v_pk_fma_f32 v[116:117], v[36:37], v[14:15], v[116:117]
	v_pk_mul_f32 v[12:13], v[102:103], v[102:103]
	v_pk_fma_f32 v[12:13], v[104:105], v[104:105], v[12:13]
	v_pk_fma_f32 v[12:13], v[106:107], v[106:107], v[12:13]
	v_pk_fma_f32 v[12:13], v[108:109], v[108:109], v[12:13]
	v_pk_fma_f32 v[12:13], v[110:111], v[110:111], v[12:13]
	v_pk_fma_f32 v[12:13], v[112:113], v[112:113], v[12:13]
	v_pk_fma_f32 v[12:13], v[114:115], v[114:115], v[12:13]
	v_pk_fma_f32 v[12:13], v[116:117], v[116:117], v[12:13]
	v_add_f32_e32 v5, v12, v13
	s_nop 1
	v_add_f32_dpp v5, v5, v5 quad_perm:[1,0,3,2] row_mask:0xf bank_mask:0xf
	s_nop 1
	v_add_f32_dpp v5, v5, v5 quad_perm:[2,3,0,1] row_mask:0xf bank_mask:0xf
	s_nop 1
	v_add_f32_dpp v5, v5, v5 row_half_mirror row_mask:0xf bank_mask:0xf
	s_nop 1
	v_add_f32_dpp v5, v5, v5 row_mirror row_mask:0xf bank_mask:0xf
	s_nop 1
	v_add_f32_dpp v5, v5, v5 row_bcast:15 row_mask:0xa bank_mask:0xf
	s_nop 1
	v_add_f32_dpp v5, v5, v5 row_bcast:31 row_mask:0xc bank_mask:0xf
	s_nop 1
	v_readlane_b32 s32, v5, 63
	s_nop 1
	v_mov_b32_e32 v6, s32
	v_fmamk_f32 v6, v6, 0x3a800000, v146
	v_rsq_f32_e32 v6, v6
	s_nop 0
	v_mov_b32_e32 v10, v6
	v_pk_mul_f32 v[14:15], v[102:103], v[10:11] op_sel_hi:[1,0]
	v_pk_mul_f32 v[14:15], v[86:87], v[14:15]
	v_pk_fma_f32 v[16:17], v[70:71], v[14:15], v[54:55]
	v_pk_mul_f32 v[14:15], v[104:105], v[10:11] op_sel_hi:[1,0]
	v_pk_mul_f32 v[14:15], v[88:89], v[14:15]
	v_pk_fma_f32 v[18:19], v[72:73], v[14:15], v[56:57]
	v_cvt_pk_bf16_f32 v118, v16, v17
	v_cvt_pk_bf16_f32 v119, v18, v19
	v_pk_mul_f32 v[14:15], v[106:107], v[10:11] op_sel_hi:[1,0]
	v_pk_mul_f32 v[14:15], v[90:91], v[14:15]
	v_pk_fma_f32 v[16:17], v[74:75], v[14:15], v[58:59]
	v_pk_mul_f32 v[14:15], v[108:109], v[10:11] op_sel_hi:[1,0]
	v_pk_mul_f32 v[14:15], v[92:93], v[14:15]
	v_pk_fma_f32 v[18:19], v[76:77], v[14:15], v[60:61]
	v_cvt_pk_bf16_f32 v122, v16, v17
	v_cvt_pk_bf16_f32 v123, v18, v19
	v_pk_mul_f32 v[14:15], v[110:111], v[10:11] op_sel_hi:[1,0]
	v_pk_mul_f32 v[14:15], v[94:95], v[14:15]
	v_pk_fma_f32 v[16:17], v[78:79], v[14:15], v[62:63]
	v_pk_mul_f32 v[14:15], v[112:113], v[10:11] op_sel_hi:[1,0]
	v_pk_mul_f32 v[14:15], v[96:97], v[14:15]
	v_pk_fma_f32 v[18:19], v[80:81], v[14:15], v[64:65]
	v_cvt_pk_bf16_f32 v134, v16, v17
	v_cvt_pk_bf16_f32 v135, v18, v19
	v_pk_mul_f32 v[14:15], v[114:115], v[10:11] op_sel_hi:[1,0]
	v_pk_mul_f32 v[14:15], v[98:99], v[14:15]
	v_pk_fma_f32 v[16:17], v[82:83], v[14:15], v[66:67]
	v_pk_mul_f32 v[14:15], v[116:117], v[10:11] op_sel_hi:[1,0]
	v_pk_mul_f32 v[14:15], v[100:101], v[14:15]
	v_pk_fma_f32 v[18:19], v[84:85], v[14:15], v[68:69]
	v_cvt_pk_bf16_f32 v138, v16, v17
	v_cvt_pk_bf16_f32 v139, v18, v19
	global_store_dwordx4 v0, v[102:105], s[46:47] offset:0 sc1
	global_store_dwordx4 v0, v[106:109], s[46:47] offset:1024 sc1
	global_store_dwordx4 v0, v[110:113], s[46:47] offset:2048 sc1
	global_store_dwordx4 v0, v[114:117], s[46:47] offset:3072 sc1
	global_store_dwordx2 v1, v[118:119], s[62:63] offset:0 sc1
	global_store_dwordx2 v1, v[122:123], s[62:63] offset:512 sc1
	global_store_dwordx2 v1, v[134:135], s[62:63] offset:1024 sc1
	global_store_dwordx2 v1, v[138:139], s[62:63] offset:1536 sc1
	s_add_u32 s46, s46, 0x1000
	s_addc_u32 s47, s47, 0
	s_add_u32 s62, s62, 0x800
	s_addc_u32 s63, s63, 0
	s_nop 1
	global_load_dwordx4 v[102:105], v0, s[4:5] offset:0
	global_load_dwordx4 v[106:109], v0, s[4:5] offset:1024
	global_load_dwordx4 v[110:113], v0, s[4:5] offset:2048
	global_load_dwordx4 v[114:117], v0, s[4:5] offset:3072
	global_load_dwordx2 v[118:119], v1, s[58:59] offset:0
	global_load_dwordx2 v[122:123], v1, s[58:59] offset:512
	global_load_dwordx2 v[134:135], v1, s[58:59] offset:1024
	global_load_dwordx2 v[138:139], v1, s[58:59] offset:1536
	global_load_dwordx2 v[120:121], v1, s[60:61] offset:0
	global_load_dwordx2 v[124:125], v1, s[60:61] offset:512
	global_load_dwordx2 v[136:137], v1, s[60:61] offset:1024
	global_load_dwordx2 v[140:141], v1, s[60:61] offset:1536
	s_add_u32 s4, s4, 0x1000
	s_addc_u32 s5, s5, 0
	s_add_u32 s58, s58, 0x800
	s_addc_u32 s59, s59, 0
	s_add_u32 s60, s60, 0x800
	s_addc_u32 s61, s61, 0
	s_waitcnt vmcnt(32)
	v_lshlrev_b32_e32 v14, 16, v172
	v_and_b32_e32 v15, 0xffff0000, v172
	v_lshlrev_b32_e32 v16, 16, v174
	v_and_b32_e32 v17, 0xffff0000, v174
	v_lshlrev_b32_e32 v18, 16, v173
	v_and_b32_e32 v19, 0xffff0000, v173
	v_lshlrev_b32_e32 v20, 16, v175
	v_and_b32_e32 v21, 0xffff0000, v175
	v_pk_add_f32 v[172:173], v[14:15], v[16:17]
	v_pk_add_f32 v[174:175], v[18:19], v[20:21]
	v_lshlrev_b32_e32 v14, 16, v176
	v_and_b32_e32 v15, 0xffff0000, v176
	v_lshlrev_b32_e32 v16, 16, v178
	v_and_b32_e32 v17, 0xffff0000, v178
	v_lshlrev_b32_e32 v18, 16, v177
	v_and_b32_e32 v19, 0xffff0000, v177
	v_lshlrev_b32_e32 v20, 16, v179
	v_and_b32_e32 v21, 0xffff0000, v179
	v_pk_add_f32 v[176:177], v[14:15], v[16:17]
	v_pk_add_f32 v[178:179], v[18:19], v[20:21]
	v_lshlrev_b32_e32 v14, 16, v204
	v_and_b32_e32 v15, 0xffff0000, v204
	v_lshlrev_b32_e32 v16, 16, v206
	v_and_b32_e32 v17, 0xffff0000, v206
	v_lshlrev_b32_e32 v18, 16, v205
	v_and_b32_e32 v19, 0xffff0000, v205
	v_lshlrev_b32_e32 v20, 16, v207
	v_and_b32_e32 v21, 0xffff0000, v207
	v_pk_add_f32 v[204:205], v[14:15], v[16:17]
	v_pk_add_f32 v[206:207], v[18:19], v[20:21]
	v_lshlrev_b32_e32 v14, 16, v214
	v_and_b32_e32 v15, 0xffff0000, v214
	v_lshlrev_b32_e32 v16, 16, v216
	v_and_b32_e32 v17, 0xffff0000, v216
	v_lshlrev_b32_e32 v18, 16, v215
	v_and_b32_e32 v19, 0xffff0000, v215
	v_lshlrev_b32_e32 v20, 16, v217
	v_and_b32_e32 v21, 0xffff0000, v217
	v_pk_add_f32 v[214:215], v[14:15], v[16:17]
	v_pk_add_f32 v[216:217], v[18:19], v[20:21]
	v_pk_mul_f32 v[12:13], v[172:173], v[172:173]
	v_pk_fma_f32 v[12:13], v[174:175], v[174:175], v[12:13]
	v_pk_fma_f32 v[12:13], v[176:177], v[176:177], v[12:13]
	v_pk_fma_f32 v[12:13], v[178:179], v[178:179], v[12:13]
	v_pk_fma_f32 v[12:13], v[204:205], v[204:205], v[12:13]
	v_pk_fma_f32 v[12:13], v[206:207], v[206:207], v[12:13]
	v_pk_fma_f32 v[12:13], v[214:215], v[214:215], v[12:13]
	v_pk_fma_f32 v[12:13], v[216:217], v[216:217], v[12:13]
	v_add_f32_e32 v5, v12, v13
	s_nop 1
	v_add_f32_dpp v5, v5, v5 quad_perm:[1,0,3,2] row_mask:0xf bank_mask:0xf
	s_nop 1
	v_add_f32_dpp v5, v5, v5 quad_perm:[2,3,0,1] row_mask:0xf bank_mask:0xf
	s_nop 1
	v_add_f32_dpp v5, v5, v5 row_half_mirror row_mask:0xf bank_mask:0xf
	s_nop 1
	v_add_f32_dpp v5, v5, v5 row_mirror row_mask:0xf bank_mask:0xf
	s_nop 1
	v_add_f32_dpp v5, v5, v5 row_bcast:15 row_mask:0xa bank_mask:0xf
	s_nop 1
	v_add_f32_dpp v5, v5, v5 row_bcast:31 row_mask:0xc bank_mask:0xf
	s_nop 1
	v_readlane_b32 s32, v5, 63
	s_nop 1
	v_mov_b32_e32 v6, s32
	v_fmamk_f32 v6, v6, 0x3a800000, v146
	v_rsq_f32_e32 v6, v6
	s_nop 0
	v_mul_f32_e32 v8, 0.5, v6
	v_pk_mul_f32 v[14:15], v[172:173], v[8:9] op_sel_hi:[1,0]
	v_pk_mul_f32 v[14:15], v[38:39], v[14:15]
	v_pk_fma_f32 v[154:155], v[22:23], v[14:15], v[154:155]
	v_pk_mul_f32 v[14:15], v[174:175], v[8:9] op_sel_hi:[1,0]
	v_pk_mul_f32 v[14:15], v[40:41], v[14:15]
	v_pk_fma_f32 v[156:157], v[24:25], v[14:15], v[156:157]
	v_pk_mul_f32 v[14:15], v[176:177], v[8:9] op_sel_hi:[1,0]
	v_pk_mul_f32 v[14:15], v[42:43], v[14:15]
	v_pk_fma_f32 v[158:159], v[26:27], v[14:15], v[158:159]
	v_pk_mul_f32 v[14:15], v[178:179], v[8:9] op_sel_hi:[1,0]
	v_pk_mul_f32 v[14:15], v[44:45], v[14:15]
	v_pk_fma_f32 v[160:161], v[28:29], v[14:15], v[160:161]
	v_pk_mul_f32 v[14:15], v[204:205], v[8:9] op_sel_hi:[1,0]
	v_pk_mul_f32 v[14:15], v[46:47], v[14:15]
	v_pk_fma_f32 v[162:163], v[30:31], v[14:15], v[162:163]
	v_pk_mul_f32 v[14:15], v[206:207], v[8:9] op_sel_hi:[1,0]
	v_pk_mul_f32 v[14:15], v[48:49], v[14:15]
	v_pk_fma_f32 v[164:165], v[32:33], v[14:15], v[164:165]
	v_pk_mul_f32 v[14:15], v[214:215], v[8:9] op_sel_hi:[1,0]
	v_pk_mul_f32 v[14:15], v[50:51], v[14:15]
	v_pk_fma_f32 v[168:169], v[34:35], v[14:15], v[168:169]
	v_pk_mul_f32 v[14:15], v[216:217], v[8:9] op_sel_hi:[1,0]
	v_pk_mul_f32 v[14:15], v[52:53], v[14:15]
	v_pk_fma_f32 v[170:171], v[36:37], v[14:15], v[170:171]
	v_pk_mul_f32 v[12:13], v[154:155], v[154:155]
	v_pk_fma_f32 v[12:13], v[156:157], v[156:157], v[12:13]
	v_pk_fma_f32 v[12:13], v[158:159], v[158:159], v[12:13]
	v_pk_fma_f32 v[12:13], v[160:161], v[160:161], v[12:13]
	v_pk_fma_f32 v[12:13], v[162:163], v[162:163], v[12:13]
	v_pk_fma_f32 v[12:13], v[164:165], v[164:165], v[12:13]
	v_pk_fma_f32 v[12:13], v[168:169], v[168:169], v[12:13]
	v_pk_fma_f32 v[12:13], v[170:171], v[170:171], v[12:13]
	v_add_f32_e32 v5, v12, v13
	s_nop 1
	v_add_f32_dpp v5, v5, v5 quad_perm:[1,0,3,2] row_mask:0xf bank_mask:0xf
	s_nop 1
	v_add_f32_dpp v5, v5, v5 quad_perm:[2,3,0,1] row_mask:0xf bank_mask:0xf
	s_nop 1
	v_add_f32_dpp v5, v5, v5 row_half_mirror row_mask:0xf bank_mask:0xf
	s_nop 1
	v_add_f32_dpp v5, v5, v5 row_mirror row_mask:0xf bank_mask:0xf
	s_nop 1
	v_add_f32_dpp v5, v5, v5 row_bcast:15 row_mask:0xa bank_mask:0xf
	s_nop 1
	v_add_f32_dpp v5, v5, v5 row_bcast:31 row_mask:0xc bank_mask:0xf
	s_nop 1
	v_readlane_b32 s32, v5, 63
	s_nop 1
	v_mov_b32_e32 v6, s32
	v_fmamk_f32 v6, v6, 0x3a800000, v146
	v_rsq_f32_e32 v6, v6
	s_nop 0
	v_mov_b32_e32 v10, v6
	v_pk_mul_f32 v[14:15], v[154:155], v[10:11] op_sel_hi:[1,0]
	v_pk_mul_f32 v[14:15], v[86:87], v[14:15]
	v_pk_fma_f32 v[16:17], v[70:71], v[14:15], v[54:55]
	v_pk_mul_f32 v[14:15], v[156:157], v[10:11] op_sel_hi:[1,0]
	v_pk_mul_f32 v[14:15], v[88:89], v[14:15]
	v_pk_fma_f32 v[18:19], v[72:73], v[14:15], v[56:57]
	v_cvt_pk_bf16_f32 v172, v16, v17
	v_cvt_pk_bf16_f32 v173, v18, v19
	v_pk_mul_f32 v[14:15], v[158:159], v[10:11] op_sel_hi:[1,0]
	v_pk_mul_f32 v[14:15], v[90:91], v[14:15]
	v_pk_fma_f32 v[16:17], v[74:75], v[14:15], v[58:59]
	v_pk_mul_f32 v[14:15], v[160:161], v[10:11] op_sel_hi:[1,0]
	v_pk_mul_f32 v[14:15], v[92:93], v[14:15]
	v_pk_fma_f32 v[18:19], v[76:77], v[14:15], v[60:61]
	v_cvt_pk_bf16_f32 v176, v16, v17
	v_cvt_pk_bf16_f32 v177, v18, v19
	v_pk_mul_f32 v[14:15], v[162:163], v[10:11] op_sel_hi:[1,0]
	v_pk_mul_f32 v[14:15], v[94:95], v[14:15]
	v_pk_fma_f32 v[16:17], v[78:79], v[14:15], v[62:63]
	v_pk_mul_f32 v[14:15], v[164:165], v[10:11] op_sel_hi:[1,0]
	v_pk_mul_f32 v[14:15], v[96:97], v[14:15]
	v_pk_fma_f32 v[18:19], v[80:81], v[14:15], v[64:65]
	v_cvt_pk_bf16_f32 v204, v16, v17
	v_cvt_pk_bf16_f32 v205, v18, v19
	v_pk_mul_f32 v[14:15], v[168:169], v[10:11] op_sel_hi:[1,0]
	v_pk_mul_f32 v[14:15], v[98:99], v[14:15]
	v_pk_fma_f32 v[16:17], v[82:83], v[14:15], v[66:67]
	v_pk_mul_f32 v[14:15], v[170:171], v[10:11] op_sel_hi:[1,0]
	v_pk_mul_f32 v[14:15], v[100:101], v[14:15]
	v_pk_fma_f32 v[18:19], v[84:85], v[14:15], v[68:69]
	v_cvt_pk_bf16_f32 v214, v16, v17
	v_cvt_pk_bf16_f32 v215, v18, v19
	global_store_dwordx4 v0, v[154:157], s[46:47] offset:0 sc1
	global_store_dwordx4 v0, v[158:161], s[46:47] offset:1024 sc1
	global_store_dwordx4 v0, v[162:165], s[46:47] offset:2048 sc1
	global_store_dwordx4 v0, v[168:171], s[46:47] offset:3072 sc1
	global_store_dwordx2 v1, v[172:173], s[62:63] offset:0 sc1
	global_store_dwordx2 v1, v[176:177], s[62:63] offset:512 sc1
	global_store_dwordx2 v1, v[204:205], s[62:63] offset:1024 sc1
	global_store_dwordx2 v1, v[214:215], s[62:63] offset:1536 sc1
	s_add_u32 s46, s46, 0x1000
	s_addc_u32 s47, s47, 0
	s_add_u32 s62, s62, 0x800
	s_addc_u32 s63, s63, 0
	s_waitcnt vmcnt(28)
	v_lshlrev_b32_e32 v14, 16, v234
	v_and_b32_e32 v15, 0xffff0000, v234
	v_lshlrev_b32_e32 v16, 16, v236
	v_and_b32_e32 v17, 0xffff0000, v236
	v_lshlrev_b32_e32 v18, 16, v235
	v_and_b32_e32 v19, 0xffff0000, v235
	v_lshlrev_b32_e32 v20, 16, v237
	v_and_b32_e32 v21, 0xffff0000, v237
	v_pk_add_f32 v[234:235], v[14:15], v[16:17]
	v_pk_add_f32 v[236:237], v[18:19], v[20:21]
	v_lshlrev_b32_e32 v14, 16, v238
	v_and_b32_e32 v15, 0xffff0000, v238
	v_lshlrev_b32_e32 v16, 16, v240
	v_and_b32_e32 v17, 0xffff0000, v240
	v_lshlrev_b32_e32 v18, 16, v239
	v_and_b32_e32 v19, 0xffff0000, v239
	v_lshlrev_b32_e32 v20, 16, v241
	v_and_b32_e32 v21, 0xffff0000, v241
	v_pk_add_f32 v[238:239], v[14:15], v[16:17]
	v_pk_add_f32 v[240:241], v[18:19], v[20:21]
	v_lshlrev_b32_e32 v14, 16, v242
	v_and_b32_e32 v15, 0xffff0000, v242
	v_lshlrev_b32_e32 v16, 16, v244
	v_and_b32_e32 v17, 0xffff0000, v244
	v_lshlrev_b32_e32 v18, 16, v243
	v_and_b32_e32 v19, 0xffff0000, v243
	v_lshlrev_b32_e32 v20, 16, v245
	v_and_b32_e32 v21, 0xffff0000, v245
	v_pk_add_f32 v[242:243], v[14:15], v[16:17]
	v_pk_add_f32 v[244:245], v[18:19], v[20:21]
	v_lshlrev_b32_e32 v14, 16, v246
	v_and_b32_e32 v15, 0xffff0000, v246
	v_lshlrev_b32_e32 v16, 16, v248
	v_and_b32_e32 v17, 0xffff0000, v248
	v_lshlrev_b32_e32 v18, 16, v247
	v_and_b32_e32 v19, 0xffff0000, v247
	v_lshlrev_b32_e32 v20, 16, v249
	v_and_b32_e32 v21, 0xffff0000, v249
	v_pk_add_f32 v[246:247], v[14:15], v[16:17]
	v_pk_add_f32 v[248:249], v[18:19], v[20:21]
	v_pk_mul_f32 v[12:13], v[234:235], v[234:235]
	v_pk_fma_f32 v[12:13], v[236:237], v[236:237], v[12:13]
	v_pk_fma_f32 v[12:13], v[238:239], v[238:239], v[12:13]
	v_pk_fma_f32 v[12:13], v[240:241], v[240:241], v[12:13]
	v_pk_fma_f32 v[12:13], v[242:243], v[242:243], v[12:13]
	v_pk_fma_f32 v[12:13], v[244:245], v[244:245], v[12:13]
	v_pk_fma_f32 v[12:13], v[246:247], v[246:247], v[12:13]
	v_pk_fma_f32 v[12:13], v[248:249], v[248:249], v[12:13]
	v_add_f32_e32 v5, v12, v13
	s_nop 1
	v_add_f32_dpp v5, v5, v5 quad_perm:[1,0,3,2] row_mask:0xf bank_mask:0xf
	s_nop 1
	v_add_f32_dpp v5, v5, v5 quad_perm:[2,3,0,1] row_mask:0xf bank_mask:0xf
	s_nop 1
	v_add_f32_dpp v5, v5, v5 row_half_mirror row_mask:0xf bank_mask:0xf
	s_nop 1
	v_add_f32_dpp v5, v5, v5 row_mirror row_mask:0xf bank_mask:0xf
	s_nop 1
	v_add_f32_dpp v5, v5, v5 row_bcast:15 row_mask:0xa bank_mask:0xf
	s_nop 1
	v_add_f32_dpp v5, v5, v5 row_bcast:31 row_mask:0xc bank_mask:0xf
	s_nop 1
	v_readlane_b32 s32, v5, 63
	s_nop 1
	v_mov_b32_e32 v6, s32
	v_fmamk_f32 v6, v6, 0x3a800000, v146
	v_rsq_f32_e32 v6, v6
	s_nop 0
	v_mul_f32_e32 v8, 0.5, v6
	v_pk_mul_f32 v[14:15], v[234:235], v[8:9] op_sel_hi:[1,0]
	v_pk_mul_f32 v[14:15], v[38:39], v[14:15]
	v_pk_fma_f32 v[218:219], v[22:23], v[14:15], v[218:219]
	v_pk_mul_f32 v[14:15], v[236:237], v[8:9] op_sel_hi:[1,0]
	v_pk_mul_f32 v[14:15], v[40:41], v[14:15]
	v_pk_fma_f32 v[220:221], v[24:25], v[14:15], v[220:221]
	v_pk_mul_f32 v[14:15], v[238:239], v[8:9] op_sel_hi:[1,0]
	v_pk_mul_f32 v[14:15], v[42:43], v[14:15]
	v_pk_fma_f32 v[222:223], v[26:27], v[14:15], v[222:223]
	v_pk_mul_f32 v[14:15], v[240:241], v[8:9] op_sel_hi:[1,0]
	v_pk_mul_f32 v[14:15], v[44:45], v[14:15]
	v_pk_fma_f32 v[224:225], v[28:29], v[14:15], v[224:225]
	v_pk_mul_f32 v[14:15], v[242:243], v[8:9] op_sel_hi:[1,0]
	v_pk_mul_f32 v[14:15], v[46:47], v[14:15]
	v_pk_fma_f32 v[226:227], v[30:31], v[14:15], v[226:227]
	v_pk_mul_f32 v[14:15], v[244:245], v[8:9] op_sel_hi:[1,0]
	v_pk_mul_f32 v[14:15], v[48:49], v[14:15]
	v_pk_fma_f32 v[228:229], v[32:33], v[14:15], v[228:229]
	v_pk_mul_f32 v[14:15], v[246:247], v[8:9] op_sel_hi:[1,0]
	v_pk_mul_f32 v[14:15], v[50:51], v[14:15]
	v_pk_fma_f32 v[230:231], v[34:35], v[14:15], v[230:231]
	v_pk_mul_f32 v[14:15], v[248:249], v[8:9] op_sel_hi:[1,0]
	v_pk_mul_f32 v[14:15], v[52:53], v[14:15]
	v_pk_fma_f32 v[232:233], v[36:37], v[14:15], v[232:233]
	v_pk_mul_f32 v[12:13], v[218:219], v[218:219]
	v_pk_fma_f32 v[12:13], v[220:221], v[220:221], v[12:13]
	v_pk_fma_f32 v[12:13], v[222:223], v[222:223], v[12:13]
	v_pk_fma_f32 v[12:13], v[224:225], v[224:225], v[12:13]
	v_pk_fma_f32 v[12:13], v[226:227], v[226:227], v[12:13]
	v_pk_fma_f32 v[12:13], v[228:229], v[228:229], v[12:13]
	v_pk_fma_f32 v[12:13], v[230:231], v[230:231], v[12:13]
	v_pk_fma_f32 v[12:13], v[232:233], v[232:233], v[12:13]
	v_add_f32_e32 v5, v12, v13
	s_nop 1
	v_add_f32_dpp v5, v5, v5 quad_perm:[1,0,3,2] row_mask:0xf bank_mask:0xf
	s_nop 1
	v_add_f32_dpp v5, v5, v5 quad_perm:[2,3,0,1] row_mask:0xf bank_mask:0xf
	s_nop 1
	v_add_f32_dpp v5, v5, v5 row_half_mirror row_mask:0xf bank_mask:0xf
	s_nop 1
	v_add_f32_dpp v5, v5, v5 row_mirror row_mask:0xf bank_mask:0xf
	s_nop 1
	v_add_f32_dpp v5, v5, v5 row_bcast:15 row_mask:0xa bank_mask:0xf
	s_nop 1
	v_add_f32_dpp v5, v5, v5 row_bcast:31 row_mask:0xc bank_mask:0xf
	s_nop 1
	v_readlane_b32 s32, v5, 63
	s_nop 1
	v_mov_b32_e32 v6, s32
	v_fmamk_f32 v6, v6, 0x3a800000, v146
	v_rsq_f32_e32 v6, v6
	s_nop 0
	v_mov_b32_e32 v10, v6
	v_pk_mul_f32 v[14:15], v[218:219], v[10:11] op_sel_hi:[1,0]
	v_pk_mul_f32 v[14:15], v[86:87], v[14:15]
	v_pk_fma_f32 v[16:17], v[70:71], v[14:15], v[54:55]
	v_pk_mul_f32 v[14:15], v[220:221], v[10:11] op_sel_hi:[1,0]
	v_pk_mul_f32 v[14:15], v[88:89], v[14:15]
	v_pk_fma_f32 v[18:19], v[72:73], v[14:15], v[56:57]
	v_cvt_pk_bf16_f32 v234, v16, v17
	v_cvt_pk_bf16_f32 v235, v18, v19
	v_pk_mul_f32 v[14:15], v[222:223], v[10:11] op_sel_hi:[1,0]
	v_pk_mul_f32 v[14:15], v[90:91], v[14:15]
	v_pk_fma_f32 v[16:17], v[74:75], v[14:15], v[58:59]
	v_pk_mul_f32 v[14:15], v[224:225], v[10:11] op_sel_hi:[1,0]
	v_pk_mul_f32 v[14:15], v[92:93], v[14:15]
	v_pk_fma_f32 v[18:19], v[76:77], v[14:15], v[60:61]
	v_cvt_pk_bf16_f32 v238, v16, v17
	v_cvt_pk_bf16_f32 v239, v18, v19
	v_pk_mul_f32 v[14:15], v[226:227], v[10:11] op_sel_hi:[1,0]
	v_pk_mul_f32 v[14:15], v[94:95], v[14:15]
	v_pk_fma_f32 v[16:17], v[78:79], v[14:15], v[62:63]
	v_pk_mul_f32 v[14:15], v[228:229], v[10:11] op_sel_hi:[1,0]
	v_pk_mul_f32 v[14:15], v[96:97], v[14:15]
	v_pk_fma_f32 v[18:19], v[80:81], v[14:15], v[64:65]
	v_cvt_pk_bf16_f32 v242, v16, v17
	v_cvt_pk_bf16_f32 v243, v18, v19
	v_pk_mul_f32 v[14:15], v[230:231], v[10:11] op_sel_hi:[1,0]
	v_pk_mul_f32 v[14:15], v[98:99], v[14:15]
	v_pk_fma_f32 v[16:17], v[82:83], v[14:15], v[66:67]
	v_pk_mul_f32 v[14:15], v[232:233], v[10:11] op_sel_hi:[1,0]
	v_pk_mul_f32 v[14:15], v[100:101], v[14:15]
	v_pk_fma_f32 v[18:19], v[84:85], v[14:15], v[68:69]
	v_cvt_pk_bf16_f32 v246, v16, v17
	v_cvt_pk_bf16_f32 v247, v18, v19
	global_store_dwordx4 v0, v[218:221], s[46:47] offset:0 sc1
	global_store_dwordx4 v0, v[222:225], s[46:47] offset:1024 sc1
	global_store_dwordx4 v0, v[226:229], s[46:47] offset:2048 sc1
	global_store_dwordx4 v0, v[230:233], s[46:47] offset:3072 sc1
	global_store_dwordx2 v1, v[234:235], s[62:63] offset:0 sc1
	global_store_dwordx2 v1, v[238:239], s[62:63] offset:512 sc1
	global_store_dwordx2 v1, v[242:243], s[62:63] offset:1024 sc1
	global_store_dwordx2 v1, v[246:247], s[62:63] offset:1536 sc1
	s_add_u32 s46, s46, 0x1000
	s_addc_u32 s47, s47, 0
	s_add_u32 s62, s62, 0x800
	s_addc_u32 s63, s63, 0
	s_waitcnt vmcnt(16)
	v_lshlrev_b32_e32 v14, 16, v118
	v_and_b32_e32 v15, 0xffff0000, v118
	v_lshlrev_b32_e32 v16, 16, v120
	v_and_b32_e32 v17, 0xffff0000, v120
	v_lshlrev_b32_e32 v18, 16, v119
	v_and_b32_e32 v19, 0xffff0000, v119
	v_lshlrev_b32_e32 v20, 16, v121
	v_and_b32_e32 v21, 0xffff0000, v121
	v_pk_add_f32 v[118:119], v[14:15], v[16:17]
	v_pk_add_f32 v[120:121], v[18:19], v[20:21]
	v_lshlrev_b32_e32 v14, 16, v122
	v_and_b32_e32 v15, 0xffff0000, v122
	v_lshlrev_b32_e32 v16, 16, v124
	v_and_b32_e32 v17, 0xffff0000, v124
	v_lshlrev_b32_e32 v18, 16, v123
	v_and_b32_e32 v19, 0xffff0000, v123
	v_lshlrev_b32_e32 v20, 16, v125
	v_and_b32_e32 v21, 0xffff0000, v125
	v_pk_add_f32 v[122:123], v[14:15], v[16:17]
	v_pk_add_f32 v[124:125], v[18:19], v[20:21]
	v_lshlrev_b32_e32 v14, 16, v134
	v_and_b32_e32 v15, 0xffff0000, v134
	v_lshlrev_b32_e32 v16, 16, v136
	v_and_b32_e32 v17, 0xffff0000, v136
	v_lshlrev_b32_e32 v18, 16, v135
	v_and_b32_e32 v19, 0xffff0000, v135
	v_lshlrev_b32_e32 v20, 16, v137
	v_and_b32_e32 v21, 0xffff0000, v137
	v_pk_add_f32 v[134:135], v[14:15], v[16:17]
	v_pk_add_f32 v[136:137], v[18:19], v[20:21]
	v_lshlrev_b32_e32 v14, 16, v138
	v_and_b32_e32 v15, 0xffff0000, v138
	v_lshlrev_b32_e32 v16, 16, v140
	v_and_b32_e32 v17, 0xffff0000, v140
	v_lshlrev_b32_e32 v18, 16, v139
	v_and_b32_e32 v19, 0xffff0000, v139
	v_lshlrev_b32_e32 v20, 16, v141
	v_and_b32_e32 v21, 0xffff0000, v141
	v_pk_add_f32 v[138:139], v[14:15], v[16:17]
	v_pk_add_f32 v[140:141], v[18:19], v[20:21]
	v_pk_mul_f32 v[12:13], v[118:119], v[118:119]
	v_pk_fma_f32 v[12:13], v[120:121], v[120:121], v[12:13]
	v_pk_fma_f32 v[12:13], v[122:123], v[122:123], v[12:13]
	v_pk_fma_f32 v[12:13], v[124:125], v[124:125], v[12:13]
	v_pk_fma_f32 v[12:13], v[134:135], v[134:135], v[12:13]
	v_pk_fma_f32 v[12:13], v[136:137], v[136:137], v[12:13]
	v_pk_fma_f32 v[12:13], v[138:139], v[138:139], v[12:13]
	v_pk_fma_f32 v[12:13], v[140:141], v[140:141], v[12:13]
	v_add_f32_e32 v5, v12, v13
	s_nop 1
	v_add_f32_dpp v5, v5, v5 quad_perm:[1,0,3,2] row_mask:0xf bank_mask:0xf
	s_nop 1
	v_add_f32_dpp v5, v5, v5 quad_perm:[2,3,0,1] row_mask:0xf bank_mask:0xf
	s_nop 1
	v_add_f32_dpp v5, v5, v5 row_half_mirror row_mask:0xf bank_mask:0xf
	s_nop 1
	v_add_f32_dpp v5, v5, v5 row_mirror row_mask:0xf bank_mask:0xf
	s_nop 1
	v_add_f32_dpp v5, v5, v5 row_bcast:15 row_mask:0xa bank_mask:0xf
	s_nop 1
	v_add_f32_dpp v5, v5, v5 row_bcast:31 row_mask:0xc bank_mask:0xf
	s_nop 1
	v_readlane_b32 s32, v5, 63
	s_nop 1
	v_mov_b32_e32 v6, s32
	v_fmamk_f32 v6, v6, 0x3a800000, v146
	v_rsq_f32_e32 v6, v6
	s_nop 0
	v_mul_f32_e32 v8, 0.5, v6
	v_pk_mul_f32 v[14:15], v[118:119], v[8:9] op_sel_hi:[1,0]
	v_pk_mul_f32 v[14:15], v[38:39], v[14:15]
	v_pk_fma_f32 v[102:103], v[22:23], v[14:15], v[102:103]
	v_pk_mul_f32 v[14:15], v[120:121], v[8:9] op_sel_hi:[1,0]
	v_pk_mul_f32 v[14:15], v[40:41], v[14:15]
	v_pk_fma_f32 v[104:105], v[24:25], v[14:15], v[104:105]
	v_pk_mul_f32 v[14:15], v[122:123], v[8:9] op_sel_hi:[1,0]
	v_pk_mul_f32 v[14:15], v[42:43], v[14:15]
	v_pk_fma_f32 v[106:107], v[26:27], v[14:15], v[106:107]
	v_pk_mul_f32 v[14:15], v[124:125], v[8:9] op_sel_hi:[1,0]
	v_pk_mul_f32 v[14:15], v[44:45], v[14:15]
	v_pk_fma_f32 v[108:109], v[28:29], v[14:15], v[108:109]
	v_pk_mul_f32 v[14:15], v[134:135], v[8:9] op_sel_hi:[1,0]
	v_pk_mul_f32 v[14:15], v[46:47], v[14:15]
	v_pk_fma_f32 v[110:111], v[30:31], v[14:15], v[110:111]
	v_pk_mul_f32 v[14:15], v[136:137], v[8:9] op_sel_hi:[1,0]
	v_pk_mul_f32 v[14:15], v[48:49], v[14:15]
	v_pk_fma_f32 v[112:113], v[32:33], v[14:15], v[112:113]
	v_pk_mul_f32 v[14:15], v[138:139], v[8:9] op_sel_hi:[1,0]
	v_pk_mul_f32 v[14:15], v[50:51], v[14:15]
	v_pk_fma_f32 v[114:115], v[34:35], v[14:15], v[114:115]
	v_pk_mul_f32 v[14:15], v[140:141], v[8:9] op_sel_hi:[1,0]
	v_pk_mul_f32 v[14:15], v[52:53], v[14:15]
	v_pk_fma_f32 v[116:117], v[36:37], v[14:15], v[116:117]
	v_pk_mul_f32 v[12:13], v[102:103], v[102:103]
	v_pk_fma_f32 v[12:13], v[104:105], v[104:105], v[12:13]
	v_pk_fma_f32 v[12:13], v[106:107], v[106:107], v[12:13]
	v_pk_fma_f32 v[12:13], v[108:109], v[108:109], v[12:13]
	v_pk_fma_f32 v[12:13], v[110:111], v[110:111], v[12:13]
	v_pk_fma_f32 v[12:13], v[112:113], v[112:113], v[12:13]
	v_pk_fma_f32 v[12:13], v[114:115], v[114:115], v[12:13]
	v_pk_fma_f32 v[12:13], v[116:117], v[116:117], v[12:13]
	v_add_f32_e32 v5, v12, v13
	s_nop 1
	v_add_f32_dpp v5, v5, v5 quad_perm:[1,0,3,2] row_mask:0xf bank_mask:0xf
	s_nop 1
	v_add_f32_dpp v5, v5, v5 quad_perm:[2,3,0,1] row_mask:0xf bank_mask:0xf
	s_nop 1
	v_add_f32_dpp v5, v5, v5 row_half_mirror row_mask:0xf bank_mask:0xf
	s_nop 1
	v_add_f32_dpp v5, v5, v5 row_mirror row_mask:0xf bank_mask:0xf
	s_nop 1
	v_add_f32_dpp v5, v5, v5 row_bcast:15 row_mask:0xa bank_mask:0xf
	s_nop 1
	v_add_f32_dpp v5, v5, v5 row_bcast:31 row_mask:0xc bank_mask:0xf
	s_nop 1
	v_readlane_b32 s32, v5, 63
	s_nop 1
	v_mov_b32_e32 v6, s32
	v_fmamk_f32 v6, v6, 0x3a800000, v146
	v_rsq_f32_e32 v6, v6
	s_nop 0
	v_mov_b32_e32 v10, v6
	v_pk_mul_f32 v[14:15], v[102:103], v[10:11] op_sel_hi:[1,0]
	v_pk_mul_f32 v[14:15], v[86:87], v[14:15]
	v_pk_fma_f32 v[16:17], v[70:71], v[14:15], v[54:55]
	v_pk_mul_f32 v[14:15], v[104:105], v[10:11] op_sel_hi:[1,0]
	v_pk_mul_f32 v[14:15], v[88:89], v[14:15]
	v_pk_fma_f32 v[18:19], v[72:73], v[14:15], v[56:57]
	v_cvt_pk_bf16_f32 v118, v16, v17
	v_cvt_pk_bf16_f32 v119, v18, v19
	v_pk_mul_f32 v[14:15], v[106:107], v[10:11] op_sel_hi:[1,0]
	v_pk_mul_f32 v[14:15], v[90:91], v[14:15]
	v_pk_fma_f32 v[16:17], v[74:75], v[14:15], v[58:59]
	v_pk_mul_f32 v[14:15], v[108:109], v[10:11] op_sel_hi:[1,0]
	v_pk_mul_f32 v[14:15], v[92:93], v[14:15]
	v_pk_fma_f32 v[18:19], v[76:77], v[14:15], v[60:61]
	v_cvt_pk_bf16_f32 v122, v16, v17
	v_cvt_pk_bf16_f32 v123, v18, v19
	v_pk_mul_f32 v[14:15], v[110:111], v[10:11] op_sel_hi:[1,0]
	v_pk_mul_f32 v[14:15], v[94:95], v[14:15]
	v_pk_fma_f32 v[16:17], v[78:79], v[14:15], v[62:63]
	v_pk_mul_f32 v[14:15], v[112:113], v[10:11] op_sel_hi:[1,0]
	v_pk_mul_f32 v[14:15], v[96:97], v[14:15]
	v_pk_fma_f32 v[18:19], v[80:81], v[14:15], v[64:65]
	v_cvt_pk_bf16_f32 v134, v16, v17
	v_cvt_pk_bf16_f32 v135, v18, v19
	v_pk_mul_f32 v[14:15], v[114:115], v[10:11] op_sel_hi:[1,0]
	v_pk_mul_f32 v[14:15], v[98:99], v[14:15]
	v_pk_fma_f32 v[16:17], v[82:83], v[14:15], v[66:67]
	v_pk_mul_f32 v[14:15], v[116:117], v[10:11] op_sel_hi:[1,0]
	v_pk_mul_f32 v[14:15], v[100:101], v[14:15]
	v_pk_fma_f32 v[18:19], v[84:85], v[14:15], v[68:69]
	v_cvt_pk_bf16_f32 v138, v16, v17
	v_cvt_pk_bf16_f32 v139, v18, v19
	global_store_dwordx4 v0, v[102:105], s[46:47] offset:0 sc1
	global_store_dwordx4 v0, v[106:109], s[46:47] offset:1024 sc1
	global_store_dwordx4 v0, v[110:113], s[46:47] offset:2048 sc1
	global_store_dwordx4 v0, v[114:117], s[46:47] offset:3072 sc1
	global_store_dwordx2 v1, v[118:119], s[62:63] offset:0 sc1
	global_store_dwordx2 v1, v[122:123], s[62:63] offset:512 sc1
	global_store_dwordx2 v1, v[134:135], s[62:63] offset:1024 sc1
	global_store_dwordx2 v1, v[138:139], s[62:63] offset:1536 sc1
	s_add_u32 s46, s46, 0x1000
	s_addc_u32 s47, s47, 0
	s_add_u32 s62, s62, 0x800
	s_addc_u32 s63, s63, 0
	s_branch .Lnorm0_done
.Lnorm0_first:
	v_readlane_b32 s2, v255, 0
	v_readfirstlane_b32 s7, v147
	s_load_dwordx2 s[4:5], s[0:1], 0x90
	s_load_dwordx2 s[12:13], s[0:1], 0x98
	s_load_dwordx2 s[14:15], s[0:1], 0x40
	s_load_dwordx2 s[58:59], s[0:1], 0x0
	s_load_dwordx2 s[60:61], s[0:1], 0x8
	v_and_b32_e32 v0, 63, v147
	v_lshlrev_b32_e32 v1, 3, v0
	v_lshlrev_b32_e32 v0, 4, v0
	s_lshr_b32 s7, s7, 6
	s_lshl_b32 s2, s2, 3
	s_add_u32 s2, s2, s7
	s_lshl_b32 s24, s2, 2
	s_sub_u32 s27, s24, 0x1000
	s_lshr_b32 s27, s27, 10
	s_add_u32 s27, s27, 1
	s_cmp_lt_u32 s24, 0x1000
	s_cselect_b32 s30, 0, s27
	v_mov_b32_e32 v3, v0
	v_add_u32_e32 v4, 0x1000, v0
	s_waitcnt lgkmcnt(0)
	s_lshl_b32 s27, s24, 11
	s_add_u32 s62, s12, s27
	s_addc_u32 s63, s13, 0
	s_add_u32 s62, s62, 0x1000000
	s_addc_u32 s63, s63, 0
	s_lshl_b32 s27, s24, 12
	s_add_u32 s46, s4, s27
	s_addc_u32 s47, s5, 0
	s_sub_u32 s37, s27, 0x1000000
	s_cmp_lt_u32 s24, 0x1000
	s_cselect_b32 s4, s58, s60
	s_cselect_b32 s5, s59, s61
	s_cselect_b32 s27, s27, s37
	s_add_u32 s4, s4, s27
	s_addc_u32 s5, s5, 0
	s_mul_i32 s27, s70, 5
	s_add_u32 s27, s27, s30
	s_mul_i32 s27, s27, 0x9000
	s_add_u32 s27, s27, 0x100000
	s_add_u32 s88, s12, s27
	s_addc_u32 s89, s13, 0
	s_mul_i32 s27, s70, 0x3000
	s_add_u32 s14, s14, s27
	s_addc_u32 s15, s15, 0
	global_load_dwordx4 v[22:25], v3, s[88:89] offset:0
	global_load_dwordx4 v[38:41], v4, s[88:89] offset:0
	global_load_dwordx4 v[54:57], v0, s[14:15] offset:0
	global_load_dwordx4 v[26:29], v3, s[88:89] offset:1024
	global_load_dwordx4 v[42:45], v4, s[88:89] offset:1024
	global_load_dwordx4 v[58:61], v0, s[14:15] offset:1024
	global_load_dwordx4 v[30:33], v3, s[88:89] offset:2048
	global_load_dwordx4 v[46:49], v4, s[88:89] offset:2048
	global_load_dwordx4 v[62:65], v0, s[14:15] offset:2048
	global_load_dwordx4 v[34:37], v3, s[88:89] offset:3072
	global_load_dwordx4 v[50:53], v4, s[88:89] offset:3072
	global_load_dwordx4 v[66:69], v0, s[14:15] offset:3072
	global_load_dwordx4 v[70:73], v0, s[4:5] offset:0 nt
	global_load_dwordx4 v[74:77], v0, s[4:5] offset:1024 nt
	global_load_dwordx4 v[78:81], v0, s[4:5] offset:2048 nt
	global_load_dwordx4 v[82:85], v0, s[4:5] offset:3072 nt
	s_add_u32 s4, s4, 0x1000
	s_addc_u32 s5, s5, 0
	global_load_dwordx4 v[86:89], v0, s[4:5] offset:0 nt
	global_load_dwordx4 v[90:93], v0, s[4:5] offset:1024 nt
	global_load_dwordx4 v[94:97], v0, s[4:5] offset:2048 nt
	global_load_dwordx4 v[98:101], v0, s[4:5] offset:3072 nt
	s_add_u32 s4, s4, 0x1000
	s_addc_u32 s5, s5, 0
	global_load_dwordx4 v[102:105], v0, s[4:5] offset:0 nt
	global_load_dwordx4 v[106:109], v0, s[4:5] offset:1024 nt
	global_load_dwordx4 v[110:113], v0, s[4:5] offset:2048 nt
	global_load_dwordx4 v[114:117], v0, s[4:5] offset:3072 nt
	s_add_u32 s4, s4, 0x1000
	s_addc_u32 s5, s5, 0
	s_waitcnt vmcnt(8)
	v_pk_add_f32 v[38:39], v[38:39], 1.0 op_sel_hi:[1,0]
	v_pk_add_f32 v[40:41], v[40:41], 1.0 op_sel_hi:[1,0]
	v_pk_add_f32 v[42:43], v[42:43], 1.0 op_sel_hi:[1,0]
	v_pk_add_f32 v[44:45], v[44:45], 1.0 op_sel_hi:[1,0]
	v_pk_add_f32 v[46:47], v[46:47], 1.0 op_sel_hi:[1,0]
	v_pk_add_f32 v[48:49], v[48:49], 1.0 op_sel_hi:[1,0]
	v_pk_add_f32 v[50:51], v[50:51], 1.0 op_sel_hi:[1,0]
	v_pk_add_f32 v[52:53], v[52:53], 1.0 op_sel_hi:[1,0]
	v_pk_mul_f32 v[12:13], v[70:71], v[70:71]
	v_pk_fma_f32 v[12:13], v[72:73], v[72:73], v[12:13]
	v_pk_fma_f32 v[12:13], v[74:75], v[74:75], v[12:13]
	v_pk_fma_f32 v[12:13], v[76:77], v[76:77], v[12:13]
	v_pk_fma_f32 v[12:13], v[78:79], v[78:79], v[12:13]
	v_pk_fma_f32 v[12:13], v[80:81], v[80:81], v[12:13]
	v_pk_fma_f32 v[12:13], v[82:83], v[82:83], v[12:13]
	v_pk_fma_f32 v[12:13], v[84:85], v[84:85], v[12:13]
	v_add_f32_e32 v5, v12, v13
	s_nop 1
	v_add_f32_dpp v5, v5, v5 quad_perm:[1,0,3,2] row_mask:0xf bank_mask:0xf
	s_nop 1
	v_add_f32_dpp v5, v5, v5 quad_perm:[2,3,0,1] row_mask:0xf bank_mask:0xf
	s_nop 1
	v_add_f32_dpp v5, v5, v5 row_half_mirror row_mask:0xf bank_mask:0xf
	s_nop 1
	v_add_f32_dpp v5, v5, v5 row_mirror row_mask:0xf bank_mask:0xf
	s_nop 1
	v_add_f32_dpp v5, v5, v5 row_bcast:15 row_mask:0xa bank_mask:0xf
	s_nop 1
	v_add_f32_dpp v5, v5, v5 row_bcast:31 row_mask:0xc bank_mask:0xf
	s_nop 1
	v_readlane_b32 s32, v5, 63
	s_nop 1
	v_mov_b32_e32 v6, s32
	v_fmamk_f32 v6, v6, 0x3a800000, v146
	v_rsq_f32_e32 v6, v6
	s_nop 0
	v_mov_b32_e32 v10, v6
	v_pk_mul_f32 v[14:15], v[70:71], v[10:11] op_sel_hi:[1,0]
	v_pk_mul_f32 v[14:15], v[54:55], v[14:15]
	v_pk_fma_f32 v[16:17], v[38:39], v[14:15], v[22:23]
	v_pk_mul_f32 v[14:15], v[72:73], v[10:11] op_sel_hi:[1,0]
	v_pk_mul_f32 v[14:15], v[56:57], v[14:15]
	v_pk_fma_f32 v[18:19], v[40:41], v[14:15], v[24:25]
	v_cvt_pk_bf16_f32 v118, v16, v17
	v_cvt_pk_bf16_f32 v119, v18, v19
	v_pk_mul_f32 v[14:15], v[74:75], v[10:11] op_sel_hi:[1,0]
	v_pk_mul_f32 v[14:15], v[58:59], v[14:15]
	v_pk_fma_f32 v[16:17], v[42:43], v[14:15], v[26:27]
	v_pk_mul_f32 v[14:15], v[76:77], v[10:11] op_sel_hi:[1,0]
	v_pk_mul_f32 v[14:15], v[60:61], v[14:15]
	v_pk_fma_f32 v[18:19], v[44:45], v[14:15], v[28:29]
	v_cvt_pk_bf16_f32 v120, v16, v17
	v_cvt_pk_bf16_f32 v121, v18, v19
	v_pk_mul_f32 v[14:15], v[78:79], v[10:11] op_sel_hi:[1,0]
	v_pk_mul_f32 v[14:15], v[62:63], v[14:15]
	v_pk_fma_f32 v[16:17], v[46:47], v[14:15], v[30:31]
	v_pk_mul_f32 v[14:15], v[80:81], v[10:11] op_sel_hi:[1,0]
	v_pk_mul_f32 v[14:15], v[64:65], v[14:15]
	v_pk_fma_f32 v[18:19], v[48:49], v[14:15], v[32:33]
	v_cvt_pk_bf16_f32 v122, v16, v17
	v_cvt_pk_bf16_f32 v123, v18, v19
	v_pk_mul_f32 v[14:15], v[82:83], v[10:11] op_sel_hi:[1,0]
	v_pk_mul_f32 v[14:15], v[66:67], v[14:15]
	v_pk_fma_f32 v[16:17], v[50:51], v[14:15], v[34:35]
	v_pk_mul_f32 v[14:15], v[84:85], v[10:11] op_sel_hi:[1,0]
	v_pk_mul_f32 v[14:15], v[68:69], v[14:15]
	v_pk_fma_f32 v[18:19], v[52:53], v[14:15], v[36:37]
	v_cvt_pk_bf16_f32 v124, v16, v17
	v_cvt_pk_bf16_f32 v125, v18, v19
	global_store_dwordx4 v0, v[70:73], s[46:47] offset:0 sc1
	global_store_dwordx4 v0, v[74:77], s[46:47] offset:1024 sc1
	global_store_dwordx4 v0, v[78:81], s[46:47] offset:2048 sc1
	global_store_dwordx4 v0, v[82:85], s[46:47] offset:3072 sc1
	global_store_dwordx2 v1, v[118:119], s[62:63] offset:0 sc1
	global_store_dwordx2 v1, v[120:121], s[62:63] offset:512 sc1
	global_store_dwordx2 v1, v[122:123], s[62:63] offset:1024 sc1
	global_store_dwordx2 v1, v[124:125], s[62:63] offset:1536 sc1
	s_add_u32 s46, s46, 0x1000
	s_addc_u32 s47, s47, 0
	s_add_u32 s62, s62, 0x800
	s_addc_u32 s63, s63, 0
	s_nop 1
	global_load_dwordx4 v[70:73], v0, s[4:5] offset:0 nt
	global_load_dwordx4 v[74:77], v0, s[4:5] offset:1024 nt
	global_load_dwordx4 v[78:81], v0, s[4:5] offset:2048 nt
	global_load_dwordx4 v[82:85], v0, s[4:5] offset:3072 nt
	s_add_u32 s4, s4, 0x1000
	s_addc_u32 s5, s5, 0
	s_waitcnt vmcnt(16)
	v_pk_mul_f32 v[12:13], v[86:87], v[86:87]
	v_pk_fma_f32 v[12:13], v[88:89], v[88:89], v[12:13]
	v_pk_fma_f32 v[12:13], v[90:91], v[90:91], v[12:13]
	v_pk_fma_f32 v[12:13], v[92:93], v[92:93], v[12:13]
	v_pk_fma_f32 v[12:13], v[94:95], v[94:95], v[12:13]
	v_pk_fma_f32 v[12:13], v[96:97], v[96:97], v[12:13]
	v_pk_fma_f32 v[12:13], v[98:99], v[98:99], v[12:13]
	v_pk_fma_f32 v[12:13], v[100:101], v[100:101], v[12:13]
	v_add_f32_e32 v5, v12, v13
	s_nop 1
	v_add_f32_dpp v5, v5, v5 quad_perm:[1,0,3,2] row_mask:0xf bank_mask:0xf
	s_nop 1
	v_add_f32_dpp v5, v5, v5 quad_perm:[2,3,0,1] row_mask:0xf bank_mask:0xf
	s_nop 1
	v_add_f32_dpp v5, v5, v5 row_half_mirror row_mask:0xf bank_mask:0xf
	s_nop 1
	v_add_f32_dpp v5, v5, v5 row_mirror row_mask:0xf bank_mask:0xf
	s_nop 1
	v_add_f32_dpp v5, v5, v5 row_bcast:15 row_mask:0xa bank_mask:0xf
	s_nop 1
	v_add_f32_dpp v5, v5, v5 row_bcast:31 row_mask:0xc bank_mask:0xf
	s_nop 1
	v_readlane_b32 s32, v5, 63
	s_nop 1
	v_mov_b32_e32 v6, s32
	v_fmamk_f32 v6, v6, 0x3a800000, v146
	v_rsq_f32_e32 v6, v6
	s_nop 0
	v_mov_b32_e32 v10, v6
	v_pk_mul_f32 v[14:15], v[86:87], v[10:11] op_sel_hi:[1,0]
	v_pk_mul_f32 v[14:15], v[54:55], v[14:15]
	v_pk_fma_f32 v[16:17], v[38:39], v[14:15], v[22:23]
	v_pk_mul_f32 v[14:15], v[88:89], v[10:11] op_sel_hi:[1,0]
	v_pk_mul_f32 v[14:15], v[56:57], v[14:15]
	v_pk_fma_f32 v[18:19], v[40:41], v[14:15], v[24:25]
	v_cvt_pk_bf16_f32 v118, v16, v17
	v_cvt_pk_bf16_f32 v119, v18, v19
	v_pk_mul_f32 v[14:15], v[90:91], v[10:11] op_sel_hi:[1,0]
	v_pk_mul_f32 v[14:15], v[58:59], v[14:15]
	v_pk_fma_f32 v[16:17], v[42:43], v[14:15], v[26:27]
	v_pk_mul_f32 v[14:15], v[92:93], v[10:11] op_sel_hi:[1,0]
	v_pk_mul_f32 v[14:15], v[60:61], v[14:15]
	v_pk_fma_f32 v[18:19], v[44:45], v[14:15], v[28:29]
	v_cvt_pk_bf16_f32 v120, v16, v17
	v_cvt_pk_bf16_f32 v121, v18, v19
	v_pk_mul_f32 v[14:15], v[94:95], v[10:11] op_sel_hi:[1,0]
	v_pk_mul_f32 v[14:15], v[62:63], v[14:15]
	v_pk_fma_f32 v[16:17], v[46:47], v[14:15], v[30:31]
	v_pk_mul_f32 v[14:15], v[96:97], v[10:11] op_sel_hi:[1,0]
	v_pk_mul_f32 v[14:15], v[64:65], v[14:15]
	v_pk_fma_f32 v[18:19], v[48:49], v[14:15], v[32:33]
	v_cvt_pk_bf16_f32 v122, v16, v17
	v_cvt_pk_bf16_f32 v123, v18, v19
	v_pk_mul_f32 v[14:15], v[98:99], v[10:11] op_sel_hi:[1,0]
	v_pk_mul_f32 v[14:15], v[66:67], v[14:15]
	v_pk_fma_f32 v[16:17], v[50:51], v[14:15], v[34:35]
	v_pk_mul_f32 v[14:15], v[100:101], v[10:11] op_sel_hi:[1,0]
	v_pk_mul_f32 v[14:15], v[68:69], v[14:15]
	v_pk_fma_f32 v[18:19], v[52:53], v[14:15], v[36:37]
	v_cvt_pk_bf16_f32 v124, v16, v17
	v_cvt_pk_bf16_f32 v125, v18, v19
	global_store_dwordx4 v0, v[86:89], s[46:47] offset:0 sc1
	global_store_dwordx4 v0, v[90:93], s[46:47] offset:1024 sc1
	global_store_dwordx4 v0, v[94:97], s[46:47] offset:2048 sc1
	global_store_dwordx4 v0, v[98:101], s[46:47] offset:3072 sc1
	global_store_dwordx2 v1, v[118:119], s[62:63] offset:0 sc1
	global_store_dwordx2 v1, v[120:121], s[62:63] offset:512 sc1
	global_store_dwordx2 v1, v[122:123], s[62:63] offset:1024 sc1
	global_store_dwordx2 v1, v[124:125], s[62:63] offset:1536 sc1
	s_add_u32 s46, s46, 0x1000
	s_addc_u32 s47, s47, 0
	s_add_u32 s62, s62, 0x800
	s_addc_u32 s63, s63, 0
	s_waitcnt vmcnt(20)
	v_pk_mul_f32 v[12:13], v[102:103], v[102:103]
	v_pk_fma_f32 v[12:13], v[104:105], v[104:105], v[12:13]
	v_pk_fma_f32 v[12:13], v[106:107], v[106:107], v[12:13]
	v_pk_fma_f32 v[12:13], v[108:109], v[108:109], v[12:13]
	v_pk_fma_f32 v[12:13], v[110:111], v[110:111], v[12:13]
	v_pk_fma_f32 v[12:13], v[112:113], v[112:113], v[12:13]
	v_pk_fma_f32 v[12:13], v[114:115], v[114:115], v[12:13]
	v_pk_fma_f32 v[12:13], v[116:117], v[116:117], v[12:13]
	v_add_f32_e32 v5, v12, v13
	s_nop 1
	v_add_f32_dpp v5, v5, v5 quad_perm:[1,0,3,2] row_mask:0xf bank_mask:0xf
	s_nop 1
	v_add_f32_dpp v5, v5, v5 quad_perm:[2,3,0,1] row_mask:0xf bank_mask:0xf
	s_nop 1
	v_add_f32_dpp v5, v5, v5 row_half_mirror row_mask:0xf bank_mask:0xf
	s_nop 1
	v_add_f32_dpp v5, v5, v5 row_mirror row_mask:0xf bank_mask:0xf
	s_nop 1
	v_add_f32_dpp v5, v5, v5 row_bcast:15 row_mask:0xa bank_mask:0xf
	s_nop 1
	v_add_f32_dpp v5, v5, v5 row_bcast:31 row_mask:0xc bank_mask:0xf
	s_nop 1
	v_readlane_b32 s32, v5, 63
	s_nop 1
	v_mov_b32_e32 v6, s32
	v_fmamk_f32 v6, v6, 0x3a800000, v146
	v_rsq_f32_e32 v6, v6
	s_nop 0
	v_mov_b32_e32 v10, v6
	v_pk_mul_f32 v[14:15], v[102:103], v[10:11] op_sel_hi:[1,0]
	v_pk_mul_f32 v[14:15], v[54:55], v[14:15]
	v_pk_fma_f32 v[16:17], v[38:39], v[14:15], v[22:23]
	v_pk_mul_f32 v[14:15], v[104:105], v[10:11] op_sel_hi:[1,0]
	v_pk_mul_f32 v[14:15], v[56:57], v[14:15]
	v_pk_fma_f32 v[18:19], v[40:41], v[14:15], v[24:25]
	v_cvt_pk_bf16_f32 v118, v16, v17
	v_cvt_pk_bf16_f32 v119, v18, v19
	v_pk_mul_f32 v[14:15], v[106:107], v[10:11] op_sel_hi:[1,0]
	v_pk_mul_f32 v[14:15], v[58:59], v[14:15]
	v_pk_fma_f32 v[16:17], v[42:43], v[14:15], v[26:27]
	v_pk_mul_f32 v[14:15], v[108:109], v[10:11] op_sel_hi:[1,0]
	v_pk_mul_f32 v[14:15], v[60:61], v[14:15]
	v_pk_fma_f32 v[18:19], v[44:45], v[14:15], v[28:29]
	v_cvt_pk_bf16_f32 v120, v16, v17
	v_cvt_pk_bf16_f32 v121, v18, v19
	v_pk_mul_f32 v[14:15], v[110:111], v[10:11] op_sel_hi:[1,0]
	v_pk_mul_f32 v[14:15], v[62:63], v[14:15]
	v_pk_fma_f32 v[16:17], v[46:47], v[14:15], v[30:31]
	v_pk_mul_f32 v[14:15], v[112:113], v[10:11] op_sel_hi:[1,0]
	v_pk_mul_f32 v[14:15], v[64:65], v[14:15]
	v_pk_fma_f32 v[18:19], v[48:49], v[14:15], v[32:33]
	v_cvt_pk_bf16_f32 v122, v16, v17
	v_cvt_pk_bf16_f32 v123, v18, v19
	v_pk_mul_f32 v[14:15], v[114:115], v[10:11] op_sel_hi:[1,0]
	v_pk_mul_f32 v[14:15], v[66:67], v[14:15]
	v_pk_fma_f32 v[16:17], v[50:51], v[14:15], v[34:35]
	v_pk_mul_f32 v[14:15], v[116:117], v[10:11] op_sel_hi:[1,0]
	v_pk_mul_f32 v[14:15], v[68:69], v[14:15]
	v_pk_fma_f32 v[18:19], v[52:53], v[14:15], v[36:37]
	v_cvt_pk_bf16_f32 v124, v16, v17
	v_cvt_pk_bf16_f32 v125, v18, v19
	global_store_dwordx4 v0, v[102:105], s[46:47] offset:0 sc1
	global_store_dwordx4 v0, v[106:109], s[46:47] offset:1024 sc1
	global_store_dwordx4 v0, v[110:113], s[46:47] offset:2048 sc1
	global_store_dwordx4 v0, v[114:117], s[46:47] offset:3072 sc1
	global_store_dwordx2 v1, v[118:119], s[62:63] offset:0 sc1
	global_store_dwordx2 v1, v[120:121], s[62:63] offset:512 sc1
	global_store_dwordx2 v1, v[122:123], s[62:63] offset:1024 sc1
	global_store_dwordx2 v1, v[124:125], s[62:63] offset:1536 sc1
	s_add_u32 s46, s46, 0x1000
	s_addc_u32 s47, s47, 0
	s_add_u32 s62, s62, 0x800
	s_addc_u32 s63, s63, 0
	s_waitcnt vmcnt(16)
	v_pk_mul_f32 v[12:13], v[70:71], v[70:71]
	v_pk_fma_f32 v[12:13], v[72:73], v[72:73], v[12:13]
	v_pk_fma_f32 v[12:13], v[74:75], v[74:75], v[12:13]
	v_pk_fma_f32 v[12:13], v[76:77], v[76:77], v[12:13]
	v_pk_fma_f32 v[12:13], v[78:79], v[78:79], v[12:13]
	v_pk_fma_f32 v[12:13], v[80:81], v[80:81], v[12:13]
	v_pk_fma_f32 v[12:13], v[82:83], v[82:83], v[12:13]
	v_pk_fma_f32 v[12:13], v[84:85], v[84:85], v[12:13]
	v_add_f32_e32 v5, v12, v13
	s_nop 1
	v_add_f32_dpp v5, v5, v5 quad_perm:[1,0,3,2] row_mask:0xf bank_mask:0xf
	s_nop 1
	v_add_f32_dpp v5, v5, v5 quad_perm:[2,3,0,1] row_mask:0xf bank_mask:0xf
	s_nop 1
	v_add_f32_dpp v5, v5, v5 row_half_mirror row_mask:0xf bank_mask:0xf
	s_nop 1
	v_add_f32_dpp v5, v5, v5 row_mirror row_mask:0xf bank_mask:0xf
	s_nop 1
	v_add_f32_dpp v5, v5, v5 row_bcast:15 row_mask:0xa bank_mask:0xf
	s_nop 1
	v_add_f32_dpp v5, v5, v5 row_bcast:31 row_mask:0xc bank_mask:0xf
	s_nop 1
	v_readlane_b32 s32, v5, 63
	s_nop 1
	v_mov_b32_e32 v6, s32
	v_fmamk_f32 v6, v6, 0x3a800000, v146
	v_rsq_f32_e32 v6, v6
	s_nop 0
	v_mov_b32_e32 v10, v6
	v_pk_mul_f32 v[14:15], v[70:71], v[10:11] op_sel_hi:[1,0]
	v_pk_mul_f32 v[14:15], v[54:55], v[14:15]
	v_pk_fma_f32 v[16:17], v[38:39], v[14:15], v[22:23]
	v_pk_mul_f32 v[14:15], v[72:73], v[10:11] op_sel_hi:[1,0]
	v_pk_mul_f32 v[14:15], v[56:57], v[14:15]
	v_pk_fma_f32 v[18:19], v[40:41], v[14:15], v[24:25]
	v_cvt_pk_bf16_f32 v118, v16, v17
	v_cvt_pk_bf16_f32 v119, v18, v19
	v_pk_mul_f32 v[14:15], v[74:75], v[10:11] op_sel_hi:[1,0]
	v_pk_mul_f32 v[14:15], v[58:59], v[14:15]
	v_pk_fma_f32 v[16:17], v[42:43], v[14:15], v[26:27]
	v_pk_mul_f32 v[14:15], v[76:77], v[10:11] op_sel_hi:[1,0]
	v_pk_mul_f32 v[14:15], v[60:61], v[14:15]
	v_pk_fma_f32 v[18:19], v[44:45], v[14:15], v[28:29]
	v_cvt_pk_bf16_f32 v120, v16, v17
	v_cvt_pk_bf16_f32 v121, v18, v19
	v_pk_mul_f32 v[14:15], v[78:79], v[10:11] op_sel_hi:[1,0]
	v_pk_mul_f32 v[14:15], v[62:63], v[14:15]
	v_pk_fma_f32 v[16:17], v[46:47], v[14:15], v[30:31]
	v_pk_mul_f32 v[14:15], v[80:81], v[10:11] op_sel_hi:[1,0]
	v_pk_mul_f32 v[14:15], v[64:65], v[14:15]
	v_pk_fma_f32 v[18:19], v[48:49], v[14:15], v[32:33]
	v_cvt_pk_bf16_f32 v122, v16, v17
	v_cvt_pk_bf16_f32 v123, v18, v19
	v_pk_mul_f32 v[14:15], v[82:83], v[10:11] op_sel_hi:[1,0]
	v_pk_mul_f32 v[14:15], v[66:67], v[14:15]
	v_pk_fma_f32 v[16:17], v[50:51], v[14:15], v[34:35]
	v_pk_mul_f32 v[14:15], v[84:85], v[10:11] op_sel_hi:[1,0]
	v_pk_mul_f32 v[14:15], v[68:69], v[14:15]
	v_pk_fma_f32 v[18:19], v[52:53], v[14:15], v[36:37]
	v_cvt_pk_bf16_f32 v124, v16, v17
	v_cvt_pk_bf16_f32 v125, v18, v19
	global_store_dwordx4 v0, v[70:73], s[46:47] offset:0 sc1
	global_store_dwordx4 v0, v[74:77], s[46:47] offset:1024 sc1
	global_store_dwordx4 v0, v[78:81], s[46:47] offset:2048 sc1
	global_store_dwordx4 v0, v[82:85], s[46:47] offset:3072 sc1
	global_store_dwordx2 v1, v[118:119], s[62:63] offset:0 sc1
	global_store_dwordx2 v1, v[120:121], s[62:63] offset:512 sc1
	global_store_dwordx2 v1, v[122:123], s[62:63] offset:1024 sc1
	global_store_dwordx2 v1, v[124:125], s[62:63] offset:1536 sc1
	s_add_u32 s46, s46, 0x1000
	s_addc_u32 s47, s47, 0
	s_add_u32 s62, s62, 0x800
	s_addc_u32 s63, s63, 0
.Lnorm0_done:
.LBB0_280:
	s_or_b64 exec, exec, s[16:17]
	s_mov_b64 s[8:9], s[0:1]
	s_waitcnt vmcnt(0)
	v_mov_b32_e32 v0, v147
	s_barrier
	s_nop 0
	v_readfirstlane_b32 vcc_lo, v0
	s_nop 1
	s_cmp_eq_u32 vcc_lo, 64
	s_cbranch_scc0 .Lxb_noinv_1
	buffer_inv sc1
	s_waitcnt vmcnt(0)

.LBB0_519:
	s_or_b64 exec, exec, s[4:5]
	s_mov_b64 s[4:5], -1
	v_writelane_b32 v255, s4, 19
	s_and_b64 vcc, exec, s[10:11]
	s_waitcnt lgkmcnt(0)
	v_writelane_b32 v255, s5, 20
	s_mov_b64 s[4:5], -1
	s_barrier
	s_cbranch_vccz .LBB0_335
	s_mov_b64 s[16:17], s[0:1]
	v_mov_b32_e32 v0, v147
	v_readlane_b32 s2, v255, 0
	s_nop 0
	v_ashrrev_i32_e32 v1, 6, v0
	v_lshl_add_u32 v16, s2, 3, v1
	s_movk_i32 s2, 0x2000
	v_cmp_gt_i32_e32 vcc, s2, v16
	s_and_saveexec_b64 s[8:9], vcc
	s_cbranch_execz .LBB0_523
	s_load_dwordx4 s[4:7], s[16:17], 0x90
	s_load_dwordx4 s[12:15], s[16:17], 0x40
	v_lshlrev_b32_e32 v1, 2, v0
	v_cmp_lt_i32_e32 vcc, v188, v183
	v_and_b32_e32 v2, 0xfc, v1
	s_mul_i32 s2, s70, 0x2d000
	v_cndmask_b32_e32 v1, v182, v188, vcc
	v_cmp_lt_i32_e32 vcc, v254, v183
	s_waitcnt lgkmcnt(0)
	s_add_u32 s18, s6, s2
	s_mul_hi_u32 s2, s70, 0x2d000
	v_lshlrev_b32_e32 v28, 2, v1
	v_cndmask_b32_e32 v1, v182, v254, vcc
	s_addc_u32 s19, s7, s2
	v_readlane_b32 s20, v255, 12
	v_lshlrev_b32_e32 v29, 2, v1
	v_xor_b32_e32 v1, 4, v182
	s_add_u32 s10, s18, 0x103000
	v_readlane_b32 s21, v255, 13
	v_cmp_lt_i32_e32 vcc, v1, v183
	s_addc_u32 s11, s19, 0
	s_lshl_b64 s[20:21], s[20:21], 2
	v_cndmask_b32_e32 v1, v182, v1, vcc
	s_add_u32 s12, s12, s20
	v_lshlrev_b32_e32 v144, 2, v2
	v_lshlrev_b32_e32 v30, 2, v1
	v_xor_b32_e32 v1, 8, v182
	s_addc_u32 s13, s13, s21
	v_lshl_add_u64 v[4:5], s[18:19], 0, v[144:145]
	s_mov_b64 s[18:19], 0x102000
	v_cmp_lt_i32_e32 vcc, v1, v183
	v_lshl_add_u64 v[18:19], v[4:5], 0, s[18:19]
	v_lshl_add_u64 v[4:5], s[12:13], 0, v[144:145]
	v_cndmask_b32_e32 v1, v182, v1, vcc
	v_cmp_lt_i32_e32 vcc, v187, v183
	v_ashrrev_i32_e32 v17, 31, v16
	v_lshl_add_u64 v[22:23], v[4:5], 0, s[94:95]
	v_lshlrev_b32_e32 v31, 2, v1
	v_cndmask_b32_e32 v1, v182, v187, vcc
	v_cmp_lt_i32_e32 vcc, v184, v183
	v_lshlrev_b64 v[4:5], 11, v[16:17]
	v_and_b32_e32 v3, 63, v0
	v_lshlrev_b32_e32 v32, 2, v1
	v_cndmask_b32_e32 v1, v182, v184, vcc
	v_lshl_or_b32 v4, v3, 3, v4
	v_lshlrev_b32_e32 v33, 2, v1
	v_lshl_add_u64 v[0:1], s[6:7], 0, v[4:5]
	s_mov_b64 s[6:7], 0x9800600
	s_add_u32 s14, s14, s20
	v_lshl_add_u64 v[24:25], v[0:1], 0, s[6:7]
	v_lshlrev_b64 v[0:1], 12, v[16:17]
	s_addc_u32 s15, s15, s21
	v_lshl_or_b32 v0, v3, 4, v0
	v_lshl_add_u64 v[20:21], s[14:15], 0, v[144:145]
	v_lshl_add_u64 v[26:27], s[4:5], 0, v[0:1]
	s_mov_b64 s[4:5], 0
	v_lshlrev_b32_e32 v144, 2, v2
	v_readlane_b32 s2, v255, 0
	v_readfirstlane_b32 s7, v147
	s_load_dwordx2 s[4:5], s[16:17], 0x90
	s_load_dwordx2 s[12:13], s[16:17], 0x98
	s_load_dwordx2 s[14:15], s[16:17], 0x40
	s_load_dwordx2 s[40:41], s[16:17], 0x48
	v_and_b32_e32 v0, 63, v147
	v_lshlrev_b32_e32 v1, 3, v0
	v_lshlrev_b32_e32 v0, 4, v0
	s_lshr_b32 s7, s7, 6
	s_lshl_b32 s2, s2, 3
	s_add_u32 s2, s2, s7
	s_lshl_b32 s24, s2, 2
	s_sub_u32 s27, s24, 0x1000
	s_lshr_b32 s27, s27, 10
	s_add_u32 s27, s27, 1
	s_cmp_lt_u32 s24, 0x1000
	s_cselect_b32 s30, 0, s27
	v_add_u32_e32 v2, 0x2000, v0
	v_add_u32_e32 v3, 0x3000, v0
	v_add_u32_e32 v4, 0x4000, v0
	s_waitcnt lgkmcnt(0)
	s_lshl_b32 s27, s24, 11
	s_add_u32 s62, s12, s27
	s_addc_u32 s63, s13, 0
	s_add_u32 s58, s62, 0x8800000
	s_addc_u32 s59, s63, 0
	s_add_u32 s60, s58, 0x1000000
	s_addc_u32 s61, s59, 0
	s_add_u32 s62, s62, 0x1000000
	s_addc_u32 s63, s63, 0
	s_lshl_b32 s27, s24, 12
	s_add_u32 s46, s4, s27
	s_addc_u32 s47, s5, 0
	s_mov_b64 s[4:5], s[46:47]
	s_mul_i32 s27, s70, 5
	s_add_u32 s27, s27, s30
	s_mul_i32 s27, s27, 0x9000
	s_add_u32 s27, s27, 0x100000
	s_add_u32 s88, s12, s27
	s_addc_u32 s89, s13, 0
	s_mov_b64 s[100:101], s[88:89]
	s_mul_i32 s27, s70, 0x3000
	s_add_u32 s40, s40, s27
	s_addc_u32 s41, s41, 0
	s_mul_i32 s27, s70, 0x3000
	s_add_u32 s27, s27, 0x1000
	s_add_u32 s14, s14, s27
	s_addc_u32 s15, s15, 0
	global_load_dwordx4 v[22:25], v2, s[100:101] offset:0
	global_load_dwordx4 v[38:41], v0, s[40:41] offset:0
	global_load_dwordx4 v[54:57], v3, s[88:89] offset:0
	global_load_dwordx4 v[70:73], v4, s[88:89] offset:0
	global_load_dwordx4 v[86:89], v0, s[14:15] offset:0
	global_load_dwordx4 v[26:29], v2, s[100:101] offset:1024
	global_load_dwordx4 v[42:45], v0, s[40:41] offset:1024
	global_load_dwordx4 v[58:61], v3, s[88:89] offset:1024
	global_load_dwordx4 v[74:77], v4, s[88:89] offset:1024
	global_load_dwordx4 v[90:93], v0, s[14:15] offset:1024
	global_load_dwordx4 v[30:33], v2, s[100:101] offset:2048
	global_load_dwordx4 v[46:49], v0, s[40:41] offset:2048
	global_load_dwordx4 v[62:65], v3, s[88:89] offset:2048
	global_load_dwordx4 v[78:81], v4, s[88:89] offset:2048
	global_load_dwordx4 v[94:97], v0, s[14:15] offset:2048
	global_load_dwordx4 v[34:37], v2, s[100:101] offset:3072
	global_load_dwordx4 v[50:53], v0, s[40:41] offset:3072
	global_load_dwordx4 v[66:69], v3, s[88:89] offset:3072
	global_load_dwordx4 v[82:85], v4, s[88:89] offset:3072
	global_load_dwordx4 v[98:101], v0, s[14:15] offset:3072
	global_load_dwordx4 v[102:105], v0, s[4:5] offset:0
	global_load_dwordx4 v[106:109], v0, s[4:5] offset:1024
	global_load_dwordx4 v[110:113], v0, s[4:5] offset:2048
	global_load_dwordx4 v[114:117], v0, s[4:5] offset:3072
	global_load_dwordx2 v[118:119], v1, s[58:59] offset:0
	global_load_dwordx2 v[122:123], v1, s[58:59] offset:512
	global_load_dwordx2 v[134:135], v1, s[58:59] offset:1024
	global_load_dwordx2 v[138:139], v1, s[58:59] offset:1536
	global_load_dwordx2 v[120:121], v1, s[60:61] offset:0
	global_load_dwordx2 v[124:125], v1, s[60:61] offset:512
	global_load_dwordx2 v[136:137], v1, s[60:61] offset:1024
	global_load_dwordx2 v[140:141], v1, s[60:61] offset:1536
	s_add_u32 s4, s4, 0x1000
	s_addc_u32 s5, s5, 0
	s_add_u32 s58, s58, 0x800
	s_addc_u32 s59, s59, 0
	s_add_u32 s60, s60, 0x800
	s_addc_u32 s61, s61, 0
	global_load_dwordx4 v[154:157], v0, s[4:5] offset:0
	global_load_dwordx4 v[158:161], v0, s[4:5] offset:1024
	global_load_dwordx4 v[162:165], v0, s[4:5] offset:2048
	global_load_dwordx4 v[168:171], v0, s[4:5] offset:3072
	global_load_dwordx2 v[172:173], v1, s[58:59] offset:0
	global_load_dwordx2 v[176:177], v1, s[58:59] offset:512
	global_load_dwordx2 v[204:205], v1, s[58:59] offset:1024
	global_load_dwordx2 v[214:215], v1, s[58:59] offset:1536
	global_load_dwordx2 v[174:175], v1, s[60:61] offset:0
	global_load_dwordx2 v[178:179], v1, s[60:61] offset:512
	global_load_dwordx2 v[206:207], v1, s[60:61] offset:1024
	global_load_dwordx2 v[216:217], v1, s[60:61] offset:1536
	s_add_u32 s4, s4, 0x1000
	s_addc_u32 s5, s5, 0
	s_add_u32 s58, s58, 0x800
	s_addc_u32 s59, s59, 0
	s_add_u32 s60, s60, 0x800
	s_addc_u32 s61, s61, 0
	global_load_dwordx4 v[218:221], v0, s[4:5] offset:0
	global_load_dwordx4 v[222:225], v0, s[4:5] offset:1024
	global_load_dwordx4 v[226:229], v0, s[4:5] offset:2048
	global_load_dwordx4 v[230:233], v0, s[4:5] offset:3072
	global_load_dwordx2 v[234:235], v1, s[58:59] offset:0
	global_load_dwordx2 v[238:239], v1, s[58:59] offset:512
	global_load_dwordx2 v[242:243], v1, s[58:59] offset:1024
	global_load_dwordx2 v[246:247], v1, s[58:59] offset:1536
	global_load_dwordx2 v[236:237], v1, s[60:61] offset:0
	global_load_dwordx2 v[240:241], v1, s[60:61] offset:512
	global_load_dwordx2 v[244:245], v1, s[60:61] offset:1024
	global_load_dwordx2 v[248:249], v1, s[60:61] offset:1536
	s_add_u32 s4, s4, 0x1000
	s_addc_u32 s5, s5, 0
	s_add_u32 s58, s58, 0x800
	s_addc_u32 s59, s59, 0
	s_add_u32 s60, s60, 0x800
	s_addc_u32 s61, s61, 0
	s_waitcnt vmcnt(24)
	v_pk_add_f32 v[70:71], v[70:71], 1.0 op_sel_hi:[1,0]
	v_pk_add_f32 v[72:73], v[72:73], 1.0 op_sel_hi:[1,0]
	v_pk_add_f32 v[74:75], v[74:75], 1.0 op_sel_hi:[1,0]
	v_pk_add_f32 v[76:77], v[76:77], 1.0 op_sel_hi:[1,0]
	v_pk_add_f32 v[78:79], v[78:79], 1.0 op_sel_hi:[1,0]
	v_pk_add_f32 v[80:81], v[80:81], 1.0 op_sel_hi:[1,0]
	v_pk_add_f32 v[82:83], v[82:83], 1.0 op_sel_hi:[1,0]
	v_pk_add_f32 v[84:85], v[84:85], 1.0 op_sel_hi:[1,0]
	v_lshlrev_b32_e32 v14, 16, v118
	v_and_b32_e32 v15, 0xffff0000, v118
	v_lshlrev_b32_e32 v16, 16, v120
	v_and_b32_e32 v17, 0xffff0000, v120
	v_lshlrev_b32_e32 v18, 16, v119
	v_and_b32_e32 v19, 0xffff0000, v119
	v_lshlrev_b32_e32 v20, 16, v121
	v_and_b32_e32 v21, 0xffff0000, v121
	v_pk_add_f32 v[118:119], v[14:15], v[16:17]
	v_pk_add_f32 v[120:121], v[18:19], v[20:21]
	v_lshlrev_b32_e32 v14, 16, v122
	v_and_b32_e32 v15, 0xffff0000, v122
	v_lshlrev_b32_e32 v16, 16, v124
	v_and_b32_e32 v17, 0xffff0000, v124
	v_lshlrev_b32_e32 v18, 16, v123
	v_and_b32_e32 v19, 0xffff0000, v123
	v_lshlrev_b32_e32 v20, 16, v125
	v_and_b32_e32 v21, 0xffff0000, v125
	v_pk_add_f32 v[122:123], v[14:15], v[16:17]
	v_pk_add_f32 v[124:125], v[18:19], v[20:21]
	v_lshlrev_b32_e32 v14, 16, v134
	v_and_b32_e32 v15, 0xffff0000, v134
	v_lshlrev_b32_e32 v16, 16, v136
	v_and_b32_e32 v17, 0xffff0000, v136
	v_lshlrev_b32_e32 v18, 16, v135
	v_and_b32_e32 v19, 0xffff0000, v135
	v_lshlrev_b32_e32 v20, 16, v137
	v_and_b32_e32 v21, 0xffff0000, v137
	v_pk_add_f32 v[134:135], v[14:15], v[16:17]
	v_pk_add_f32 v[136:137], v[18:19], v[20:21]
	v_lshlrev_b32_e32 v14, 16, v138
	v_and_b32_e32 v15, 0xffff0000, v138
	v_lshlrev_b32_e32 v16, 16, v140
	v_and_b32_e32 v17, 0xffff0000, v140
	v_lshlrev_b32_e32 v18, 16, v139
	v_and_b32_e32 v19, 0xffff0000, v139
	v_lshlrev_b32_e32 v20, 16, v141
	v_and_b32_e32 v21, 0xffff0000, v141
	v_pk_add_f32 v[138:139], v[14:15], v[16:17]
	v_pk_add_f32 v[140:141], v[18:19], v[20:21]
	v_pk_mul_f32 v[12:13], v[118:119], v[118:119]
	v_pk_fma_f32 v[12:13], v[120:121], v[120:121], v[12:13]
	v_pk_fma_f32 v[12:13], v[122:123], v[122:123], v[12:13]
	v_pk_fma_f32 v[12:13], v[124:125], v[124:125], v[12:13]
	v_pk_fma_f32 v[12:13], v[134:135], v[134:135], v[12:13]
	v_pk_fma_f32 v[12:13], v[136:137], v[136:137], v[12:13]
	v_pk_fma_f32 v[12:13], v[138:139], v[138:139], v[12:13]
	v_pk_fma_f32 v[12:13], v[140:141], v[140:141], v[12:13]
	v_add_f32_e32 v5, v12, v13
	s_nop 1
	v_add_f32_dpp v5, v5, v5 quad_perm:[1,0,3,2] row_mask:0xf bank_mask:0xf
	s_nop 1
	v_add_f32_dpp v5, v5, v5 quad_perm:[2,3,0,1] row_mask:0xf bank_mask:0xf
	s_nop 1
	v_add_f32_dpp v5, v5, v5 row_half_mirror row_mask:0xf bank_mask:0xf
	s_nop 1
	v_add_f32_dpp v5, v5, v5 row_mirror row_mask:0xf bank_mask:0xf
	s_nop 1
	v_add_f32_dpp v5, v5, v5 row_bcast:15 row_mask:0xa bank_mask:0xf
	s_nop 1
	v_add_f32_dpp v5, v5, v5 row_bcast:31 row_mask:0xc bank_mask:0xf
	s_nop 1
	v_readlane_b32 s32, v5, 63
	s_nop 1
	v_mov_b32_e32 v6, s32
	v_fmamk_f32 v6, v6, 0x3a800000, v146
	v_rsq_f32_e32 v6, v6
	s_nop 0
	v_mul_f32_e32 v8, 0.5, v6
	v_pk_mul_f32 v[14:15], v[118:119], v[8:9] op_sel_hi:[1,0]
	v_pk_mul_f32 v[14:15], v[38:39], v[14:15]
	v_pk_fma_f32 v[102:103], v[22:23], v[14:15], v[102:103]
	v_pk_mul_f32 v[14:15], v[120:121], v[8:9] op_sel_hi:[1,0]
	v_pk_mul_f32 v[14:15], v[40:41], v[14:15]
	v_pk_fma_f32 v[104:105], v[24:25], v[14:15], v[104:105]
	v_pk_mul_f32 v[14:15], v[122:123], v[8:9] op_sel_hi:[1,0]
	v_pk_mul_f32 v[14:15], v[42:43], v[14:15]
	v_pk_fma_f32 v[106:107], v[26:27], v[14:15], v[106:107]
	v_pk_mul_f32 v[14:15], v[124:125], v[8:9] op_sel_hi:[1,0]
	v_pk_mul_f32 v[14:15], v[44:45], v[14:15]
	v_pk_fma_f32 v[108:109], v[28:29], v[14:15], v[108:109]
	v_pk_mul_f32 v[14:15], v[134:135], v[8:9] op_sel_hi:[1,0]
	v_pk_mul_f32 v[14:15], v[46:47], v[14:15]
	v_pk_fma_f32 v[110:111], v[30:31], v[14:15], v[110:111]
	v_pk_mul_f32 v[14:15], v[136:137], v[8:9] op_sel_hi:[1,0]
	v_pk_mul_f32 v[14:15], v[48:49], v[14:15]
	v_pk_fma_f32 v[112:113], v[32:33], v[14:15], v[112:113]
	v_pk_mul_f32 v[14:15], v[138:139], v[8:9] op_sel_hi:[1,0]
	v_pk_mul_f32 v[14:15], v[50:51], v[14:15]
	v_pk_fma_f32 v[114:115], v[34:35], v[14:15], v[114:115]
	v_pk_mul_f32 v[14:15], v[140:141], v[8:9] op_sel_hi:[1,0]
	v_pk_mul_f32 v[14:15], v[52:53], v[14:15]
	v_pk_fma_f32 v[116:117], v[36:37], v[14:15], v[116:117]
	v_pk_mul_f32 v[12:13], v[102:103], v[102:103]
	v_pk_fma_f32 v[12:13], v[104:105], v[104:105], v[12:13]
	v_pk_fma_f32 v[12:13], v[106:107], v[106:107], v[12:13]
	v_pk_fma_f32 v[12:13], v[108:109], v[108:109], v[12:13]
	v_pk_fma_f32 v[12:13], v[110:111], v[110:111], v[12:13]
	v_pk_fma_f32 v[12:13], v[112:113], v[112:113], v[12:13]
	v_pk_fma_f32 v[12:13], v[114:115], v[114:115], v[12:13]
	v_pk_fma_f32 v[12:13], v[116:117], v[116:117], v[12:13]
	v_add_f32_e32 v5, v12, v13
	s_nop 1
	v_add_f32_dpp v5, v5, v5 quad_perm:[1,0,3,2] row_mask:0xf bank_mask:0xf
	s_nop 1
	v_add_f32_dpp v5, v5, v5 quad_perm:[2,3,0,1] row_mask:0xf bank_mask:0xf
	s_nop 1
	v_add_f32_dpp v5, v5, v5 row_half_mirror row_mask:0xf bank_mask:0xf
	s_nop 1
	v_add_f32_dpp v5, v5, v5 row_mirror row_mask:0xf bank_mask:0xf
	s_nop 1
	v_add_f32_dpp v5, v5, v5 row_bcast:15 row_mask:0xa bank_mask:0xf
	s_nop 1
	v_add_f32_dpp v5, v5, v5 row_bcast:31 row_mask:0xc bank_mask:0xf
	s_nop 1
	v_readlane_b32 s32, v5, 63
	s_nop 1
	v_mov_b32_e32 v6, s32
	v_fmamk_f32 v6, v6, 0x3a800000, v146
	v_rsq_f32_e32 v6, v6
	s_nop 0
	v_mov_b32_e32 v10, v6
	v_pk_mul_f32 v[14:15], v[102:103], v[10:11] op_sel_hi:[1,0]
	v_pk_mul_f32 v[14:15], v[86:87], v[14:15]
	v_pk_fma_f32 v[16:17], v[70:71], v[14:15], v[54:55]
	v_pk_mul_f32 v[14:15], v[104:105], v[10:11] op_sel_hi:[1,0]
	v_pk_mul_f32 v[14:15], v[88:89], v[14:15]
	v_pk_fma_f32 v[18:19], v[72:73], v[14:15], v[56:57]
	v_cvt_pk_bf16_f32 v118, v16, v17
	v_cvt_pk_bf16_f32 v119, v18, v19
	v_pk_mul_f32 v[14:15], v[106:107], v[10:11] op_sel_hi:[1,0]
	v_pk_mul_f32 v[14:15], v[90:91], v[14:15]
	v_pk_fma_f32 v[16:17], v[74:75], v[14:15], v[58:59]
	v_pk_mul_f32 v[14:15], v[108:109], v[10:11] op_sel_hi:[1,0]
	v_pk_mul_f32 v[14:15], v[92:93], v[14:15]
	v_pk_fma_f32 v[18:19], v[76:77], v[14:15], v[60:61]
	v_cvt_pk_bf16_f32 v122, v16, v17
	v_cvt_pk_bf16_f32 v123, v18, v19
	v_pk_mul_f32 v[14:15], v[110:111], v[10:11] op_sel_hi:[1,0]
	v_pk_mul_f32 v[14:15], v[94:95], v[14:15]
	v_pk_fma_f32 v[16:17], v[78:79], v[14:15], v[62:63]
	v_pk_mul_f32 v[14:15], v[112:113], v[10:11] op_sel_hi:[1,0]
	v_pk_mul_f32 v[14:15], v[96:97], v[14:15]
	v_pk_fma_f32 v[18:19], v[80:81], v[14:15], v[64:65]
	v_cvt_pk_bf16_f32 v134, v16, v17
	v_cvt_pk_bf16_f32 v135, v18, v19
	v_pk_mul_f32 v[14:15], v[114:115], v[10:11] op_sel_hi:[1,0]
	v_pk_mul_f32 v[14:15], v[98:99], v[14:15]
	v_pk_fma_f32 v[16:17], v[82:83], v[14:15], v[66:67]
	v_pk_mul_f32 v[14:15], v[116:117], v[10:11] op_sel_hi:[1,0]
	v_pk_mul_f32 v[14:15], v[100:101], v[14:15]
	v_pk_fma_f32 v[18:19], v[84:85], v[14:15], v[68:69]
	v_cvt_pk_bf16_f32 v138, v16, v17
	v_cvt_pk_bf16_f32 v139, v18, v19
	global_store_dwordx4 v0, v[102:105], s[46:47] offset:0 sc1
	global_store_dwordx4 v0, v[106:109], s[46:47] offset:1024 sc1
	global_store_dwordx4 v0, v[110:113], s[46:47] offset:2048 sc1
	global_store_dwordx4 v0, v[114:117], s[46:47] offset:3072 sc1
	global_store_dwordx2 v1, v[118:119], s[62:63] offset:0 sc1
	global_store_dwordx2 v1, v[122:123], s[62:63] offset:512 sc1
	global_store_dwordx2 v1, v[134:135], s[62:63] offset:1024 sc1
	global_store_dwordx2 v1, v[138:139], s[62:63] offset:1536 sc1
	s_add_u32 s46, s46, 0x1000
	s_addc_u32 s47, s47, 0
	s_add_u32 s62, s62, 0x800
	s_addc_u32 s63, s63, 0
	s_nop 1
	global_load_dwordx4 v[102:105], v0, s[4:5] offset:0
	global_load_dwordx4 v[106:109], v0, s[4:5] offset:1024
	global_load_dwordx4 v[110:113], v0, s[4:5] offset:2048
	global_load_dwordx4 v[114:117], v0, s[4:5] offset:3072
	global_load_dwordx2 v[118:119], v1, s[58:59] offset:0
	global_load_dwordx2 v[122:123], v1, s[58:59] offset:512
	global_load_dwordx2 v[134:135], v1, s[58:59] offset:1024
	global_load_dwordx2 v[138:139], v1, s[58:59] offset:1536
	global_load_dwordx2 v[120:121], v1, s[60:61] offset:0
	global_load_dwordx2 v[124:125], v1, s[60:61] offset:512
	global_load_dwordx2 v[136:137], v1, s[60:61] offset:1024
	global_load_dwordx2 v[140:141], v1, s[60:61] offset:1536
	s_add_u32 s4, s4, 0x1000
	s_addc_u32 s5, s5, 0
	s_add_u32 s58, s58, 0x800
	s_addc_u32 s59, s59, 0
	s_add_u32 s60, s60, 0x800
	s_addc_u32 s61, s61, 0
	s_waitcnt vmcnt(32)
	v_lshlrev_b32_e32 v14, 16, v172
	v_and_b32_e32 v15, 0xffff0000, v172
	v_lshlrev_b32_e32 v16, 16, v174
	v_and_b32_e32 v17, 0xffff0000, v174
	v_lshlrev_b32_e32 v18, 16, v173
	v_and_b32_e32 v19, 0xffff0000, v173
	v_lshlrev_b32_e32 v20, 16, v175
	v_and_b32_e32 v21, 0xffff0000, v175
	v_pk_add_f32 v[172:173], v[14:15], v[16:17]
	v_pk_add_f32 v[174:175], v[18:19], v[20:21]
	v_lshlrev_b32_e32 v14, 16, v176
	v_and_b32_e32 v15, 0xffff0000, v176
	v_lshlrev_b32_e32 v16, 16, v178
	v_and_b32_e32 v17, 0xffff0000, v178
	v_lshlrev_b32_e32 v18, 16, v177
	v_and_b32_e32 v19, 0xffff0000, v177
	v_lshlrev_b32_e32 v20, 16, v179
	v_and_b32_e32 v21, 0xffff0000, v179
	v_pk_add_f32 v[176:177], v[14:15], v[16:17]
	v_pk_add_f32 v[178:179], v[18:19], v[20:21]
	v_lshlrev_b32_e32 v14, 16, v204
	v_and_b32_e32 v15, 0xffff0000, v204
	v_lshlrev_b32_e32 v16, 16, v206
	v_and_b32_e32 v17, 0xffff0000, v206
	v_lshlrev_b32_e32 v18, 16, v205
	v_and_b32_e32 v19, 0xffff0000, v205
	v_lshlrev_b32_e32 v20, 16, v207
	v_and_b32_e32 v21, 0xffff0000, v207
	v_pk_add_f32 v[204:205], v[14:15], v[16:17]
	v_pk_add_f32 v[206:207], v[18:19], v[20:21]
	v_lshlrev_b32_e32 v14, 16, v214
	v_and_b32_e32 v15, 0xffff0000, v214
	v_lshlrev_b32_e32 v16, 16, v216
	v_and_b32_e32 v17, 0xffff0000, v216
	v_lshlrev_b32_e32 v18, 16, v215
	v_and_b32_e32 v19, 0xffff0000, v215
	v_lshlrev_b32_e32 v20, 16, v217
	v_and_b32_e32 v21, 0xffff0000, v217
	v_pk_add_f32 v[214:215], v[14:15], v[16:17]
	v_pk_add_f32 v[216:217], v[18:19], v[20:21]
	v_pk_mul_f32 v[12:13], v[172:173], v[172:173]
	v_pk_fma_f32 v[12:13], v[174:175], v[174:175], v[12:13]
	v_pk_fma_f32 v[12:13], v[176:177], v[176:177], v[12:13]
	v_pk_fma_f32 v[12:13], v[178:179], v[178:179], v[12:13]
	v_pk_fma_f32 v[12:13], v[204:205], v[204:205], v[12:13]
	v_pk_fma_f32 v[12:13], v[206:207], v[206:207], v[12:13]
	v_pk_fma_f32 v[12:13], v[214:215], v[214:215], v[12:13]
	v_pk_fma_f32 v[12:13], v[216:217], v[216:217], v[12:13]
	v_add_f32_e32 v5, v12, v13
	s_nop 1
	v_add_f32_dpp v5, v5, v5 quad_perm:[1,0,3,2] row_mask:0xf bank_mask:0xf
	s_nop 1
	v_add_f32_dpp v5, v5, v5 quad_perm:[2,3,0,1] row_mask:0xf bank_mask:0xf
	s_nop 1
	v_add_f32_dpp v5, v5, v5 row_half_mirror row_mask:0xf bank_mask:0xf
	s_nop 1
	v_add_f32_dpp v5, v5, v5 row_mirror row_mask:0xf bank_mask:0xf
	s_nop 1
	v_add_f32_dpp v5, v5, v5 row_bcast:15 row_mask:0xa bank_mask:0xf
	s_nop 1
	v_add_f32_dpp v5, v5, v5 row_bcast:31 row_mask:0xc bank_mask:0xf
	s_nop 1
	v_readlane_b32 s32, v5, 63
	s_nop 1
	v_mov_b32_e32 v6, s32
	v_fmamk_f32 v6, v6, 0x3a800000, v146
	v_rsq_f32_e32 v6, v6
	s_nop 0
	v_mul_f32_e32 v8, 0.5, v6
	v_pk_mul_f32 v[14:15], v[172:173], v[8:9] op_sel_hi:[1,0]
	v_pk_mul_f32 v[14:15], v[38:39], v[14:15]
	v_pk_fma_f32 v[154:155], v[22:23], v[14:15], v[154:155]
	v_pk_mul_f32 v[14:15], v[174:175], v[8:9] op_sel_hi:[1,0]
	v_pk_mul_f32 v[14:15], v[40:41], v[14:15]
	v_pk_fma_f32 v[156:157], v[24:25], v[14:15], v[156:157]
	v_pk_mul_f32 v[14:15], v[176:177], v[8:9] op_sel_hi:[1,0]
	v_pk_mul_f32 v[14:15], v[42:43], v[14:15]
	v_pk_fma_f32 v[158:159], v[26:27], v[14:15], v[158:159]
	v_pk_mul_f32 v[14:15], v[178:179], v[8:9] op_sel_hi:[1,0]
	v_pk_mul_f32 v[14:15], v[44:45], v[14:15]
	v_pk_fma_f32 v[160:161], v[28:29], v[14:15], v[160:161]
	v_pk_mul_f32 v[14:15], v[204:205], v[8:9] op_sel_hi:[1,0]
	v_pk_mul_f32 v[14:15], v[46:47], v[14:15]
	v_pk_fma_f32 v[162:163], v[30:31], v[14:15], v[162:163]
	v_pk_mul_f32 v[14:15], v[206:207], v[8:9] op_sel_hi:[1,0]
	v_pk_mul_f32 v[14:15], v[48:49], v[14:15]
	v_pk_fma_f32 v[164:165], v[32:33], v[14:15], v[164:165]
	v_pk_mul_f32 v[14:15], v[214:215], v[8:9] op_sel_hi:[1,0]
	v_pk_mul_f32 v[14:15], v[50:51], v[14:15]
	v_pk_fma_f32 v[168:169], v[34:35], v[14:15], v[168:169]
	v_pk_mul_f32 v[14:15], v[216:217], v[8:9] op_sel_hi:[1,0]
	v_pk_mul_f32 v[14:15], v[52:53], v[14:15]
	v_pk_fma_f32 v[170:171], v[36:37], v[14:15], v[170:171]
	v_pk_mul_f32 v[12:13], v[154:155], v[154:155]
	v_pk_fma_f32 v[12:13], v[156:157], v[156:157], v[12:13]
	v_pk_fma_f32 v[12:13], v[158:159], v[158:159], v[12:13]
	v_pk_fma_f32 v[12:13], v[160:161], v[160:161], v[12:13]
	v_pk_fma_f32 v[12:13], v[162:163], v[162:163], v[12:13]
	v_pk_fma_f32 v[12:13], v[164:165], v[164:165], v[12:13]
	v_pk_fma_f32 v[12:13], v[168:169], v[168:169], v[12:13]
	v_pk_fma_f32 v[12:13], v[170:171], v[170:171], v[12:13]
	v_add_f32_e32 v5, v12, v13
	s_nop 1
	v_add_f32_dpp v5, v5, v5 quad_perm:[1,0,3,2] row_mask:0xf bank_mask:0xf
	s_nop 1
	v_add_f32_dpp v5, v5, v5 quad_perm:[2,3,0,1] row_mask:0xf bank_mask:0xf
	s_nop 1
	v_add_f32_dpp v5, v5, v5 row_half_mirror row_mask:0xf bank_mask:0xf
	s_nop 1
	v_add_f32_dpp v5, v5, v5 row_mirror row_mask:0xf bank_mask:0xf
	s_nop 1
	v_add_f32_dpp v5, v5, v5 row_bcast:15 row_mask:0xa bank_mask:0xf
	s_nop 1
	v_add_f32_dpp v5, v5, v5 row_bcast:31 row_mask:0xc bank_mask:0xf
	s_nop 1
	v_readlane_b32 s32, v5, 63
	s_nop 1
	v_mov_b32_e32 v6, s32
	v_fmamk_f32 v6, v6, 0x3a800000, v146
	v_rsq_f32_e32 v6, v6
	s_nop 0
	v_mov_b32_e32 v10, v6
	v_pk_mul_f32 v[14:15], v[154:155], v[10:11] op_sel_hi:[1,0]
	v_pk_mul_f32 v[14:15], v[86:87], v[14:15]
	v_pk_fma_f32 v[16:17], v[70:71], v[14:15], v[54:55]
	v_pk_mul_f32 v[14:15], v[156:157], v[10:11] op_sel_hi:[1,0]
	v_pk_mul_f32 v[14:15], v[88:89], v[14:15]
	v_pk_fma_f32 v[18:19], v[72:73], v[14:15], v[56:57]
	v_cvt_pk_bf16_f32 v172, v16, v17
	v_cvt_pk_bf16_f32 v173, v18, v19
	v_pk_mul_f32 v[14:15], v[158:159], v[10:11] op_sel_hi:[1,0]
	v_pk_mul_f32 v[14:15], v[90:91], v[14:15]
	v_pk_fma_f32 v[16:17], v[74:75], v[14:15], v[58:59]
	v_pk_mul_f32 v[14:15], v[160:161], v[10:11] op_sel_hi:[1,0]
	v_pk_mul_f32 v[14:15], v[92:93], v[14:15]
	v_pk_fma_f32 v[18:19], v[76:77], v[14:15], v[60:61]
	v_cvt_pk_bf16_f32 v176, v16, v17
	v_cvt_pk_bf16_f32 v177, v18, v19
	v_pk_mul_f32 v[14:15], v[162:163], v[10:11] op_sel_hi:[1,0]
	v_pk_mul_f32 v[14:15], v[94:95], v[14:15]
	v_pk_fma_f32 v[16:17], v[78:79], v[14:15], v[62:63]
	v_pk_mul_f32 v[14:15], v[164:165], v[10:11] op_sel_hi:[1,0]
	v_pk_mul_f32 v[14:15], v[96:97], v[14:15]
	v_pk_fma_f32 v[18:19], v[80:81], v[14:15], v[64:65]
	v_cvt_pk_bf16_f32 v204, v16, v17
	v_cvt_pk_bf16_f32 v205, v18, v19
	v_pk_mul_f32 v[14:15], v[168:169], v[10:11] op_sel_hi:[1,0]
	v_pk_mul_f32 v[14:15], v[98:99], v[14:15]
	v_pk_fma_f32 v[16:17], v[82:83], v[14:15], v[66:67]
	v_pk_mul_f32 v[14:15], v[170:171], v[10:11] op_sel_hi:[1,0]
	v_pk_mul_f32 v[14:15], v[100:101], v[14:15]
	v_pk_fma_f32 v[18:19], v[84:85], v[14:15], v[68:69]
	v_cvt_pk_bf16_f32 v214, v16, v17
	v_cvt_pk_bf16_f32 v215, v18, v19
	global_store_dwordx4 v0, v[154:157], s[46:47] offset:0 sc1
	global_store_dwordx4 v0, v[158:161], s[46:47] offset:1024 sc1
	global_store_dwordx4 v0, v[162:165], s[46:47] offset:2048 sc1
	global_store_dwordx4 v0, v[168:171], s[46:47] offset:3072 sc1
	global_store_dwordx2 v1, v[172:173], s[62:63] offset:0 sc1
	global_store_dwordx2 v1, v[176:177], s[62:63] offset:512 sc1
	global_store_dwordx2 v1, v[204:205], s[62:63] offset:1024 sc1
	global_store_dwordx2 v1, v[214:215], s[62:63] offset:1536 sc1
	s_add_u32 s46, s46, 0x1000
	s_addc_u32 s47, s47, 0
	s_add_u32 s62, s62, 0x800
	s_addc_u32 s63, s63, 0
	s_waitcnt vmcnt(28)
	v_lshlrev_b32_e32 v14, 16, v234
	v_and_b32_e32 v15, 0xffff0000, v234
	v_lshlrev_b32_e32 v16, 16, v236
	v_and_b32_e32 v17, 0xffff0000, v236
	v_lshlrev_b32_e32 v18, 16, v235
	v_and_b32_e32 v19, 0xffff0000, v235
	v_lshlrev_b32_e32 v20, 16, v237
	v_and_b32_e32 v21, 0xffff0000, v237
	v_pk_add_f32 v[234:235], v[14:15], v[16:17]
	v_pk_add_f32 v[236:237], v[18:19], v[20:21]
	v_lshlrev_b32_e32 v14, 16, v238
	v_and_b32_e32 v15, 0xffff0000, v238
	v_lshlrev_b32_e32 v16, 16, v240
	v_and_b32_e32 v17, 0xffff0000, v240
	v_lshlrev_b32_e32 v18, 16, v239
	v_and_b32_e32 v19, 0xffff0000, v239
	v_lshlrev_b32_e32 v20, 16, v241
	v_and_b32_e32 v21, 0xffff0000, v241
	v_pk_add_f32 v[238:239], v[14:15], v[16:17]
	v_pk_add_f32 v[240:241], v[18:19], v[20:21]
	v_lshlrev_b32_e32 v14, 16, v242
	v_and_b32_e32 v15, 0xffff0000, v242
	v_lshlrev_b32_e32 v16, 16, v244
	v_and_b32_e32 v17, 0xffff0000, v244
	v_lshlrev_b32_e32 v18, 16, v243
	v_and_b32_e32 v19, 0xffff0000, v243
	v_lshlrev_b32_e32 v20, 16, v245
	v_and_b32_e32 v21, 0xffff0000, v245
	v_pk_add_f32 v[242:243], v[14:15], v[16:17]
	v_pk_add_f32 v[244:245], v[18:19], v[20:21]
	v_lshlrev_b32_e32 v14, 16, v246
	v_and_b32_e32 v15, 0xffff0000, v246
	v_lshlrev_b32_e32 v16, 16, v248
	v_and_b32_e32 v17, 0xffff0000, v248
	v_lshlrev_b32_e32 v18, 16, v247
	v_and_b32_e32 v19, 0xffff0000, v247
	v_lshlrev_b32_e32 v20, 16, v249
	v_and_b32_e32 v21, 0xffff0000, v249
	v_pk_add_f32 v[246:247], v[14:15], v[16:17]
	v_pk_add_f32 v[248:249], v[18:19], v[20:21]
	v_pk_mul_f32 v[12:13], v[234:235], v[234:235]
	v_pk_fma_f32 v[12:13], v[236:237], v[236:237], v[12:13]
	v_pk_fma_f32 v[12:13], v[238:239], v[238:239], v[12:13]
	v_pk_fma_f32 v[12:13], v[240:241], v[240:241], v[12:13]
	v_pk_fma_f32 v[12:13], v[242:243], v[242:243], v[12:13]
	v_pk_fma_f32 v[12:13], v[244:245], v[244:245], v[12:13]
	v_pk_fma_f32 v[12:13], v[246:247], v[246:247], v[12:13]
	v_pk_fma_f32 v[12:13], v[248:249], v[248:249], v[12:13]
	v_add_f32_e32 v5, v12, v13
	s_nop 1
	v_add_f32_dpp v5, v5, v5 quad_perm:[1,0,3,2] row_mask:0xf bank_mask:0xf
	s_nop 1
	v_add_f32_dpp v5, v5, v5 quad_perm:[2,3,0,1] row_mask:0xf bank_mask:0xf
	s_nop 1
	v_add_f32_dpp v5, v5, v5 row_half_mirror row_mask:0xf bank_mask:0xf
	s_nop 1
	v_add_f32_dpp v5, v5, v5 row_mirror row_mask:0xf bank_mask:0xf
	s_nop 1
	v_add_f32_dpp v5, v5, v5 row_bcast:15 row_mask:0xa bank_mask:0xf
	s_nop 1
	v_add_f32_dpp v5, v5, v5 row_bcast:31 row_mask:0xc bank_mask:0xf
	s_nop 1
	v_readlane_b32 s32, v5, 63
	s_nop 1
	v_mov_b32_e32 v6, s32
	v_fmamk_f32 v6, v6, 0x3a800000, v146
	v_rsq_f32_e32 v6, v6
	s_nop 0
	v_mul_f32_e32 v8, 0.5, v6
	v_pk_mul_f32 v[14:15], v[234:235], v[8:9] op_sel_hi:[1,0]
	v_pk_mul_f32 v[14:15], v[38:39], v[14:15]
	v_pk_fma_f32 v[218:219], v[22:23], v[14:15], v[218:219]
	v_pk_mul_f32 v[14:15], v[236:237], v[8:9] op_sel_hi:[1,0]
	v_pk_mul_f32 v[14:15], v[40:41], v[14:15]
	v_pk_fma_f32 v[220:221], v[24:25], v[14:15], v[220:221]
	v_pk_mul_f32 v[14:15], v[238:239], v[8:9] op_sel_hi:[1,0]
	v_pk_mul_f32 v[14:15], v[42:43], v[14:15]
	v_pk_fma_f32 v[222:223], v[26:27], v[14:15], v[222:223]
	v_pk_mul_f32 v[14:15], v[240:241], v[8:9] op_sel_hi:[1,0]
	v_pk_mul_f32 v[14:15], v[44:45], v[14:15]
	v_pk_fma_f32 v[224:225], v[28:29], v[14:15], v[224:225]
	v_pk_mul_f32 v[14:15], v[242:243], v[8:9] op_sel_hi:[1,0]
	v_pk_mul_f32 v[14:15], v[46:47], v[14:15]
	v_pk_fma_f32 v[226:227], v[30:31], v[14:15], v[226:227]
	v_pk_mul_f32 v[14:15], v[244:245], v[8:9] op_sel_hi:[1,0]
	v_pk_mul_f32 v[14:15], v[48:49], v[14:15]
	v_pk_fma_f32 v[228:229], v[32:33], v[14:15], v[228:229]
	v_pk_mul_f32 v[14:15], v[246:247], v[8:9] op_sel_hi:[1,0]
	v_pk_mul_f32 v[14:15], v[50:51], v[14:15]
	v_pk_fma_f32 v[230:231], v[34:35], v[14:15], v[230:231]
	v_pk_mul_f32 v[14:15], v[248:249], v[8:9] op_sel_hi:[1,0]
	v_pk_mul_f32 v[14:15], v[52:53], v[14:15]
	v_pk_fma_f32 v[232:233], v[36:37], v[14:15], v[232:233]
	v_pk_mul_f32 v[12:13], v[218:219], v[218:219]
	v_pk_fma_f32 v[12:13], v[220:221], v[220:221], v[12:13]
	v_pk_fma_f32 v[12:13], v[222:223], v[222:223], v[12:13]
	v_pk_fma_f32 v[12:13], v[224:225], v[224:225], v[12:13]
	v_pk_fma_f32 v[12:13], v[226:227], v[226:227], v[12:13]
	v_pk_fma_f32 v[12:13], v[228:229], v[228:229], v[12:13]
	v_pk_fma_f32 v[12:13], v[230:231], v[230:231], v[12:13]
	v_pk_fma_f32 v[12:13], v[232:233], v[232:233], v[12:13]
	v_add_f32_e32 v5, v12, v13
	s_nop 1
	v_add_f32_dpp v5, v5, v5 quad_perm:[1,0,3,2] row_mask:0xf bank_mask:0xf
	s_nop 1
	v_add_f32_dpp v5, v5, v5 quad_perm:[2,3,0,1] row_mask:0xf bank_mask:0xf
	s_nop 1
	v_add_f32_dpp v5, v5, v5 row_half_mirror row_mask:0xf bank_mask:0xf
	s_nop 1
	v_add_f32_dpp v5, v5, v5 row_mirror row_mask:0xf bank_mask:0xf
	s_nop 1
	v_add_f32_dpp v5, v5, v5 row_bcast:15 row_mask:0xa bank_mask:0xf
	s_nop 1
	v_add_f32_dpp v5, v5, v5 row_bcast:31 row_mask:0xc bank_mask:0xf
	s_nop 1
	v_readlane_b32 s32, v5, 63
	s_nop 1
	v_mov_b32_e32 v6, s32
	v_fmamk_f32 v6, v6, 0x3a800000, v146
	v_rsq_f32_e32 v6, v6
	s_nop 0
	v_mov_b32_e32 v10, v6
	v_pk_mul_f32 v[14:15], v[218:219], v[10:11] op_sel_hi:[1,0]
	v_pk_mul_f32 v[14:15], v[86:87], v[14:15]
	v_pk_fma_f32 v[16:17], v[70:71], v[14:15], v[54:55]
	v_pk_mul_f32 v[14:15], v[220:221], v[10:11] op_sel_hi:[1,0]
	v_pk_mul_f32 v[14:15], v[88:89], v[14:15]
	v_pk_fma_f32 v[18:19], v[72:73], v[14:15], v[56:57]
	v_cvt_pk_bf16_f32 v234, v16, v17
	v_cvt_pk_bf16_f32 v235, v18, v19
	v_pk_mul_f32 v[14:15], v[222:223], v[10:11] op_sel_hi:[1,0]
	v_pk_mul_f32 v[14:15], v[90:91], v[14:15]
	v_pk_fma_f32 v[16:17], v[74:75], v[14:15], v[58:59]
	v_pk_mul_f32 v[14:15], v[224:225], v[10:11] op_sel_hi:[1,0]
	v_pk_mul_f32 v[14:15], v[92:93], v[14:15]
	v_pk_fma_f32 v[18:19], v[76:77], v[14:15], v[60:61]
	v_cvt_pk_bf16_f32 v238, v16, v17
	v_cvt_pk_bf16_f32 v239, v18, v19
	v_pk_mul_f32 v[14:15], v[226:227], v[10:11] op_sel_hi:[1,0]
	v_pk_mul_f32 v[14:15], v[94:95], v[14:15]
	v_pk_fma_f32 v[16:17], v[78:79], v[14:15], v[62:63]
	v_pk_mul_f32 v[14:15], v[228:229], v[10:11] op_sel_hi:[1,0]
	v_pk_mul_f32 v[14:15], v[96:97], v[14:15]
	v_pk_fma_f32 v[18:19], v[80:81], v[14:15], v[64:65]
	v_cvt_pk_bf16_f32 v242, v16, v17
	v_cvt_pk_bf16_f32 v243, v18, v19
	v_pk_mul_f32 v[14:15], v[230:231], v[10:11] op_sel_hi:[1,0]
	v_pk_mul_f32 v[14:15], v[98:99], v[14:15]
	v_pk_fma_f32 v[16:17], v[82:83], v[14:15], v[66:67]
	v_pk_mul_f32 v[14:15], v[232:233], v[10:11] op_sel_hi:[1,0]
	v_pk_mul_f32 v[14:15], v[100:101], v[14:15]
	v_pk_fma_f32 v[18:19], v[84:85], v[14:15], v[68:69]
	v_cvt_pk_bf16_f32 v246, v16, v17
	v_cvt_pk_bf16_f32 v247, v18, v19
	global_store_dwordx4 v0, v[218:221], s[46:47] offset:0 sc1
	global_store_dwordx4 v0, v[222:225], s[46:47] offset:1024 sc1
	global_store_dwordx4 v0, v[226:229], s[46:47] offset:2048 sc1
	global_store_dwordx4 v0, v[230:233], s[46:47] offset:3072 sc1
	global_store_dwordx2 v1, v[234:235], s[62:63] offset:0 sc1
	global_store_dwordx2 v1, v[238:239], s[62:63] offset:512 sc1
	global_store_dwordx2 v1, v[242:243], s[62:63] offset:1024 sc1
	global_store_dwordx2 v1, v[246:247], s[62:63] offset:1536 sc1
	s_add_u32 s46, s46, 0x1000
	s_addc_u32 s47, s47, 0
	s_add_u32 s62, s62, 0x800
	s_addc_u32 s63, s63, 0
	s_waitcnt vmcnt(16)
	v_lshlrev_b32_e32 v14, 16, v118
	v_and_b32_e32 v15, 0xffff0000, v118
	v_lshlrev_b32_e32 v16, 16, v120
	v_and_b32_e32 v17, 0xffff0000, v120
	v_lshlrev_b32_e32 v18, 16, v119
	v_and_b32_e32 v19, 0xffff0000, v119
	v_lshlrev_b32_e32 v20, 16, v121
	v_and_b32_e32 v21, 0xffff0000, v121
	v_pk_add_f32 v[118:119], v[14:15], v[16:17]
	v_pk_add_f32 v[120:121], v[18:19], v[20:21]
	v_lshlrev_b32_e32 v14, 16, v122
	v_and_b32_e32 v15, 0xffff0000, v122
	v_lshlrev_b32_e32 v16, 16, v124
	v_and_b32_e32 v17, 0xffff0000, v124
	v_lshlrev_b32_e32 v18, 16, v123
	v_and_b32_e32 v19, 0xffff0000, v123
	v_lshlrev_b32_e32 v20, 16, v125
	v_and_b32_e32 v21, 0xffff0000, v125
	v_pk_add_f32 v[122:123], v[14:15], v[16:17]
	v_pk_add_f32 v[124:125], v[18:19], v[20:21]
	v_lshlrev_b32_e32 v14, 16, v134
	v_and_b32_e32 v15, 0xffff0000, v134
	v_lshlrev_b32_e32 v16, 16, v136
	v_and_b32_e32 v17, 0xffff0000, v136
	v_lshlrev_b32_e32 v18, 16, v135
	v_and_b32_e32 v19, 0xffff0000, v135
	v_lshlrev_b32_e32 v20, 16, v137
	v_and_b32_e32 v21, 0xffff0000, v137
	v_pk_add_f32 v[134:135], v[14:15], v[16:17]
	v_pk_add_f32 v[136:137], v[18:19], v[20:21]
	v_lshlrev_b32_e32 v14, 16, v138
	v_and_b32_e32 v15, 0xffff0000, v138
	v_lshlrev_b32_e32 v16, 16, v140
	v_and_b32_e32 v17, 0xffff0000, v140
	v_lshlrev_b32_e32 v18, 16, v139
	v_and_b32_e32 v19, 0xffff0000, v139
	v_lshlrev_b32_e32 v20, 16, v141
	v_and_b32_e32 v21, 0xffff0000, v141
	v_pk_add_f32 v[138:139], v[14:15], v[16:17]
	v_pk_add_f32 v[140:141], v[18:19], v[20:21]
	v_pk_mul_f32 v[12:13], v[118:119], v[118:119]
	v_pk_fma_f32 v[12:13], v[120:121], v[120:121], v[12:13]
	v_pk_fma_f32 v[12:13], v[122:123], v[122:123], v[12:13]
	v_pk_fma_f32 v[12:13], v[124:125], v[124:125], v[12:13]
	v_pk_fma_f32 v[12:13], v[134:135], v[134:135], v[12:13]
	v_pk_fma_f32 v[12:13], v[136:137], v[136:137], v[12:13]
	v_pk_fma_f32 v[12:13], v[138:139], v[138:139], v[12:13]
	v_pk_fma_f32 v[12:13], v[140:141], v[140:141], v[12:13]
	v_add_f32_e32 v5, v12, v13
	s_nop 1
	v_add_f32_dpp v5, v5, v5 quad_perm:[1,0,3,2] row_mask:0xf bank_mask:0xf
	s_nop 1
	v_add_f32_dpp v5, v5, v5 quad_perm:[2,3,0,1] row_mask:0xf bank_mask:0xf
	s_nop 1
	v_add_f32_dpp v5, v5, v5 row_half_mirror row_mask:0xf bank_mask:0xf
	s_nop 1
	v_add_f32_dpp v5, v5, v5 row_mirror row_mask:0xf bank_mask:0xf
	s_nop 1
	v_add_f32_dpp v5, v5, v5 row_bcast:15 row_mask:0xa bank_mask:0xf
	s_nop 1
	v_add_f32_dpp v5, v5, v5 row_bcast:31 row_mask:0xc bank_mask:0xf
	s_nop 1
	v_readlane_b32 s32, v5, 63
	s_nop 1
	v_mov_b32_e32 v6, s32
	v_fmamk_f32 v6, v6, 0x3a800000, v146
	v_rsq_f32_e32 v6, v6
	s_nop 0
	v_mul_f32_e32 v8, 0.5, v6
	v_pk_mul_f32 v[14:15], v[118:119], v[8:9] op_sel_hi:[1,0]
	v_pk_mul_f32 v[14:15], v[38:39], v[14:15]
	v_pk_fma_f32 v[102:103], v[22:23], v[14:15], v[102:103]
	v_pk_mul_f32 v[14:15], v[120:121], v[8:9] op_sel_hi:[1,0]
	v_pk_mul_f32 v[14:15], v[40:41], v[14:15]
	v_pk_fma_f32 v[104:105], v[24:25], v[14:15], v[104:105]
	v_pk_mul_f32 v[14:15], v[122:123], v[8:9] op_sel_hi:[1,0]
	v_pk_mul_f32 v[14:15], v[42:43], v[14:15]
	v_pk_fma_f32 v[106:107], v[26:27], v[14:15], v[106:107]
	v_pk_mul_f32 v[14:15], v[124:125], v[8:9] op_sel_hi:[1,0]
	v_pk_mul_f32 v[14:15], v[44:45], v[14:15]
	v_pk_fma_f32 v[108:109], v[28:29], v[14:15], v[108:109]
	v_pk_mul_f32 v[14:15], v[134:135], v[8:9] op_sel_hi:[1,0]
	v_pk_mul_f32 v[14:15], v[46:47], v[14:15]
	v_pk_fma_f32 v[110:111], v[30:31], v[14:15], v[110:111]
	v_pk_mul_f32 v[14:15], v[136:137], v[8:9] op_sel_hi:[1,0]
	v_pk_mul_f32 v[14:15], v[48:49], v[14:15]
	v_pk_fma_f32 v[112:113], v[32:33], v[14:15], v[112:113]
	v_pk_mul_f32 v[14:15], v[138:139], v[8:9] op_sel_hi:[1,0]
	v_pk_mul_f32 v[14:15], v[50:51], v[14:15]
	v_pk_fma_f32 v[114:115], v[34:35], v[14:15], v[114:115]
	v_pk_mul_f32 v[14:15], v[140:141], v[8:9] op_sel_hi:[1,0]
	v_pk_mul_f32 v[14:15], v[52:53], v[14:15]
	v_pk_fma_f32 v[116:117], v[36:37], v[14:15], v[116:117]
	v_pk_mul_f32 v[12:13], v[102:103], v[102:103]
	v_pk_fma_f32 v[12:13], v[104:105], v[104:105], v[12:13]
	v_pk_fma_f32 v[12:13], v[106:107], v[106:107], v[12:13]
	v_pk_fma_f32 v[12:13], v[108:109], v[108:109], v[12:13]
	v_pk_fma_f32 v[12:13], v[110:111], v[110:111], v[12:13]
	v_pk_fma_f32 v[12:13], v[112:113], v[112:113], v[12:13]
	v_pk_fma_f32 v[12:13], v[114:115], v[114:115], v[12:13]
	v_pk_fma_f32 v[12:13], v[116:117], v[116:117], v[12:13]
	v_add_f32_e32 v5, v12, v13
	s_nop 1
	v_add_f32_dpp v5, v5, v5 quad_perm:[1,0,3,2] row_mask:0xf bank_mask:0xf
	s_nop 1
	v_add_f32_dpp v5, v5, v5 quad_perm:[2,3,0,1] row_mask:0xf bank_mask:0xf
	s_nop 1
	v_add_f32_dpp v5, v5, v5 row_half_mirror row_mask:0xf bank_mask:0xf
	s_nop 1
	v_add_f32_dpp v5, v5, v5 row_mirror row_mask:0xf bank_mask:0xf
	s_nop 1
	v_add_f32_dpp v5, v5, v5 row_bcast:15 row_mask:0xa bank_mask:0xf
	s_nop 1
	v_add_f32_dpp v5, v5, v5 row_bcast:31 row_mask:0xc bank_mask:0xf
	s_nop 1
	v_readlane_b32 s32, v5, 63
	s_nop 1
	v_mov_b32_e32 v6, s32
	v_fmamk_f32 v6, v6, 0x3a800000, v146
	v_rsq_f32_e32 v6, v6
	s_nop 0
	v_mov_b32_e32 v10, v6
	v_pk_mul_f32 v[14:15], v[102:103], v[10:11] op_sel_hi:[1,0]
	v_pk_mul_f32 v[14:15], v[86:87], v[14:15]
	v_pk_fma_f32 v[16:17], v[70:71], v[14:15], v[54:55]
	v_pk_mul_f32 v[14:15], v[104:105], v[10:11] op_sel_hi:[1,0]
	v_pk_mul_f32 v[14:15], v[88:89], v[14:15]
	v_pk_fma_f32 v[18:19], v[72:73], v[14:15], v[56:57]
	v_cvt_pk_bf16_f32 v118, v16, v17
	v_cvt_pk_bf16_f32 v119, v18, v19
	v_pk_mul_f32 v[14:15], v[106:107], v[10:11] op_sel_hi:[1,0]
	v_pk_mul_f32 v[14:15], v[90:91], v[14:15]
	v_pk_fma_f32 v[16:17], v[74:75], v[14:15], v[58:59]
	v_pk_mul_f32 v[14:15], v[108:109], v[10:11] op_sel_hi:[1,0]
	v_pk_mul_f32 v[14:15], v[92:93], v[14:15]
	v_pk_fma_f32 v[18:19], v[76:77], v[14:15], v[60:61]
	v_cvt_pk_bf16_f32 v122, v16, v17
	v_cvt_pk_bf16_f32 v123, v18, v19
	v_pk_mul_f32 v[14:15], v[110:111], v[10:11] op_sel_hi:[1,0]
	v_pk_mul_f32 v[14:15], v[94:95], v[14:15]
	v_pk_fma_f32 v[16:17], v[78:79], v[14:15], v[62:63]
	v_pk_mul_f32 v[14:15], v[112:113], v[10:11] op_sel_hi:[1,0]
	v_pk_mul_f32 v[14:15], v[96:97], v[14:15]
	v_pk_fma_f32 v[18:19], v[80:81], v[14:15], v[64:65]
	v_cvt_pk_bf16_f32 v134, v16, v17
	v_cvt_pk_bf16_f32 v135, v18, v19
	v_pk_mul_f32 v[14:15], v[114:115], v[10:11] op_sel_hi:[1,0]
	v_pk_mul_f32 v[14:15], v[98:99], v[14:15]
	v_pk_fma_f32 v[16:17], v[82:83], v[14:15], v[66:67]
	v_pk_mul_f32 v[14:15], v[116:117], v[10:11] op_sel_hi:[1,0]
	v_pk_mul_f32 v[14:15], v[100:101], v[14:15]
	v_pk_fma_f32 v[18:19], v[84:85], v[14:15], v[68:69]
	v_cvt_pk_bf16_f32 v138, v16, v17
	v_cvt_pk_bf16_f32 v139, v18, v19
	global_store_dwordx4 v0, v[102:105], s[46:47] offset:0 sc1
	global_store_dwordx4 v0, v[106:109], s[46:47] offset:1024 sc1
	global_store_dwordx4 v0, v[110:113], s[46:47] offset:2048 sc1
	global_store_dwordx4 v0, v[114:117], s[46:47] offset:3072 sc1
	global_store_dwordx2 v1, v[118:119], s[62:63] offset:0 sc1
	global_store_dwordx2 v1, v[122:123], s[62:63] offset:512 sc1
	global_store_dwordx2 v1, v[134:135], s[62:63] offset:1024 sc1
	global_store_dwordx2 v1, v[138:139], s[62:63] offset:1536 sc1
	s_add_u32 s46, s46, 0x1000
	s_addc_u32 s47, s47, 0
	s_add_u32 s62, s62, 0x800
	s_addc_u32 s63, s63, 0

.LBB0_1222:
	s_or_b64 exec, exec, s[4:5]
	s_waitcnt lgkmcnt(0)
	v_mov_b32_e32 v0, v147
	v_readlane_b32 s2, v255, 0
	s_barrier
	s_nop 0
	v_ashrrev_i32_e32 v1, 6, v0
	v_lshl_add_u32 v16, s2, 3, v1
	s_movk_i32 s2, 0x2000
	v_cmp_gt_i32_e32 vcc, s2, v16
	s_and_saveexec_b64 s[10:11], vcc
	s_cbranch_execz .LBB0_1225
	s_load_dwordx4 s[4:7], s[8:9], 0x90
	s_load_dwordx4 s[16:19], s[8:9], 0x40
	s_mul_i32 s2, s70, 0x2d000
	v_lshlrev_b32_e32 v1, 2, v0
	v_readlane_b32 s20, v255, 12
	s_waitcnt lgkmcnt(0)
	s_add_u32 s14, s6, s2
	s_mul_hi_u32 s2, s70, 0x2d000
	s_addc_u32 s15, s7, s2
	v_cmp_lt_i32_e32 vcc, v188, v183
	v_and_b32_e32 v2, 0xfc, v1
	s_add_u32 s12, s14, 0x106000
	v_readlane_b32 s21, v255, 13
	v_cndmask_b32_e32 v1, v182, v188, vcc
	v_cmp_lt_i32_e32 vcc, v254, v183
	s_addc_u32 s13, s15, 0
	s_lshl_b64 s[20:21], s[20:21], 2
	v_lshlrev_b32_e32 v28, 2, v1
	v_cndmask_b32_e32 v1, v182, v254, vcc
	s_add_u32 s16, s16, s20
	v_lshlrev_b32_e32 v29, 2, v1
	v_xor_b32_e32 v1, 4, v182
	s_addc_u32 s17, s17, s21
	v_cmp_lt_i32_e32 vcc, v1, v183
	s_add_u32 s18, s18, s20
	v_lshlrev_b32_e32 v144, 2, v2
	v_cndmask_b32_e32 v1, v182, v1, vcc
	s_addc_u32 s19, s19, s21
	v_lshl_add_u64 v[4:5], s[14:15], 0, v[144:145]
	s_mov_b64 s[14:15], 0x105000
	v_lshlrev_b32_e32 v30, 2, v1
	v_xor_b32_e32 v1, 8, v182
	v_lshl_add_u64 v[18:19], v[4:5], 0, s[14:15]
	v_lshl_add_u64 v[4:5], s[18:19], 0, v[144:145]
	v_cmp_lt_i32_e32 vcc, v1, v183
	v_lshl_add_u64 v[20:21], v[4:5], 0, s[94:95]
	v_lshl_add_u64 v[4:5], s[16:17], 0, v[144:145]
	s_mov_b64 s[14:15], 0x2000
	v_cndmask_b32_e32 v1, v182, v1, vcc
	v_cmp_lt_i32_e32 vcc, v187, v183
	v_ashrrev_i32_e32 v17, 31, v16
	v_lshl_add_u64 v[22:23], v[4:5], 0, s[14:15]
	v_lshlrev_b32_e32 v31, 2, v1
	v_cndmask_b32_e32 v1, v182, v187, vcc
	v_cmp_lt_i32_e32 vcc, v184, v183
	v_lshlrev_b64 v[4:5], 11, v[16:17]
	v_and_b32_e32 v3, 63, v0
	v_lshlrev_b32_e32 v32, 2, v1
	v_cndmask_b32_e32 v1, v182, v184, vcc
	v_lshl_or_b32 v4, v3, 3, v4
	v_lshlrev_b32_e32 v33, 2, v1
	v_lshl_add_u64 v[0:1], s[6:7], 0, v[4:5]
	s_mov_b64 s[6:7], 0x9800600
	v_lshl_add_u64 v[24:25], v[0:1], 0, s[6:7]
	v_lshlrev_b64 v[0:1], 12, v[16:17]
	v_lshl_or_b32 v0, v3, 4, v0
	v_lshl_add_u64 v[26:27], s[4:5], 0, v[0:1]
	s_mov_b64 s[4:5], 0
	v_lshlrev_b32_e32 v144, 2, v2
	v_readlane_b32 s2, v255, 0
	v_readfirstlane_b32 s7, v147
	s_load_dwordx2 s[4:5], s[8:9], 0x90
	s_load_dwordx2 s[12:13], s[8:9], 0x98
	s_load_dwordx2 s[14:15], s[8:9], 0x40
	s_load_dwordx2 s[40:41], s[8:9], 0x48
	v_and_b32_e32 v0, 63, v147
	v_lshlrev_b32_e32 v1, 3, v0
	v_lshlrev_b32_e32 v0, 4, v0
	s_lshr_b32 s7, s7, 6
	s_lshl_b32 s2, s2, 3
	s_add_u32 s2, s2, s7
	s_lshl_b32 s24, s2, 2
	s_sub_u32 s27, s24, 0x1000
	s_lshr_b32 s27, s27, 10
	s_add_u32 s27, s27, 1
	s_cmp_lt_u32 s24, 0x1000
	s_cselect_b32 s30, 0, s27
	v_add_u32_e32 v2, 0x5000, v0
	v_add_u32_e32 v3, 0x6000, v0
	v_add_u32_e32 v4, 0x7000, v0
	s_waitcnt lgkmcnt(0)
	s_lshl_b32 s27, s24, 11
	s_add_u32 s62, s12, s27
	s_addc_u32 s63, s13, 0
	s_add_u32 s58, s62, 0x8800000
	s_addc_u32 s59, s63, 0
	s_add_u32 s60, s58, 0x1000000
	s_addc_u32 s61, s59, 0
	s_add_u32 s62, s62, 0x1000000
	s_addc_u32 s63, s63, 0
	s_lshl_b32 s27, s24, 12
	s_add_u32 s46, s4, s27
	s_addc_u32 s47, s5, 0
	s_mov_b64 s[4:5], s[46:47]
	s_mul_i32 s27, s70, 5
	s_add_u32 s27, s27, s30
	s_mul_i32 s27, s27, 0x9000
	s_add_u32 s27, s27, 0x100000
	s_add_u32 s88, s12, s27
	s_addc_u32 s89, s13, 0
	s_mov_b64 s[100:101], s[88:89]
	s_mul_i32 s27, s70, 0x3000
	s_add_u32 s27, s27, 0x1000
	s_add_u32 s40, s40, s27
	s_addc_u32 s41, s41, 0
	s_mul_i32 s27, s70, 0x3000
	s_add_u32 s27, s27, 0x2000
	s_add_u32 s14, s14, s27
	s_addc_u32 s15, s15, 0
	global_load_dwordx4 v[22:25], v2, s[100:101] offset:0
	global_load_dwordx4 v[38:41], v0, s[40:41] offset:0
	global_load_dwordx4 v[54:57], v3, s[88:89] offset:0
	global_load_dwordx4 v[70:73], v4, s[88:89] offset:0
	global_load_dwordx4 v[86:89], v0, s[14:15] offset:0
	global_load_dwordx4 v[26:29], v2, s[100:101] offset:1024
	global_load_dwordx4 v[42:45], v0, s[40:41] offset:1024
	global_load_dwordx4 v[58:61], v3, s[88:89] offset:1024
	global_load_dwordx4 v[74:77], v4, s[88:89] offset:1024
	global_load_dwordx4 v[90:93], v0, s[14:15] offset:1024
	global_load_dwordx4 v[30:33], v2, s[100:101] offset:2048
	global_load_dwordx4 v[46:49], v0, s[40:41] offset:2048
	global_load_dwordx4 v[62:65], v3, s[88:89] offset:2048
	global_load_dwordx4 v[78:81], v4, s[88:89] offset:2048
	global_load_dwordx4 v[94:97], v0, s[14:15] offset:2048
	global_load_dwordx4 v[34:37], v2, s[100:101] offset:3072
	global_load_dwordx4 v[50:53], v0, s[40:41] offset:3072
	global_load_dwordx4 v[66:69], v3, s[88:89] offset:3072
	global_load_dwordx4 v[82:85], v4, s[88:89] offset:3072
	global_load_dwordx4 v[98:101], v0, s[14:15] offset:3072
	global_load_dwordx4 v[102:105], v0, s[4:5] offset:0
	global_load_dwordx4 v[106:109], v0, s[4:5] offset:1024
	global_load_dwordx4 v[110:113], v0, s[4:5] offset:2048
	global_load_dwordx4 v[114:117], v0, s[4:5] offset:3072
	global_load_dwordx2 v[118:119], v1, s[58:59] offset:0
	global_load_dwordx2 v[122:123], v1, s[58:59] offset:512
	global_load_dwordx2 v[134:135], v1, s[58:59] offset:1024
	global_load_dwordx2 v[138:139], v1, s[58:59] offset:1536
	global_load_dwordx2 v[120:121], v1, s[60:61] offset:0
	global_load_dwordx2 v[124:125], v1, s[60:61] offset:512
	global_load_dwordx2 v[136:137], v1, s[60:61] offset:1024
	global_load_dwordx2 v[140:141], v1, s[60:61] offset:1536
	s_add_u32 s4, s4, 0x1000
	s_addc_u32 s5, s5, 0
	s_add_u32 s58, s58, 0x800
	s_addc_u32 s59, s59, 0
	s_add_u32 s60, s60, 0x800
	s_addc_u32 s61, s61, 0
	global_load_dwordx4 v[154:157], v0, s[4:5] offset:0
	global_load_dwordx4 v[158:161], v0, s[4:5] offset:1024
	global_load_dwordx4 v[162:165], v0, s[4:5] offset:2048
	global_load_dwordx4 v[168:171], v0, s[4:5] offset:3072
	global_load_dwordx2 v[172:173], v1, s[58:59] offset:0
	global_load_dwordx2 v[176:177], v1, s[58:59] offset:512
	global_load_dwordx2 v[204:205], v1, s[58:59] offset:1024
	global_load_dwordx2 v[214:215], v1, s[58:59] offset:1536
	global_load_dwordx2 v[174:175], v1, s[60:61] offset:0
	global_load_dwordx2 v[178:179], v1, s[60:61] offset:512
	global_load_dwordx2 v[206:207], v1, s[60:61] offset:1024
	global_load_dwordx2 v[216:217], v1, s[60:61] offset:1536
	s_add_u32 s4, s4, 0x1000
	s_addc_u32 s5, s5, 0
	s_add_u32 s58, s58, 0x800
	s_addc_u32 s59, s59, 0
	s_add_u32 s60, s60, 0x800
	s_addc_u32 s61, s61, 0
	global_load_dwordx4 v[218:221], v0, s[4:5] offset:0
	global_load_dwordx4 v[222:225], v0, s[4:5] offset:1024
	global_load_dwordx4 v[226:229], v0, s[4:5] offset:2048
	global_load_dwordx4 v[230:233], v0, s[4:5] offset:3072
	global_load_dwordx2 v[234:235], v1, s[58:59] offset:0
	global_load_dwordx2 v[238:239], v1, s[58:59] offset:512
	global_load_dwordx2 v[242:243], v1, s[58:59] offset:1024
	global_load_dwordx2 v[246:247], v1, s[58:59] offset:1536
	global_load_dwordx2 v[236:237], v1, s[60:61] offset:0
	global_load_dwordx2 v[240:241], v1, s[60:61] offset:512
	global_load_dwordx2 v[244:245], v1, s[60:61] offset:1024
	global_load_dwordx2 v[248:249], v1, s[60:61] offset:1536
	s_add_u32 s4, s4, 0x1000
	s_addc_u32 s5, s5, 0
	s_add_u32 s58, s58, 0x800
	s_addc_u32 s59, s59, 0
	s_add_u32 s60, s60, 0x800
	s_addc_u32 s61, s61, 0
	s_waitcnt vmcnt(24)
	v_pk_add_f32 v[70:71], v[70:71], 1.0 op_sel_hi:[1,0]
	v_pk_add_f32 v[72:73], v[72:73], 1.0 op_sel_hi:[1,0]
	v_pk_add_f32 v[74:75], v[74:75], 1.0 op_sel_hi:[1,0]
	v_pk_add_f32 v[76:77], v[76:77], 1.0 op_sel_hi:[1,0]
	v_pk_add_f32 v[78:79], v[78:79], 1.0 op_sel_hi:[1,0]
	v_pk_add_f32 v[80:81], v[80:81], 1.0 op_sel_hi:[1,0]
	v_pk_add_f32 v[82:83], v[82:83], 1.0 op_sel_hi:[1,0]
	v_pk_add_f32 v[84:85], v[84:85], 1.0 op_sel_hi:[1,0]
	v_lshlrev_b32_e32 v14, 16, v118
	v_and_b32_e32 v15, 0xffff0000, v118
	v_lshlrev_b32_e32 v16, 16, v120
	v_and_b32_e32 v17, 0xffff0000, v120
	v_lshlrev_b32_e32 v18, 16, v119
	v_and_b32_e32 v19, 0xffff0000, v119
	v_lshlrev_b32_e32 v20, 16, v121
	v_and_b32_e32 v21, 0xffff0000, v121
	v_pk_add_f32 v[118:119], v[14:15], v[16:17]
	v_pk_add_f32 v[120:121], v[18:19], v[20:21]
	v_lshlrev_b32_e32 v14, 16, v122
	v_and_b32_e32 v15, 0xffff0000, v122
	v_lshlrev_b32_e32 v16, 16, v124
	v_and_b32_e32 v17, 0xffff0000, v124
	v_lshlrev_b32_e32 v18, 16, v123
	v_and_b32_e32 v19, 0xffff0000, v123
	v_lshlrev_b32_e32 v20, 16, v125
	v_and_b32_e32 v21, 0xffff0000, v125
	v_pk_add_f32 v[122:123], v[14:15], v[16:17]
	v_pk_add_f32 v[124:125], v[18:19], v[20:21]
	v_lshlrev_b32_e32 v14, 16, v134
	v_and_b32_e32 v15, 0xffff0000, v134
	v_lshlrev_b32_e32 v16, 16, v136
	v_and_b32_e32 v17, 0xffff0000, v136
	v_lshlrev_b32_e32 v18, 16, v135
	v_and_b32_e32 v19, 0xffff0000, v135
	v_lshlrev_b32_e32 v20, 16, v137
	v_and_b32_e32 v21, 0xffff0000, v137
	v_pk_add_f32 v[134:135], v[14:15], v[16:17]
	v_pk_add_f32 v[136:137], v[18:19], v[20:21]
	v_lshlrev_b32_e32 v14, 16, v138
	v_and_b32_e32 v15, 0xffff0000, v138
	v_lshlrev_b32_e32 v16, 16, v140
	v_and_b32_e32 v17, 0xffff0000, v140
	v_lshlrev_b32_e32 v18, 16, v139
	v_and_b32_e32 v19, 0xffff0000, v139
	v_lshlrev_b32_e32 v20, 16, v141
	v_and_b32_e32 v21, 0xffff0000, v141
	v_pk_add_f32 v[138:139], v[14:15], v[16:17]
	v_pk_add_f32 v[140:141], v[18:19], v[20:21]
	v_pk_mul_f32 v[12:13], v[118:119], v[118:119]
	v_pk_fma_f32 v[12:13], v[120:121], v[120:121], v[12:13]
	v_pk_fma_f32 v[12:13], v[122:123], v[122:123], v[12:13]
	v_pk_fma_f32 v[12:13], v[124:125], v[124:125], v[12:13]
	v_pk_fma_f32 v[12:13], v[134:135], v[134:135], v[12:13]
	v_pk_fma_f32 v[12:13], v[136:137], v[136:137], v[12:13]
	v_pk_fma_f32 v[12:13], v[138:139], v[138:139], v[12:13]
	v_pk_fma_f32 v[12:13], v[140:141], v[140:141], v[12:13]
	v_add_f32_e32 v5, v12, v13
	s_nop 1
	v_add_f32_dpp v5, v5, v5 quad_perm:[1,0,3,2] row_mask:0xf bank_mask:0xf
	s_nop 1
	v_add_f32_dpp v5, v5, v5 quad_perm:[2,3,0,1] row_mask:0xf bank_mask:0xf
	s_nop 1
	v_add_f32_dpp v5, v5, v5 row_half_mirror row_mask:0xf bank_mask:0xf
	s_nop 1
	v_add_f32_dpp v5, v5, v5 row_mirror row_mask:0xf bank_mask:0xf
	s_nop 1
	v_add_f32_dpp v5, v5, v5 row_bcast:15 row_mask:0xa bank_mask:0xf
	s_nop 1
	v_add_f32_dpp v5, v5, v5 row_bcast:31 row_mask:0xc bank_mask:0xf
	s_nop 1
	v_readlane_b32 s32, v5, 63
	s_nop 1
	v_mov_b32_e32 v6, s32
	v_fmamk_f32 v6, v6, 0x3a800000, v146
	v_rsq_f32_e32 v6, v6
	s_nop 0
	v_mov_b32_e32 v8, v6
	v_pk_mul_f32 v[14:15], v[118:119], v[8:9] op_sel_hi:[1,0]
	v_pk_mul_f32 v[14:15], v[38:39], v[14:15]
	v_pk_fma_f32 v[102:103], v[22:23], v[14:15], v[102:103]
	v_pk_mul_f32 v[14:15], v[120:121], v[8:9] op_sel_hi:[1,0]
	v_pk_mul_f32 v[14:15], v[40:41], v[14:15]
	v_pk_fma_f32 v[104:105], v[24:25], v[14:15], v[104:105]
	v_pk_mul_f32 v[14:15], v[122:123], v[8:9] op_sel_hi:[1,0]
	v_pk_mul_f32 v[14:15], v[42:43], v[14:15]
	v_pk_fma_f32 v[106:107], v[26:27], v[14:15], v[106:107]
	v_pk_mul_f32 v[14:15], v[124:125], v[8:9] op_sel_hi:[1,0]
	v_pk_mul_f32 v[14:15], v[44:45], v[14:15]
	v_pk_fma_f32 v[108:109], v[28:29], v[14:15], v[108:109]
	v_pk_mul_f32 v[14:15], v[134:135], v[8:9] op_sel_hi:[1,0]
	v_pk_mul_f32 v[14:15], v[46:47], v[14:15]
	v_pk_fma_f32 v[110:111], v[30:31], v[14:15], v[110:111]
	v_pk_mul_f32 v[14:15], v[136:137], v[8:9] op_sel_hi:[1,0]
	v_pk_mul_f32 v[14:15], v[48:49], v[14:15]
	v_pk_fma_f32 v[112:113], v[32:33], v[14:15], v[112:113]
	v_pk_mul_f32 v[14:15], v[138:139], v[8:9] op_sel_hi:[1,0]
	v_pk_mul_f32 v[14:15], v[50:51], v[14:15]
	v_pk_fma_f32 v[114:115], v[34:35], v[14:15], v[114:115]
	v_pk_mul_f32 v[14:15], v[140:141], v[8:9] op_sel_hi:[1,0]
	v_pk_mul_f32 v[14:15], v[52:53], v[14:15]
	v_pk_fma_f32 v[116:117], v[36:37], v[14:15], v[116:117]
	v_pk_mul_f32 v[12:13], v[102:103], v[102:103]
	v_pk_fma_f32 v[12:13], v[104:105], v[104:105], v[12:13]
	v_pk_fma_f32 v[12:13], v[106:107], v[106:107], v[12:13]
	v_pk_fma_f32 v[12:13], v[108:109], v[108:109], v[12:13]
	v_pk_fma_f32 v[12:13], v[110:111], v[110:111], v[12:13]
	v_pk_fma_f32 v[12:13], v[112:113], v[112:113], v[12:13]
	v_pk_fma_f32 v[12:13], v[114:115], v[114:115], v[12:13]
	v_pk_fma_f32 v[12:13], v[116:117], v[116:117], v[12:13]
	v_add_f32_e32 v5, v12, v13
	s_nop 1
	v_add_f32_dpp v5, v5, v5 quad_perm:[1,0,3,2] row_mask:0xf bank_mask:0xf
	s_nop 1
	v_add_f32_dpp v5, v5, v5 quad_perm:[2,3,0,1] row_mask:0xf bank_mask:0xf
	s_nop 1
	v_add_f32_dpp v5, v5, v5 row_half_mirror row_mask:0xf bank_mask:0xf
	s_nop 1
	v_add_f32_dpp v5, v5, v5 row_mirror row_mask:0xf bank_mask:0xf
	s_nop 1
	v_add_f32_dpp v5, v5, v5 row_bcast:15 row_mask:0xa bank_mask:0xf
	s_nop 1
	v_add_f32_dpp v5, v5, v5 row_bcast:31 row_mask:0xc bank_mask:0xf
	s_nop 1
	v_readlane_b32 s32, v5, 63
	s_nop 1
	v_mov_b32_e32 v6, s32
	v_fmamk_f32 v6, v6, 0x3a800000, v146
	v_rsq_f32_e32 v6, v6
	s_nop 0
	v_mov_b32_e32 v10, v6
	v_pk_mul_f32 v[14:15], v[102:103], v[10:11] op_sel_hi:[1,0]
	v_pk_mul_f32 v[14:15], v[86:87], v[14:15]
	v_pk_fma_f32 v[16:17], v[70:71], v[14:15], v[54:55]
	v_pk_mul_f32 v[14:15], v[104:105], v[10:11] op_sel_hi:[1,0]
	v_pk_mul_f32 v[14:15], v[88:89], v[14:15]
	v_pk_fma_f32 v[18:19], v[72:73], v[14:15], v[56:57]
	v_cvt_pk_bf16_f32 v118, v16, v17
	v_cvt_pk_bf16_f32 v119, v18, v19
	v_pk_mul_f32 v[14:15], v[106:107], v[10:11] op_sel_hi:[1,0]
	v_pk_mul_f32 v[14:15], v[90:91], v[14:15]
	v_pk_fma_f32 v[16:17], v[74:75], v[14:15], v[58:59]
	v_pk_mul_f32 v[14:15], v[108:109], v[10:11] op_sel_hi:[1,0]
	v_pk_mul_f32 v[14:15], v[92:93], v[14:15]
	v_pk_fma_f32 v[18:19], v[76:77], v[14:15], v[60:61]
	v_cvt_pk_bf16_f32 v122, v16, v17
	v_cvt_pk_bf16_f32 v123, v18, v19
	v_pk_mul_f32 v[14:15], v[110:111], v[10:11] op_sel_hi:[1,0]
	v_pk_mul_f32 v[14:15], v[94:95], v[14:15]
	v_pk_fma_f32 v[16:17], v[78:79], v[14:15], v[62:63]
	v_pk_mul_f32 v[14:15], v[112:113], v[10:11] op_sel_hi:[1,0]
	v_pk_mul_f32 v[14:15], v[96:97], v[14:15]
	v_pk_fma_f32 v[18:19], v[80:81], v[14:15], v[64:65]
	v_cvt_pk_bf16_f32 v134, v16, v17
	v_cvt_pk_bf16_f32 v135, v18, v19
	v_pk_mul_f32 v[14:15], v[114:115], v[10:11] op_sel_hi:[1,0]
	v_pk_mul_f32 v[14:15], v[98:99], v[14:15]
	v_pk_fma_f32 v[16:17], v[82:83], v[14:15], v[66:67]
	v_pk_mul_f32 v[14:15], v[116:117], v[10:11] op_sel_hi:[1,0]
	v_pk_mul_f32 v[14:15], v[100:101], v[14:15]
	v_pk_fma_f32 v[18:19], v[84:85], v[14:15], v[68:69]
	v_cvt_pk_bf16_f32 v138, v16, v17
	v_cvt_pk_bf16_f32 v139, v18, v19
	global_store_dwordx4 v0, v[102:105], s[46:47] offset:0 sc1
	global_store_dwordx4 v0, v[106:109], s[46:47] offset:1024 sc1
	global_store_dwordx4 v0, v[110:113], s[46:47] offset:2048 sc1
	global_store_dwordx4 v0, v[114:117], s[46:47] offset:3072 sc1
	global_store_dwordx2 v1, v[118:119], s[62:63] offset:0 sc1
	global_store_dwordx2 v1, v[122:123], s[62:63] offset:512 sc1
	global_store_dwordx2 v1, v[134:135], s[62:63] offset:1024 sc1
	global_store_dwordx2 v1, v[138:139], s[62:63] offset:1536 sc1
	s_add_u32 s46, s46, 0x1000
	s_addc_u32 s47, s47, 0
	s_add_u32 s62, s62, 0x800
	s_addc_u32 s63, s63, 0
	s_nop 1
	global_load_dwordx4 v[102:105], v0, s[4:5] offset:0
	global_load_dwordx4 v[106:109], v0, s[4:5] offset:1024
	global_load_dwordx4 v[110:113], v0, s[4:5] offset:2048
	global_load_dwordx4 v[114:117], v0, s[4:5] offset:3072
	global_load_dwordx2 v[118:119], v1, s[58:59] offset:0
	global_load_dwordx2 v[122:123], v1, s[58:59] offset:512
	global_load_dwordx2 v[134:135], v1, s[58:59] offset:1024
	global_load_dwordx2 v[138:139], v1, s[58:59] offset:1536
	global_load_dwordx2 v[120:121], v1, s[60:61] offset:0
	global_load_dwordx2 v[124:125], v1, s[60:61] offset:512
	global_load_dwordx2 v[136:137], v1, s[60:61] offset:1024
	global_load_dwordx2 v[140:141], v1, s[60:61] offset:1536
	s_add_u32 s4, s4, 0x1000
	s_addc_u32 s5, s5, 0
	s_add_u32 s58, s58, 0x800
	s_addc_u32 s59, s59, 0
	s_add_u32 s60, s60, 0x800
	s_addc_u32 s61, s61, 0
	s_waitcnt vmcnt(32)
	v_lshlrev_b32_e32 v14, 16, v172
	v_and_b32_e32 v15, 0xffff0000, v172
	v_lshlrev_b32_e32 v16, 16, v174
	v_and_b32_e32 v17, 0xffff0000, v174
	v_lshlrev_b32_e32 v18, 16, v173
	v_and_b32_e32 v19, 0xffff0000, v173
	v_lshlrev_b32_e32 v20, 16, v175
	v_and_b32_e32 v21, 0xffff0000, v175
	v_pk_add_f32 v[172:173], v[14:15], v[16:17]
	v_pk_add_f32 v[174:175], v[18:19], v[20:21]
	v_lshlrev_b32_e32 v14, 16, v176
	v_and_b32_e32 v15, 0xffff0000, v176
	v_lshlrev_b32_e32 v16, 16, v178
	v_and_b32_e32 v17, 0xffff0000, v178
	v_lshlrev_b32_e32 v18, 16, v177
	v_and_b32_e32 v19, 0xffff0000, v177
	v_lshlrev_b32_e32 v20, 16, v179
	v_and_b32_e32 v21, 0xffff0000, v179
	v_pk_add_f32 v[176:177], v[14:15], v[16:17]
	v_pk_add_f32 v[178:179], v[18:19], v[20:21]
	v_lshlrev_b32_e32 v14, 16, v204
	v_and_b32_e32 v15, 0xffff0000, v204
	v_lshlrev_b32_e32 v16, 16, v206
	v_and_b32_e32 v17, 0xffff0000, v206
	v_lshlrev_b32_e32 v18, 16, v205
	v_and_b32_e32 v19, 0xffff0000, v205
	v_lshlrev_b32_e32 v20, 16, v207
	v_and_b32_e32 v21, 0xffff0000, v207
	v_pk_add_f32 v[204:205], v[14:15], v[16:17]
	v_pk_add_f32 v[206:207], v[18:19], v[20:21]
	v_lshlrev_b32_e32 v14, 16, v214
	v_and_b32_e32 v15, 0xffff0000, v214
	v_lshlrev_b32_e32 v16, 16, v216
	v_and_b32_e32 v17, 0xffff0000, v216
	v_lshlrev_b32_e32 v18, 16, v215
	v_and_b32_e32 v19, 0xffff0000, v215
	v_lshlrev_b32_e32 v20, 16, v217
	v_and_b32_e32 v21, 0xffff0000, v217
	v_pk_add_f32 v[214:215], v[14:15], v[16:17]
	v_pk_add_f32 v[216:217], v[18:19], v[20:21]
	v_pk_mul_f32 v[12:13], v[172:173], v[172:173]
	v_pk_fma_f32 v[12:13], v[174:175], v[174:175], v[12:13]
	v_pk_fma_f32 v[12:13], v[176:177], v[176:177], v[12:13]
	v_pk_fma_f32 v[12:13], v[178:179], v[178:179], v[12:13]
	v_pk_fma_f32 v[12:13], v[204:205], v[204:205], v[12:13]
	v_pk_fma_f32 v[12:13], v[206:207], v[206:207], v[12:13]
	v_pk_fma_f32 v[12:13], v[214:215], v[214:215], v[12:13]
	v_pk_fma_f32 v[12:13], v[216:217], v[216:217], v[12:13]
	v_add_f32_e32 v5, v12, v13
	s_nop 1
	v_add_f32_dpp v5, v5, v5 quad_perm:[1,0,3,2] row_mask:0xf bank_mask:0xf
	s_nop 1
	v_add_f32_dpp v5, v5, v5 quad_perm:[2,3,0,1] row_mask:0xf bank_mask:0xf
	s_nop 1
	v_add_f32_dpp v5, v5, v5 row_half_mirror row_mask:0xf bank_mask:0xf
	s_nop 1
	v_add_f32_dpp v5, v5, v5 row_mirror row_mask:0xf bank_mask:0xf
	s_nop 1
	v_add_f32_dpp v5, v5, v5 row_bcast:15 row_mask:0xa bank_mask:0xf
	s_nop 1
	v_add_f32_dpp v5, v5, v5 row_bcast:31 row_mask:0xc bank_mask:0xf
	s_nop 1
	v_readlane_b32 s32, v5, 63
	s_nop 1
	v_mov_b32_e32 v6, s32
	v_fmamk_f32 v6, v6, 0x3a800000, v146
	v_rsq_f32_e32 v6, v6
	s_nop 0
	v_mov_b32_e32 v8, v6
	v_pk_mul_f32 v[14:15], v[172:173], v[8:9] op_sel_hi:[1,0]
	v_pk_mul_f32 v[14:15], v[38:39], v[14:15]
	v_pk_fma_f32 v[154:155], v[22:23], v[14:15], v[154:155]
	v_pk_mul_f32 v[14:15], v[174:175], v[8:9] op_sel_hi:[1,0]
	v_pk_mul_f32 v[14:15], v[40:41], v[14:15]
	v_pk_fma_f32 v[156:157], v[24:25], v[14:15], v[156:157]
	v_pk_mul_f32 v[14:15], v[176:177], v[8:9] op_sel_hi:[1,0]
	v_pk_mul_f32 v[14:15], v[42:43], v[14:15]
	v_pk_fma_f32 v[158:159], v[26:27], v[14:15], v[158:159]
	v_pk_mul_f32 v[14:15], v[178:179], v[8:9] op_sel_hi:[1,0]
	v_pk_mul_f32 v[14:15], v[44:45], v[14:15]
	v_pk_fma_f32 v[160:161], v[28:29], v[14:15], v[160:161]
	v_pk_mul_f32 v[14:15], v[204:205], v[8:9] op_sel_hi:[1,0]
	v_pk_mul_f32 v[14:15], v[46:47], v[14:15]
	v_pk_fma_f32 v[162:163], v[30:31], v[14:15], v[162:163]
	v_pk_mul_f32 v[14:15], v[206:207], v[8:9] op_sel_hi:[1,0]
	v_pk_mul_f32 v[14:15], v[48:49], v[14:15]
	v_pk_fma_f32 v[164:165], v[32:33], v[14:15], v[164:165]
	v_pk_mul_f32 v[14:15], v[214:215], v[8:9] op_sel_hi:[1,0]
	v_pk_mul_f32 v[14:15], v[50:51], v[14:15]
	v_pk_fma_f32 v[168:169], v[34:35], v[14:15], v[168:169]
	v_pk_mul_f32 v[14:15], v[216:217], v[8:9] op_sel_hi:[1,0]
	v_pk_mul_f32 v[14:15], v[52:53], v[14:15]
	v_pk_fma_f32 v[170:171], v[36:37], v[14:15], v[170:171]
	v_pk_mul_f32 v[12:13], v[154:155], v[154:155]
	v_pk_fma_f32 v[12:13], v[156:157], v[156:157], v[12:13]
	v_pk_fma_f32 v[12:13], v[158:159], v[158:159], v[12:13]
	v_pk_fma_f32 v[12:13], v[160:161], v[160:161], v[12:13]
	v_pk_fma_f32 v[12:13], v[162:163], v[162:163], v[12:13]
	v_pk_fma_f32 v[12:13], v[164:165], v[164:165], v[12:13]
	v_pk_fma_f32 v[12:13], v[168:169], v[168:169], v[12:13]
	v_pk_fma_f32 v[12:13], v[170:171], v[170:171], v[12:13]
	v_add_f32_e32 v5, v12, v13
	s_nop 1
	v_add_f32_dpp v5, v5, v5 quad_perm:[1,0,3,2] row_mask:0xf bank_mask:0xf
	s_nop 1
	v_add_f32_dpp v5, v5, v5 quad_perm:[2,3,0,1] row_mask:0xf bank_mask:0xf
	s_nop 1
	v_add_f32_dpp v5, v5, v5 row_half_mirror row_mask:0xf bank_mask:0xf
	s_nop 1
	v_add_f32_dpp v5, v5, v5 row_mirror row_mask:0xf bank_mask:0xf
	s_nop 1
	v_add_f32_dpp v5, v5, v5 row_bcast:15 row_mask:0xa bank_mask:0xf
	s_nop 1
	v_add_f32_dpp v5, v5, v5 row_bcast:31 row_mask:0xc bank_mask:0xf
	s_nop 1
	v_readlane_b32 s32, v5, 63
	s_nop 1
	v_mov_b32_e32 v6, s32
	v_fmamk_f32 v6, v6, 0x3a800000, v146
	v_rsq_f32_e32 v6, v6
	s_nop 0
	v_mov_b32_e32 v10, v6
	v_pk_mul_f32 v[14:15], v[154:155], v[10:11] op_sel_hi:[1,0]
	v_pk_mul_f32 v[14:15], v[86:87], v[14:15]
	v_pk_fma_f32 v[16:17], v[70:71], v[14:15], v[54:55]
	v_pk_mul_f32 v[14:15], v[156:157], v[10:11] op_sel_hi:[1,0]
	v_pk_mul_f32 v[14:15], v[88:89], v[14:15]
	v_pk_fma_f32 v[18:19], v[72:73], v[14:15], v[56:57]
	v_cvt_pk_bf16_f32 v172, v16, v17
	v_cvt_pk_bf16_f32 v173, v18, v19
	v_pk_mul_f32 v[14:15], v[158:159], v[10:11] op_sel_hi:[1,0]
	v_pk_mul_f32 v[14:15], v[90:91], v[14:15]
	v_pk_fma_f32 v[16:17], v[74:75], v[14:15], v[58:59]
	v_pk_mul_f32 v[14:15], v[160:161], v[10:11] op_sel_hi:[1,0]
	v_pk_mul_f32 v[14:15], v[92:93], v[14:15]
	v_pk_fma_f32 v[18:19], v[76:77], v[14:15], v[60:61]
	v_cvt_pk_bf16_f32 v176, v16, v17
	v_cvt_pk_bf16_f32 v177, v18, v19
	v_pk_mul_f32 v[14:15], v[162:163], v[10:11] op_sel_hi:[1,0]
	v_pk_mul_f32 v[14:15], v[94:95], v[14:15]
	v_pk_fma_f32 v[16:17], v[78:79], v[14:15], v[62:63]
	v_pk_mul_f32 v[14:15], v[164:165], v[10:11] op_sel_hi:[1,0]
	v_pk_mul_f32 v[14:15], v[96:97], v[14:15]
	v_pk_fma_f32 v[18:19], v[80:81], v[14:15], v[64:65]
	v_cvt_pk_bf16_f32 v204, v16, v17
	v_cvt_pk_bf16_f32 v205, v18, v19
	v_pk_mul_f32 v[14:15], v[168:169], v[10:11] op_sel_hi:[1,0]
	v_pk_mul_f32 v[14:15], v[98:99], v[14:15]
	v_pk_fma_f32 v[16:17], v[82:83], v[14:15], v[66:67]
	v_pk_mul_f32 v[14:15], v[170:171], v[10:11] op_sel_hi:[1,0]
	v_pk_mul_f32 v[14:15], v[100:101], v[14:15]
	v_pk_fma_f32 v[18:19], v[84:85], v[14:15], v[68:69]
	v_cvt_pk_bf16_f32 v214, v16, v17
	v_cvt_pk_bf16_f32 v215, v18, v19
	global_store_dwordx4 v0, v[154:157], s[46:47] offset:0 sc1
	global_store_dwordx4 v0, v[158:161], s[46:47] offset:1024 sc1
	global_store_dwordx4 v0, v[162:165], s[46:47] offset:2048 sc1
	global_store_dwordx4 v0, v[168:171], s[46:47] offset:3072 sc1
	global_store_dwordx2 v1, v[172:173], s[62:63] offset:0 sc1
	global_store_dwordx2 v1, v[176:177], s[62:63] offset:512 sc1
	global_store_dwordx2 v1, v[204:205], s[62:63] offset:1024 sc1
	global_store_dwordx2 v1, v[214:215], s[62:63] offset:1536 sc1
	s_add_u32 s46, s46, 0x1000
	s_addc_u32 s47, s47, 0
	s_add_u32 s62, s62, 0x800
	s_addc_u32 s63, s63, 0
	s_waitcnt vmcnt(28)
	v_lshlrev_b32_e32 v14, 16, v234
	v_and_b32_e32 v15, 0xffff0000, v234
	v_lshlrev_b32_e32 v16, 16, v236
	v_and_b32_e32 v17, 0xffff0000, v236
	v_lshlrev_b32_e32 v18, 16, v235
	v_and_b32_e32 v19, 0xffff0000, v235
	v_lshlrev_b32_e32 v20, 16, v237
	v_and_b32_e32 v21, 0xffff0000, v237
	v_pk_add_f32 v[234:235], v[14:15], v[16:17]
	v_pk_add_f32 v[236:237], v[18:19], v[20:21]
	v_lshlrev_b32_e32 v14, 16, v238
	v_and_b32_e32 v15, 0xffff0000, v238
	v_lshlrev_b32_e32 v16, 16, v240
	v_and_b32_e32 v17, 0xffff0000, v240
	v_lshlrev_b32_e32 v18, 16, v239
	v_and_b32_e32 v19, 0xffff0000, v239
	v_lshlrev_b32_e32 v20, 16, v241
	v_and_b32_e32 v21, 0xffff0000, v241
	v_pk_add_f32 v[238:239], v[14:15], v[16:17]
	v_pk_add_f32 v[240:241], v[18:19], v[20:21]
	v_lshlrev_b32_e32 v14, 16, v242
	v_and_b32_e32 v15, 0xffff0000, v242
	v_lshlrev_b32_e32 v16, 16, v244
	v_and_b32_e32 v17, 0xffff0000, v244
	v_lshlrev_b32_e32 v18, 16, v243
	v_and_b32_e32 v19, 0xffff0000, v243
	v_lshlrev_b32_e32 v20, 16, v245
	v_and_b32_e32 v21, 0xffff0000, v245
	v_pk_add_f32 v[242:243], v[14:15], v[16:17]
	v_pk_add_f32 v[244:245], v[18:19], v[20:21]
	v_lshlrev_b32_e32 v14, 16, v246
	v_and_b32_e32 v15, 0xffff0000, v246
	v_lshlrev_b32_e32 v16, 16, v248
	v_and_b32_e32 v17, 0xffff0000, v248
	v_lshlrev_b32_e32 v18, 16, v247
	v_and_b32_e32 v19, 0xffff0000, v247
	v_lshlrev_b32_e32 v20, 16, v249
	v_and_b32_e32 v21, 0xffff0000, v249
	v_pk_add_f32 v[246:247], v[14:15], v[16:17]
	v_pk_add_f32 v[248:249], v[18:19], v[20:21]
	v_pk_mul_f32 v[12:13], v[234:235], v[234:235]
	v_pk_fma_f32 v[12:13], v[236:237], v[236:237], v[12:13]
	v_pk_fma_f32 v[12:13], v[238:239], v[238:239], v[12:13]
	v_pk_fma_f32 v[12:13], v[240:241], v[240:241], v[12:13]
	v_pk_fma_f32 v[12:13], v[242:243], v[242:243], v[12:13]
	v_pk_fma_f32 v[12:13], v[244:245], v[244:245], v[12:13]
	v_pk_fma_f32 v[12:13], v[246:247], v[246:247], v[12:13]
	v_pk_fma_f32 v[12:13], v[248:249], v[248:249], v[12:13]
	v_add_f32_e32 v5, v12, v13
	s_nop 1
	v_add_f32_dpp v5, v5, v5 quad_perm:[1,0,3,2] row_mask:0xf bank_mask:0xf
	s_nop 1
	v_add_f32_dpp v5, v5, v5 quad_perm:[2,3,0,1] row_mask:0xf bank_mask:0xf
	s_nop 1
	v_add_f32_dpp v5, v5, v5 row_half_mirror row_mask:0xf bank_mask:0xf
	s_nop 1
	v_add_f32_dpp v5, v5, v5 row_mirror row_mask:0xf bank_mask:0xf
	s_nop 1
	v_add_f32_dpp v5, v5, v5 row_bcast:15 row_mask:0xa bank_mask:0xf
	s_nop 1
	v_add_f32_dpp v5, v5, v5 row_bcast:31 row_mask:0xc bank_mask:0xf
	s_nop 1
	v_readlane_b32 s32, v5, 63
	s_nop 1
	v_mov_b32_e32 v6, s32
	v_fmamk_f32 v6, v6, 0x3a800000, v146
	v_rsq_f32_e32 v6, v6
	s_nop 0
	v_mov_b32_e32 v8, v6
	v_pk_mul_f32 v[14:15], v[234:235], v[8:9] op_sel_hi:[1,0]
	v_pk_mul_f32 v[14:15], v[38:39], v[14:15]
	v_pk_fma_f32 v[218:219], v[22:23], v[14:15], v[218:219]
	v_pk_mul_f32 v[14:15], v[236:237], v[8:9] op_sel_hi:[1,0]
	v_pk_mul_f32 v[14:15], v[40:41], v[14:15]
	v_pk_fma_f32 v[220:221], v[24:25], v[14:15], v[220:221]
	v_pk_mul_f32 v[14:15], v[238:239], v[8:9] op_sel_hi:[1,0]
	v_pk_mul_f32 v[14:15], v[42:43], v[14:15]
	v_pk_fma_f32 v[222:223], v[26:27], v[14:15], v[222:223]
	v_pk_mul_f32 v[14:15], v[240:241], v[8:9] op_sel_hi:[1,0]
	v_pk_mul_f32 v[14:15], v[44:45], v[14:15]
	v_pk_fma_f32 v[224:225], v[28:29], v[14:15], v[224:225]
	v_pk_mul_f32 v[14:15], v[242:243], v[8:9] op_sel_hi:[1,0]
	v_pk_mul_f32 v[14:15], v[46:47], v[14:15]
	v_pk_fma_f32 v[226:227], v[30:31], v[14:15], v[226:227]
	v_pk_mul_f32 v[14:15], v[244:245], v[8:9] op_sel_hi:[1,0]
	v_pk_mul_f32 v[14:15], v[48:49], v[14:15]
	v_pk_fma_f32 v[228:229], v[32:33], v[14:15], v[228:229]
	v_pk_mul_f32 v[14:15], v[246:247], v[8:9] op_sel_hi:[1,0]
	v_pk_mul_f32 v[14:15], v[50:51], v[14:15]
	v_pk_fma_f32 v[230:231], v[34:35], v[14:15], v[230:231]
	v_pk_mul_f32 v[14:15], v[248:249], v[8:9] op_sel_hi:[1,0]
	v_pk_mul_f32 v[14:15], v[52:53], v[14:15]
	v_pk_fma_f32 v[232:233], v[36:37], v[14:15], v[232:233]
	v_pk_mul_f32 v[12:13], v[218:219], v[218:219]
	v_pk_fma_f32 v[12:13], v[220:221], v[220:221], v[12:13]
	v_pk_fma_f32 v[12:13], v[222:223], v[222:223], v[12:13]
	v_pk_fma_f32 v[12:13], v[224:225], v[224:225], v[12:13]
	v_pk_fma_f32 v[12:13], v[226:227], v[226:227], v[12:13]
	v_pk_fma_f32 v[12:13], v[228:229], v[228:229], v[12:13]
	v_pk_fma_f32 v[12:13], v[230:231], v[230:231], v[12:13]
	v_pk_fma_f32 v[12:13], v[232:233], v[232:233], v[12:13]
	v_add_f32_e32 v5, v12, v13
	s_nop 1
	v_add_f32_dpp v5, v5, v5 quad_perm:[1,0,3,2] row_mask:0xf bank_mask:0xf
	s_nop 1
	v_add_f32_dpp v5, v5, v5 quad_perm:[2,3,0,1] row_mask:0xf bank_mask:0xf
	s_nop 1
	v_add_f32_dpp v5, v5, v5 row_half_mirror row_mask:0xf bank_mask:0xf
	s_nop 1
	v_add_f32_dpp v5, v5, v5 row_mirror row_mask:0xf bank_mask:0xf
	s_nop 1
	v_add_f32_dpp v5, v5, v5 row_bcast:15 row_mask:0xa bank_mask:0xf
	s_nop 1
	v_add_f32_dpp v5, v5, v5 row_bcast:31 row_mask:0xc bank_mask:0xf
	s_nop 1
	v_readlane_b32 s32, v5, 63
	s_nop 1
	v_mov_b32_e32 v6, s32
	v_fmamk_f32 v6, v6, 0x3a800000, v146
	v_rsq_f32_e32 v6, v6
	s_nop 0
	v_mov_b32_e32 v10, v6
	v_pk_mul_f32 v[14:15], v[218:219], v[10:11] op_sel_hi:[1,0]
	v_pk_mul_f32 v[14:15], v[86:87], v[14:15]
	v_pk_fma_f32 v[16:17], v[70:71], v[14:15], v[54:55]
	v_pk_mul_f32 v[14:15], v[220:221], v[10:11] op_sel_hi:[1,0]
	v_pk_mul_f32 v[14:15], v[88:89], v[14:15]
	v_pk_fma_f32 v[18:19], v[72:73], v[14:15], v[56:57]
	v_cvt_pk_bf16_f32 v234, v16, v17
	v_cvt_pk_bf16_f32 v235, v18, v19
	v_pk_mul_f32 v[14:15], v[222:223], v[10:11] op_sel_hi:[1,0]
	v_pk_mul_f32 v[14:15], v[90:91], v[14:15]
	v_pk_fma_f32 v[16:17], v[74:75], v[14:15], v[58:59]
	v_pk_mul_f32 v[14:15], v[224:225], v[10:11] op_sel_hi:[1,0]
	v_pk_mul_f32 v[14:15], v[92:93], v[14:15]
	v_pk_fma_f32 v[18:19], v[76:77], v[14:15], v[60:61]
	v_cvt_pk_bf16_f32 v238, v16, v17
	v_cvt_pk_bf16_f32 v239, v18, v19
	v_pk_mul_f32 v[14:15], v[226:227], v[10:11] op_sel_hi:[1,0]
	v_pk_mul_f32 v[14:15], v[94:95], v[14:15]
	v_pk_fma_f32 v[16:17], v[78:79], v[14:15], v[62:63]
	v_pk_mul_f32 v[14:15], v[228:229], v[10:11] op_sel_hi:[1,0]
	v_pk_mul_f32 v[14:15], v[96:97], v[14:15]
	v_pk_fma_f32 v[18:19], v[80:81], v[14:15], v[64:65]
	v_cvt_pk_bf16_f32 v242, v16, v17
	v_cvt_pk_bf16_f32 v243, v18, v19
	v_pk_mul_f32 v[14:15], v[230:231], v[10:11] op_sel_hi:[1,0]
	v_pk_mul_f32 v[14:15], v[98:99], v[14:15]
	v_pk_fma_f32 v[16:17], v[82:83], v[14:15], v[66:67]
	v_pk_mul_f32 v[14:15], v[232:233], v[10:11] op_sel_hi:[1,0]
	v_pk_mul_f32 v[14:15], v[100:101], v[14:15]
	v_pk_fma_f32 v[18:19], v[84:85], v[14:15], v[68:69]
	v_cvt_pk_bf16_f32 v246, v16, v17
	v_cvt_pk_bf16_f32 v247, v18, v19
	global_store_dwordx4 v0, v[218:221], s[46:47] offset:0 sc1
	global_store_dwordx4 v0, v[222:225], s[46:47] offset:1024 sc1
	global_store_dwordx4 v0, v[226:229], s[46:47] offset:2048 sc1
	global_store_dwordx4 v0, v[230:233], s[46:47] offset:3072 sc1
	global_store_dwordx2 v1, v[234:235], s[62:63] offset:0 sc1
	global_store_dwordx2 v1, v[238:239], s[62:63] offset:512 sc1
	global_store_dwordx2 v1, v[242:243], s[62:63] offset:1024 sc1
	global_store_dwordx2 v1, v[246:247], s[62:63] offset:1536 sc1
	s_add_u32 s46, s46, 0x1000
	s_addc_u32 s47, s47, 0
	s_add_u32 s62, s62, 0x800
	s_addc_u32 s63, s63, 0
	s_waitcnt vmcnt(16)
	v_lshlrev_b32_e32 v14, 16, v118
	v_and_b32_e32 v15, 0xffff0000, v118
	v_lshlrev_b32_e32 v16, 16, v120
	v_and_b32_e32 v17, 0xffff0000, v120
	v_lshlrev_b32_e32 v18, 16, v119
	v_and_b32_e32 v19, 0xffff0000, v119
	v_lshlrev_b32_e32 v20, 16, v121
	v_and_b32_e32 v21, 0xffff0000, v121
	v_pk_add_f32 v[118:119], v[14:15], v[16:17]
	v_pk_add_f32 v[120:121], v[18:19], v[20:21]
	v_lshlrev_b32_e32 v14, 16, v122
	v_and_b32_e32 v15, 0xffff0000, v122
	v_lshlrev_b32_e32 v16, 16, v124
	v_and_b32_e32 v17, 0xffff0000, v124
	v_lshlrev_b32_e32 v18, 16, v123
	v_and_b32_e32 v19, 0xffff0000, v123
	v_lshlrev_b32_e32 v20, 16, v125
	v_and_b32_e32 v21, 0xffff0000, v125
	v_pk_add_f32 v[122:123], v[14:15], v[16:17]
	v_pk_add_f32 v[124:125], v[18:19], v[20:21]
	v_lshlrev_b32_e32 v14, 16, v134
	v_and_b32_e32 v15, 0xffff0000, v134
	v_lshlrev_b32_e32 v16, 16, v136
	v_and_b32_e32 v17, 0xffff0000, v136
	v_lshlrev_b32_e32 v18, 16, v135
	v_and_b32_e32 v19, 0xffff0000, v135
	v_lshlrev_b32_e32 v20, 16, v137
	v_and_b32_e32 v21, 0xffff0000, v137
	v_pk_add_f32 v[134:135], v[14:15], v[16:17]
	v_pk_add_f32 v[136:137], v[18:19], v[20:21]
	v_lshlrev_b32_e32 v14, 16, v138
	v_and_b32_e32 v15, 0xffff0000, v138
	v_lshlrev_b32_e32 v16, 16, v140
	v_and_b32_e32 v17, 0xffff0000, v140
	v_lshlrev_b32_e32 v18, 16, v139
	v_and_b32_e32 v19, 0xffff0000, v139
	v_lshlrev_b32_e32 v20, 16, v141
	v_and_b32_e32 v21, 0xffff0000, v141
	v_pk_add_f32 v[138:139], v[14:15], v[16:17]
	v_pk_add_f32 v[140:141], v[18:19], v[20:21]
	v_pk_mul_f32 v[12:13], v[118:119], v[118:119]
	v_pk_fma_f32 v[12:13], v[120:121], v[120:121], v[12:13]
	v_pk_fma_f32 v[12:13], v[122:123], v[122:123], v[12:13]
	v_pk_fma_f32 v[12:13], v[124:125], v[124:125], v[12:13]
	v_pk_fma_f32 v[12:13], v[134:135], v[134:135], v[12:13]
	v_pk_fma_f32 v[12:13], v[136:137], v[136:137], v[12:13]
	v_pk_fma_f32 v[12:13], v[138:139], v[138:139], v[12:13]
	v_pk_fma_f32 v[12:13], v[140:141], v[140:141], v[12:13]
	v_add_f32_e32 v5, v12, v13
	s_nop 1
	v_add_f32_dpp v5, v5, v5 quad_perm:[1,0,3,2] row_mask:0xf bank_mask:0xf
	s_nop 1
	v_add_f32_dpp v5, v5, v5 quad_perm:[2,3,0,1] row_mask:0xf bank_mask:0xf
	s_nop 1
	v_add_f32_dpp v5, v5, v5 row_half_mirror row_mask:0xf bank_mask:0xf
	s_nop 1
	v_add_f32_dpp v5, v5, v5 row_mirror row_mask:0xf bank_mask:0xf
	s_nop 1
	v_add_f32_dpp v5, v5, v5 row_bcast:15 row_mask:0xa bank_mask:0xf
	s_nop 1
	v_add_f32_dpp v5, v5, v5 row_bcast:31 row_mask:0xc bank_mask:0xf
	s_nop 1
	v_readlane_b32 s32, v5, 63
	s_nop 1
	v_mov_b32_e32 v6, s32
	v_fmamk_f32 v6, v6, 0x3a800000, v146
	v_rsq_f32_e32 v6, v6
	s_nop 0
	v_mov_b32_e32 v8, v6
	v_pk_mul_f32 v[14:15], v[118:119], v[8:9] op_sel_hi:[1,0]
	v_pk_mul_f32 v[14:15], v[38:39], v[14:15]
	v_pk_fma_f32 v[102:103], v[22:23], v[14:15], v[102:103]
	v_pk_mul_f32 v[14:15], v[120:121], v[8:9] op_sel_hi:[1,0]
	v_pk_mul_f32 v[14:15], v[40:41], v[14:15]
	v_pk_fma_f32 v[104:105], v[24:25], v[14:15], v[104:105]
	v_pk_mul_f32 v[14:15], v[122:123], v[8:9] op_sel_hi:[1,0]
	v_pk_mul_f32 v[14:15], v[42:43], v[14:15]
	v_pk_fma_f32 v[106:107], v[26:27], v[14:15], v[106:107]
	v_pk_mul_f32 v[14:15], v[124:125], v[8:9] op_sel_hi:[1,0]
	v_pk_mul_f32 v[14:15], v[44:45], v[14:15]
	v_pk_fma_f32 v[108:109], v[28:29], v[14:15], v[108:109]
	v_pk_mul_f32 v[14:15], v[134:135], v[8:9] op_sel_hi:[1,0]
	v_pk_mul_f32 v[14:15], v[46:47], v[14:15]
	v_pk_fma_f32 v[110:111], v[30:31], v[14:15], v[110:111]
	v_pk_mul_f32 v[14:15], v[136:137], v[8:9] op_sel_hi:[1,0]
	v_pk_mul_f32 v[14:15], v[48:49], v[14:15]
	v_pk_fma_f32 v[112:113], v[32:33], v[14:15], v[112:113]
	v_pk_mul_f32 v[14:15], v[138:139], v[8:9] op_sel_hi:[1,0]
	v_pk_mul_f32 v[14:15], v[50:51], v[14:15]
	v_pk_fma_f32 v[114:115], v[34:35], v[14:15], v[114:115]
	v_pk_mul_f32 v[14:15], v[140:141], v[8:9] op_sel_hi:[1,0]
	v_pk_mul_f32 v[14:15], v[52:53], v[14:15]
	v_pk_fma_f32 v[116:117], v[36:37], v[14:15], v[116:117]
	v_pk_mul_f32 v[12:13], v[102:103], v[102:103]
	v_pk_fma_f32 v[12:13], v[104:105], v[104:105], v[12:13]
	v_pk_fma_f32 v[12:13], v[106:107], v[106:107], v[12:13]
	v_pk_fma_f32 v[12:13], v[108:109], v[108:109], v[12:13]
	v_pk_fma_f32 v[12:13], v[110:111], v[110:111], v[12:13]
	v_pk_fma_f32 v[12:13], v[112:113], v[112:113], v[12:13]
	v_pk_fma_f32 v[12:13], v[114:115], v[114:115], v[12:13]
	v_pk_fma_f32 v[12:13], v[116:117], v[116:117], v[12:13]
	v_add_f32_e32 v5, v12, v13
	s_nop 1
	v_add_f32_dpp v5, v5, v5 quad_perm:[1,0,3,2] row_mask:0xf bank_mask:0xf
	s_nop 1
	v_add_f32_dpp v5, v5, v5 quad_perm:[2,3,0,1] row_mask:0xf bank_mask:0xf
	s_nop 1
	v_add_f32_dpp v5, v5, v5 row_half_mirror row_mask:0xf bank_mask:0xf
	s_nop 1
	v_add_f32_dpp v5, v5, v5 row_mirror row_mask:0xf bank_mask:0xf
	s_nop 1
	v_add_f32_dpp v5, v5, v5 row_bcast:15 row_mask:0xa bank_mask:0xf
	s_nop 1
	v_add_f32_dpp v5, v5, v5 row_bcast:31 row_mask:0xc bank_mask:0xf
	s_nop 1
	v_readlane_b32 s32, v5, 63
	s_nop 1
	v_mov_b32_e32 v6, s32
	v_fmamk_f32 v6, v6, 0x3a800000, v146
	v_rsq_f32_e32 v6, v6
	s_nop 0
	v_mov_b32_e32 v10, v6
	v_pk_mul_f32 v[14:15], v[102:103], v[10:11] op_sel_hi:[1,0]
	v_pk_mul_f32 v[14:15], v[86:87], v[14:15]
	v_pk_fma_f32 v[16:17], v[70:71], v[14:15], v[54:55]
	v_pk_mul_f32 v[14:15], v[104:105], v[10:11] op_sel_hi:[1,0]
	v_pk_mul_f32 v[14:15], v[88:89], v[14:15]
	v_pk_fma_f32 v[18:19], v[72:73], v[14:15], v[56:57]
	v_cvt_pk_bf16_f32 v118, v16, v17
	v_cvt_pk_bf16_f32 v119, v18, v19
	v_pk_mul_f32 v[14:15], v[106:107], v[10:11] op_sel_hi:[1,0]
	v_pk_mul_f32 v[14:15], v[90:91], v[14:15]
	v_pk_fma_f32 v[16:17], v[74:75], v[14:15], v[58:59]
	v_pk_mul_f32 v[14:15], v[108:109], v[10:11] op_sel_hi:[1,0]
	v_pk_mul_f32 v[14:15], v[92:93], v[14:15]
	v_pk_fma_f32 v[18:19], v[76:77], v[14:15], v[60:61]
	v_cvt_pk_bf16_f32 v122, v16, v17
	v_cvt_pk_bf16_f32 v123, v18, v19
	v_pk_mul_f32 v[14:15], v[110:111], v[10:11] op_sel_hi:[1,0]
	v_pk_mul_f32 v[14:15], v[94:95], v[14:15]
	v_pk_fma_f32 v[16:17], v[78:79], v[14:15], v[62:63]
	v_pk_mul_f32 v[14:15], v[112:113], v[10:11] op_sel_hi:[1,0]
	v_pk_mul_f32 v[14:15], v[96:97], v[14:15]
	v_pk_fma_f32 v[18:19], v[80:81], v[14:15], v[64:65]
	v_cvt_pk_bf16_f32 v134, v16, v17
	v_cvt_pk_bf16_f32 v135, v18, v19
	v_pk_mul_f32 v[14:15], v[114:115], v[10:11] op_sel_hi:[1,0]
	v_pk_mul_f32 v[14:15], v[98:99], v[14:15]
	v_pk_fma_f32 v[16:17], v[82:83], v[14:15], v[66:67]
	v_pk_mul_f32 v[14:15], v[116:117], v[10:11] op_sel_hi:[1,0]
	v_pk_mul_f32 v[14:15], v[100:101], v[14:15]
	v_pk_fma_f32 v[18:19], v[84:85], v[14:15], v[68:69]
	v_cvt_pk_bf16_f32 v138, v16, v17
	v_cvt_pk_bf16_f32 v139, v18, v19
	global_store_dwordx4 v0, v[102:105], s[46:47] offset:0 sc1
	global_store_dwordx4 v0, v[106:109], s[46:47] offset:1024 sc1
	global_store_dwordx4 v0, v[110:113], s[46:47] offset:2048 sc1
	global_store_dwordx4 v0, v[114:117], s[46:47] offset:3072 sc1
	global_store_dwordx2 v1, v[118:119], s[62:63] offset:0 sc1
	global_store_dwordx2 v1, v[122:123], s[62:63] offset:512 sc1
	global_store_dwordx2 v1, v[134:135], s[62:63] offset:1024 sc1
	global_store_dwordx2 v1, v[138:139], s[62:63] offset:1536 sc1
	s_add_u32 s46, s46, 0x1000
	s_addc_u32 s47, s47, 0
	s_add_u32 s62, s62, 0x800
	s_addc_u32 s63, s63, 0
